# rowA phase rewritten like H1/rowB for G==256: parameter vectors staged in LDS by LDS-DMA (second latent cond replaces cond 0 after row 3 behind two workgroup barriers), six rows per wave unrolled, nex
# speedup vs baseline: 1.0148x; 1.0081x over previous
.LBB0_711:
	s_cmp_lt_i32 s72, 11
	s_cselect_b64 s[6:7], -1, 0
	s_and_b64 s[4:5], s[6:7], s[4:5]
	s_andn2_b64 vcc, exec, s[4:5]
	s_cbranch_vccnz .LBB0_715
	s_lshl_b32 s3, s2, 3
	s_add_i32 s6, s96, s3
	s_cmpk_gt_i32 s6, 0x2fff
	s_cbranch_scc1 .LBB0_715
	s_cmp_lg_u32 s33, 0x100
	s_cbranch_scc1 .LrA_old
	v_readlane_b32 s18, v255, 8
	v_readlane_b32 s19, v255, 9
	v_readlane_b32 s20, v255, 10
	v_readlane_b32 s21, v255, 11
	v_lshlrev_b32_e32 v238, 4, v174
	v_add_u32_e32 v239, 0x10000, v238
	s_lshl_b32 s7, s96, 11
	v_add_u32_e32 v240, s7, v238
	v_add_u32_e32 v241, 0x1000, v238
	v_add_u32_e32 v242, 0x2000, v238
	v_add_u32_e32 v243, 0x3000, v238
	v_lshlrev_b32_e32 v244, 3, v174
	v_add_u32_e32 v245, 0x1000, v244
	v_xor_b32_e32 v246, 1, v174
	v_lshlrev_b32_e32 v246, 2, v246
	v_xor_b32_e32 v247, 2, v174
	v_lshlrev_b32_e32 v247, 2, v247
	v_xor_b32_e32 v248, 4, v174
	v_lshlrev_b32_e32 v248, 2, v248
	v_xor_b32_e32 v249, 8, v174
	v_lshlrev_b32_e32 v249, 2, v249
	v_xor_b32_e32 v250, 16, v174
	v_lshlrev_b32_e32 v250, 2, v250
	v_xor_b32_e32 v251, 32, v174
	v_lshlrev_b32_e32 v251, 2, v251
	s_mov_b32 s32, 0x800000
	s_lshr_b32 s3, s2, 7
	s_nop 4
	s_add_u32 s8, s7, 0x0
	s_mov_b32 m0, s8
	s_nop 0
	global_load_lds_dwordx4 v240, s[18:19]
	global_load_lds_dwordx4 v240, s[18:19] offset:1024
	s_add_u32 s8, s7, 0x4000
	s_mov_b32 m0, s8
	s_nop 0
	global_load_lds_dwordx4 v240, s[20:21]
	global_load_lds_dwordx4 v240, s[20:21] offset:1024
	s_mov_b32 s10, s28
	s_mov_b32 s11, s29
	s_add_u32 s12, s10, 0x8000
	s_addc_u32 s13, s11, 0
	s_add_u32 s8, s7, 0x8000
	s_mov_b32 m0, s8
	s_nop 0
	global_load_lds_dwordx4 v240, s[12:13]
	global_load_lds_dwordx4 v240, s[12:13] offset:1024
	s_add_u32 s12, s10, 0xc000
	s_addc_u32 s13, s11, 0
	s_add_u32 s8, s7, 0xc000
	s_mov_b32 m0, s8
	s_nop 0
	global_load_lds_dwordx4 v240, s[12:13]
	global_load_lds_dwordx4 v240, s[12:13] offset:1024
	s_add_u32 s12, s10, 0x10000
	s_addc_u32 s13, s11, 0
	s_add_u32 s8, s7, 0x10000
	s_mov_b32 m0, s8
	s_nop 0
	global_load_lds_dwordx4 v240, s[12:13]
	global_load_lds_dwordx4 v240, s[12:13] offset:1024
	s_add_i32 s9, s3, 1
	s_mul_i32 s9, s9, 0x18000
	s_add_u32 s10, s28, s9
	s_addc_u32 s11, s29, 0
	s_add_u32 s12, s10, 0x8000
	s_addc_u32 s13, s11, 0
	s_add_u32 s8, s7, 0x14000
	s_mov_b32 m0, s8
	s_nop 0
	global_load_lds_dwordx4 v240, s[12:13]
	global_load_lds_dwordx4 v240, s[12:13] offset:1024
	s_add_u32 s12, s10, 0xc000
	s_addc_u32 s13, s11, 0
	s_add_u32 s8, s7, 0x18000
	s_mov_b32 m0, s8
	s_nop 0
	global_load_lds_dwordx4 v240, s[12:13]
	global_load_lds_dwordx4 v240, s[12:13] offset:1024
	s_add_u32 s12, s10, 0x10000
	s_addc_u32 s13, s11, 0
	s_add_u32 s8, s7, 0x1c000
	s_mov_b32 m0, s8
	s_nop 0
	global_load_lds_dwordx4 v240, s[12:13]
	global_load_lds_dwordx4 v240, s[12:13] offset:1024
	s_lshl_b32 s9, s6, 14
	s_add_u32 s14, s52, s9
	s_addc_u32 s15, s53, 0
	s_add_u32 s44, s54, s9
	s_addc_u32 s45, s55, 0
	s_lshl_b32 s9, s6, 13
	s_add_u32 s22, s70, s9
	s_addc_u32 s23, s71, 0
	s_add_u32 s16, s22, 0x1ec00000
	s_addc_u32 s17, s23, 0
	s_add_u32 s38, s22, 0x4b000000
	s_addc_u32 s39, s23, 0
	s_add_u32 s22, s22, 0x3f000000
	s_addc_u32 s23, s23, 0
	s_waitcnt vmcnt(0)
	s_barrier
	global_load_dwordx4 v[2:5], v238, s[14:15] offset:0
	global_load_dwordx4 v[6:9], v238, s[14:15] offset:1024
	global_load_dwordx4 v[10:13], v238, s[14:15] offset:2048
	global_load_dwordx4 v[14:17], v238, s[14:15] offset:3072
	global_load_dwordx4 v[18:21], v241, s[14:15] offset:0
	global_load_dwordx4 v[22:25], v241, s[14:15] offset:1024
	global_load_dwordx4 v[26:29], v241, s[14:15] offset:2048
	global_load_dwordx4 v[30:33], v241, s[14:15] offset:3072
	global_load_dwordx4 v[34:37], v242, s[14:15] offset:0
	global_load_dwordx4 v[38:41], v242, s[14:15] offset:1024
	global_load_dwordx4 v[42:45], v242, s[14:15] offset:2048
	global_load_dwordx4 v[46:49], v242, s[14:15] offset:3072
	global_load_dwordx4 v[50:53], v243, s[14:15] offset:0
	global_load_dwordx4 v[54:57], v243, s[14:15] offset:1024
	global_load_dwordx4 v[58:61], v243, s[14:15] offset:2048
	global_load_dwordx4 v[62:65], v243, s[14:15] offset:3072
	global_load_dwordx2 v[130:131], v244, s[16:17] offset:0
	global_load_dwordx2 v[132:133], v244, s[16:17] offset:512
	global_load_dwordx2 v[134:135], v244, s[16:17] offset:1024
	global_load_dwordx2 v[136:137], v244, s[16:17] offset:1536
	global_load_dwordx2 v[138:139], v244, s[16:17] offset:2048
	global_load_dwordx2 v[140:141], v244, s[16:17] offset:2560
	global_load_dwordx2 v[142:143], v244, s[16:17] offset:3072
	global_load_dwordx2 v[144:145], v244, s[16:17] offset:3584
	global_load_dwordx2 v[146:147], v245, s[16:17] offset:0
	global_load_dwordx2 v[148:149], v245, s[16:17] offset:512
	global_load_dwordx2 v[150:151], v245, s[16:17] offset:1024
	global_load_dwordx2 v[152:153], v245, s[16:17] offset:1536
	global_load_dwordx2 v[154:155], v245, s[16:17] offset:2048
	global_load_dwordx2 v[156:157], v245, s[16:17] offset:2560
	global_load_dwordx2 v[158:159], v245, s[16:17] offset:3072
	global_load_dwordx2 v[160:161], v245, s[16:17] offset:3584
	s_waitcnt vmcnt(0)
	s_add_u32 s14, s14, 0x2000000
	s_addc_u32 s15, s15, 0
	global_load_dwordx4 v[66:69], v238, s[14:15] offset:0
	global_load_dwordx4 v[70:73], v238, s[14:15] offset:1024
	global_load_dwordx4 v[74:77], v238, s[14:15] offset:2048
	global_load_dwordx4 v[78:81], v238, s[14:15] offset:3072
	global_load_dwordx4 v[82:85], v241, s[14:15] offset:0
	global_load_dwordx4 v[86:89], v241, s[14:15] offset:1024
	global_load_dwordx4 v[90:93], v241, s[14:15] offset:2048
	global_load_dwordx4 v[94:97], v241, s[14:15] offset:3072
	global_load_dwordx4 v[98:101], v242, s[14:15] offset:0
	global_load_dwordx4 v[102:105], v242, s[14:15] offset:1024
	global_load_dwordx4 v[106:109], v242, s[14:15] offset:2048
	global_load_dwordx4 v[110:113], v242, s[14:15] offset:3072
	global_load_dwordx4 v[114:117], v243, s[14:15] offset:0
	global_load_dwordx4 v[118:121], v243, s[14:15] offset:1024
	global_load_dwordx4 v[122:125], v243, s[14:15] offset:2048
	global_load_dwordx4 v[126:129], v243, s[14:15] offset:3072
	ds_read_b128 v[214:217], v238 offset:0
	ds_read_b128 v[218:221], v238 offset:32768
	v_lshlrev_b32_e32 v162, 16, v130
	v_and_b32_e32 v163, 0xffff0000, v130
	v_lshlrev_b32_e32 v164, 16, v131
	v_and_b32_e32 v165, 0xffff0000, v131
	v_pk_mul_f32 v[170:171], v[162:163], v[162:163]
	v_pk_mul_f32 v[172:173], v[164:165], v[164:165]
	v_lshlrev_b32_e32 v166, 16, v132
	v_and_b32_e32 v167, 0xffff0000, v132
	v_lshlrev_b32_e32 v168, 16, v133
	v_and_b32_e32 v169, 0xffff0000, v133
	v_pk_fma_f32 v[170:171], v[166:167], v[166:167], v[170:171]
	v_pk_fma_f32 v[172:173], v[168:169], v[168:169], v[172:173]
	v_lshlrev_b32_e32 v162, 16, v134
	v_and_b32_e32 v163, 0xffff0000, v134
	v_lshlrev_b32_e32 v164, 16, v135
	v_and_b32_e32 v165, 0xffff0000, v135
	v_pk_fma_f32 v[170:171], v[162:163], v[162:163], v[170:171]
	v_pk_fma_f32 v[172:173], v[164:165], v[164:165], v[172:173]
	v_lshlrev_b32_e32 v166, 16, v136
	v_and_b32_e32 v167, 0xffff0000, v136
	v_lshlrev_b32_e32 v168, 16, v137
	v_and_b32_e32 v169, 0xffff0000, v137
	v_pk_fma_f32 v[170:171], v[166:167], v[166:167], v[170:171]
	v_pk_fma_f32 v[172:173], v[168:169], v[168:169], v[172:173]
	v_lshlrev_b32_e32 v162, 16, v138
	v_and_b32_e32 v163, 0xffff0000, v138
	v_lshlrev_b32_e32 v164, 16, v139
	v_and_b32_e32 v165, 0xffff0000, v139
	v_pk_fma_f32 v[170:171], v[162:163], v[162:163], v[170:171]
	v_pk_fma_f32 v[172:173], v[164:165], v[164:165], v[172:173]
	v_lshlrev_b32_e32 v166, 16, v140
	v_and_b32_e32 v167, 0xffff0000, v140
	v_lshlrev_b32_e32 v168, 16, v141
	v_and_b32_e32 v169, 0xffff0000, v141
	v_pk_fma_f32 v[170:171], v[166:167], v[166:167], v[170:171]
	v_pk_fma_f32 v[172:173], v[168:169], v[168:169], v[172:173]
	v_lshlrev_b32_e32 v162, 16, v142
	v_and_b32_e32 v163, 0xffff0000, v142
	v_lshlrev_b32_e32 v164, 16, v143
	v_and_b32_e32 v165, 0xffff0000, v143
	v_pk_fma_f32 v[170:171], v[162:163], v[162:163], v[170:171]
	v_pk_fma_f32 v[172:173], v[164:165], v[164:165], v[172:173]
	v_lshlrev_b32_e32 v166, 16, v144
	v_and_b32_e32 v167, 0xffff0000, v144
	v_lshlrev_b32_e32 v168, 16, v145
	v_and_b32_e32 v169, 0xffff0000, v145
	v_pk_fma_f32 v[170:171], v[166:167], v[166:167], v[170:171]
	v_pk_fma_f32 v[172:173], v[168:169], v[168:169], v[172:173]
	v_lshlrev_b32_e32 v162, 16, v146
	v_and_b32_e32 v163, 0xffff0000, v146
	v_lshlrev_b32_e32 v164, 16, v147
	v_and_b32_e32 v165, 0xffff0000, v147
	v_pk_fma_f32 v[170:171], v[162:163], v[162:163], v[170:171]
	v_pk_fma_f32 v[172:173], v[164:165], v[164:165], v[172:173]
	v_lshlrev_b32_e32 v166, 16, v148
	v_and_b32_e32 v167, 0xffff0000, v148
	v_lshlrev_b32_e32 v168, 16, v149
	v_and_b32_e32 v169, 0xffff0000, v149
	v_pk_fma_f32 v[170:171], v[166:167], v[166:167], v[170:171]
	v_pk_fma_f32 v[172:173], v[168:169], v[168:169], v[172:173]
	v_lshlrev_b32_e32 v162, 16, v150
	v_and_b32_e32 v163, 0xffff0000, v150
	v_lshlrev_b32_e32 v164, 16, v151
	v_and_b32_e32 v165, 0xffff0000, v151
	v_pk_fma_f32 v[170:171], v[162:163], v[162:163], v[170:171]
	v_pk_fma_f32 v[172:173], v[164:165], v[164:165], v[172:173]
	v_lshlrev_b32_e32 v166, 16, v152
	v_and_b32_e32 v167, 0xffff0000, v152
	v_lshlrev_b32_e32 v168, 16, v153
	v_and_b32_e32 v169, 0xffff0000, v153
	v_pk_fma_f32 v[170:171], v[166:167], v[166:167], v[170:171]
	v_pk_fma_f32 v[172:173], v[168:169], v[168:169], v[172:173]
	v_lshlrev_b32_e32 v162, 16, v154
	v_and_b32_e32 v163, 0xffff0000, v154
	v_lshlrev_b32_e32 v164, 16, v155
	v_and_b32_e32 v165, 0xffff0000, v155
	v_pk_fma_f32 v[170:171], v[162:163], v[162:163], v[170:171]
	v_pk_fma_f32 v[172:173], v[164:165], v[164:165], v[172:173]
	v_lshlrev_b32_e32 v166, 16, v156
	v_and_b32_e32 v167, 0xffff0000, v156
	v_lshlrev_b32_e32 v168, 16, v157
	v_and_b32_e32 v169, 0xffff0000, v157
	v_pk_fma_f32 v[170:171], v[166:167], v[166:167], v[170:171]
	v_pk_fma_f32 v[172:173], v[168:169], v[168:169], v[172:173]
	v_lshlrev_b32_e32 v162, 16, v158
	v_and_b32_e32 v163, 0xffff0000, v158
	v_lshlrev_b32_e32 v164, 16, v159
	v_and_b32_e32 v165, 0xffff0000, v159
	v_pk_fma_f32 v[170:171], v[162:163], v[162:163], v[170:171]
	v_pk_fma_f32 v[172:173], v[164:165], v[164:165], v[172:173]
	v_lshlrev_b32_e32 v166, 16, v160
	v_and_b32_e32 v167, 0xffff0000, v160
	v_lshlrev_b32_e32 v168, 16, v161
	v_and_b32_e32 v169, 0xffff0000, v161
	v_pk_fma_f32 v[170:171], v[166:167], v[166:167], v[170:171]
	v_pk_fma_f32 v[172:173], v[168:169], v[168:169], v[172:173]
	v_pk_add_f32 v[170:171], v[170:171], v[172:173]
	s_nop 0
	v_add_f32_e32 v252, v170, v171
	s_waitcnt lgkmcnt(0)
	ds_bpermute_b32 v254, v246, v252
	s_waitcnt lgkmcnt(0)
	v_add_f32_e32 v252, v252, v254
	ds_bpermute_b32 v254, v247, v252
	s_waitcnt lgkmcnt(0)
	v_add_f32_e32 v252, v252, v254
	ds_bpermute_b32 v254, v248, v252
	s_waitcnt lgkmcnt(0)
	v_add_f32_e32 v252, v252, v254
	ds_bpermute_b32 v254, v249, v252
	s_waitcnt lgkmcnt(0)
	v_add_f32_e32 v252, v252, v254
	ds_bpermute_b32 v254, v250, v252
	s_waitcnt lgkmcnt(0)
	v_add_f32_e32 v252, v252, v254
	ds_bpermute_b32 v254, v251, v252
	s_waitcnt lgkmcnt(0)
	v_add_f32_e32 v252, v252, v254
	v_mov_b32_e32 v254, 0x358637bd
	v_fmac_f32_e32 v254, 0x39800000, v252
	v_mul_f32_e32 v252, 0x4b800000, v254
	v_cmp_gt_f32_e32 vcc, s32, v254
	s_nop 1
	v_cndmask_b32_e32 v254, v254, v252, vcc
	v_rsq_f32_e32 v254, v254
	s_nop 0
	v_mul_f32_e32 v252, 0x45800000, v254
	v_cndmask_b32_e32 v252, v254, v252, vcc
	ds_read_b128 v[226:229], v238 offset:1024
	ds_read_b128 v[230:233], v238 offset:33792
	s_waitcnt lgkmcnt(2)
	v_lshlrev_b32_e32 v162, 16, v130
	v_and_b32_e32 v163, 0xffff0000, v130
	v_lshlrev_b32_e32 v164, 16, v131
	v_and_b32_e32 v165, 0xffff0000, v131
	v_pk_mul_f32 v[162:163], v[162:163], v[252:253] op_sel_hi:[1,0]
	v_pk_mul_f32 v[164:165], v[164:165], v[252:253] op_sel_hi:[1,0]
	v_pk_mul_f32 v[162:163], v[162:163], v[214:215]
	v_pk_mul_f32 v[164:165], v[164:165], v[216:217]
	v_pk_fma_f32 v[2:3], v[218:219], v[162:163], v[2:3]
	v_pk_fma_f32 v[4:5], v[220:221], v[164:165], v[4:5]
	v_pk_mul_f32 v[170:171], v[2:3], v[2:3]
	v_pk_mul_f32 v[172:173], v[4:5], v[4:5]
	v_cvt_pk_bf16_f32 v166, v2, v3
	v_cvt_pk_bf16_f32 v167, v4, v5
	global_store_dwordx2 v244, v[166:167], s[22:23] offset:0
	ds_read_b128 v[214:217], v238 offset:2048
	ds_read_b128 v[218:221], v238 offset:34816
	s_waitcnt lgkmcnt(2)
	v_lshlrev_b32_e32 v162, 16, v132
	v_and_b32_e32 v163, 0xffff0000, v132
	v_lshlrev_b32_e32 v164, 16, v133
	v_and_b32_e32 v165, 0xffff0000, v133
	v_pk_mul_f32 v[162:163], v[162:163], v[252:253] op_sel_hi:[1,0]
	v_pk_mul_f32 v[164:165], v[164:165], v[252:253] op_sel_hi:[1,0]
	v_pk_mul_f32 v[162:163], v[162:163], v[226:227]
	v_pk_mul_f32 v[164:165], v[164:165], v[228:229]
	v_pk_fma_f32 v[6:7], v[230:231], v[162:163], v[6:7]
	v_pk_fma_f32 v[8:9], v[232:233], v[164:165], v[8:9]
	v_pk_fma_f32 v[170:171], v[6:7], v[6:7], v[170:171]
	v_pk_fma_f32 v[172:173], v[8:9], v[8:9], v[172:173]
	v_cvt_pk_bf16_f32 v168, v6, v7
	v_cvt_pk_bf16_f32 v169, v8, v9
	global_store_dwordx2 v244, v[168:169], s[22:23] offset:512
	ds_read_b128 v[226:229], v238 offset:3072
	ds_read_b128 v[230:233], v238 offset:35840
	s_waitcnt lgkmcnt(2)
	v_lshlrev_b32_e32 v162, 16, v134
	v_and_b32_e32 v163, 0xffff0000, v134
	v_lshlrev_b32_e32 v164, 16, v135
	v_and_b32_e32 v165, 0xffff0000, v135
	v_pk_mul_f32 v[162:163], v[162:163], v[252:253] op_sel_hi:[1,0]
	v_pk_mul_f32 v[164:165], v[164:165], v[252:253] op_sel_hi:[1,0]
	v_pk_mul_f32 v[162:163], v[162:163], v[214:215]
	v_pk_mul_f32 v[164:165], v[164:165], v[216:217]
	v_pk_fma_f32 v[10:11], v[218:219], v[162:163], v[10:11]
	v_pk_fma_f32 v[12:13], v[220:221], v[164:165], v[12:13]
	v_pk_fma_f32 v[170:171], v[10:11], v[10:11], v[170:171]
	v_pk_fma_f32 v[172:173], v[12:13], v[12:13], v[172:173]
	v_cvt_pk_bf16_f32 v166, v10, v11
	v_cvt_pk_bf16_f32 v167, v12, v13
	global_store_dwordx2 v244, v[166:167], s[22:23] offset:1024
	ds_read_b128 v[214:217], v238 offset:4096
	ds_read_b128 v[218:221], v238 offset:36864
	s_waitcnt lgkmcnt(2)
	v_lshlrev_b32_e32 v162, 16, v136
	v_and_b32_e32 v163, 0xffff0000, v136
	v_lshlrev_b32_e32 v164, 16, v137
	v_and_b32_e32 v165, 0xffff0000, v137
	v_pk_mul_f32 v[162:163], v[162:163], v[252:253] op_sel_hi:[1,0]
	v_pk_mul_f32 v[164:165], v[164:165], v[252:253] op_sel_hi:[1,0]
	v_pk_mul_f32 v[162:163], v[162:163], v[226:227]
	v_pk_mul_f32 v[164:165], v[164:165], v[228:229]
	v_pk_fma_f32 v[14:15], v[230:231], v[162:163], v[14:15]
	v_pk_fma_f32 v[16:17], v[232:233], v[164:165], v[16:17]
	v_pk_fma_f32 v[170:171], v[14:15], v[14:15], v[170:171]
	v_pk_fma_f32 v[172:173], v[16:17], v[16:17], v[172:173]
	v_cvt_pk_bf16_f32 v168, v14, v15
	v_cvt_pk_bf16_f32 v169, v16, v17
	global_store_dwordx2 v244, v[168:169], s[22:23] offset:1536
	ds_read_b128 v[226:229], v238 offset:5120
	ds_read_b128 v[230:233], v238 offset:37888
	s_waitcnt lgkmcnt(2)
	v_lshlrev_b32_e32 v162, 16, v138
	v_and_b32_e32 v163, 0xffff0000, v138
	v_lshlrev_b32_e32 v164, 16, v139
	v_and_b32_e32 v165, 0xffff0000, v139
	v_pk_mul_f32 v[162:163], v[162:163], v[252:253] op_sel_hi:[1,0]
	v_pk_mul_f32 v[164:165], v[164:165], v[252:253] op_sel_hi:[1,0]
	v_pk_mul_f32 v[162:163], v[162:163], v[214:215]
	v_pk_mul_f32 v[164:165], v[164:165], v[216:217]
	v_pk_fma_f32 v[18:19], v[218:219], v[162:163], v[18:19]
	v_pk_fma_f32 v[20:21], v[220:221], v[164:165], v[20:21]
	v_pk_fma_f32 v[170:171], v[18:19], v[18:19], v[170:171]
	v_pk_fma_f32 v[172:173], v[20:21], v[20:21], v[172:173]
	v_cvt_pk_bf16_f32 v166, v18, v19
	v_cvt_pk_bf16_f32 v167, v20, v21
	global_store_dwordx2 v244, v[166:167], s[22:23] offset:2048
	ds_read_b128 v[214:217], v238 offset:6144
	ds_read_b128 v[218:221], v238 offset:38912
	s_waitcnt lgkmcnt(2)
	v_lshlrev_b32_e32 v162, 16, v140
	v_and_b32_e32 v163, 0xffff0000, v140
	v_lshlrev_b32_e32 v164, 16, v141
	v_and_b32_e32 v165, 0xffff0000, v141
	v_pk_mul_f32 v[162:163], v[162:163], v[252:253] op_sel_hi:[1,0]
	v_pk_mul_f32 v[164:165], v[164:165], v[252:253] op_sel_hi:[1,0]
	v_pk_mul_f32 v[162:163], v[162:163], v[226:227]
	v_pk_mul_f32 v[164:165], v[164:165], v[228:229]
	v_pk_fma_f32 v[22:23], v[230:231], v[162:163], v[22:23]
	v_pk_fma_f32 v[24:25], v[232:233], v[164:165], v[24:25]
	v_pk_fma_f32 v[170:171], v[22:23], v[22:23], v[170:171]
	v_pk_fma_f32 v[172:173], v[24:25], v[24:25], v[172:173]
	v_cvt_pk_bf16_f32 v168, v22, v23
	v_cvt_pk_bf16_f32 v169, v24, v25
	global_store_dwordx2 v244, v[168:169], s[22:23] offset:2560
	ds_read_b128 v[226:229], v238 offset:7168
	ds_read_b128 v[230:233], v238 offset:39936
	s_waitcnt lgkmcnt(2)
	v_lshlrev_b32_e32 v162, 16, v142
	v_and_b32_e32 v163, 0xffff0000, v142
	v_lshlrev_b32_e32 v164, 16, v143
	v_and_b32_e32 v165, 0xffff0000, v143
	v_pk_mul_f32 v[162:163], v[162:163], v[252:253] op_sel_hi:[1,0]
	v_pk_mul_f32 v[164:165], v[164:165], v[252:253] op_sel_hi:[1,0]
	v_pk_mul_f32 v[162:163], v[162:163], v[214:215]
	v_pk_mul_f32 v[164:165], v[164:165], v[216:217]
	v_pk_fma_f32 v[26:27], v[218:219], v[162:163], v[26:27]
	v_pk_fma_f32 v[28:29], v[220:221], v[164:165], v[28:29]
	v_pk_fma_f32 v[170:171], v[26:27], v[26:27], v[170:171]
	v_pk_fma_f32 v[172:173], v[28:29], v[28:29], v[172:173]
	v_cvt_pk_bf16_f32 v166, v26, v27
	v_cvt_pk_bf16_f32 v167, v28, v29
	global_store_dwordx2 v244, v[166:167], s[22:23] offset:3072
	ds_read_b128 v[214:217], v238 offset:8192
	ds_read_b128 v[218:221], v238 offset:40960
	s_waitcnt lgkmcnt(2)
	v_lshlrev_b32_e32 v162, 16, v144
	v_and_b32_e32 v163, 0xffff0000, v144
	v_lshlrev_b32_e32 v164, 16, v145
	v_and_b32_e32 v165, 0xffff0000, v145
	v_pk_mul_f32 v[162:163], v[162:163], v[252:253] op_sel_hi:[1,0]
	v_pk_mul_f32 v[164:165], v[164:165], v[252:253] op_sel_hi:[1,0]
	v_pk_mul_f32 v[162:163], v[162:163], v[226:227]
	v_pk_mul_f32 v[164:165], v[164:165], v[228:229]
	v_pk_fma_f32 v[30:31], v[230:231], v[162:163], v[30:31]
	v_pk_fma_f32 v[32:33], v[232:233], v[164:165], v[32:33]
	v_pk_fma_f32 v[170:171], v[30:31], v[30:31], v[170:171]
	v_pk_fma_f32 v[172:173], v[32:33], v[32:33], v[172:173]
	v_cvt_pk_bf16_f32 v168, v30, v31
	v_cvt_pk_bf16_f32 v169, v32, v33
	global_store_dwordx2 v244, v[168:169], s[22:23] offset:3584
	ds_read_b128 v[226:229], v238 offset:9216
	ds_read_b128 v[230:233], v238 offset:41984
	s_waitcnt lgkmcnt(2)
	v_lshlrev_b32_e32 v162, 16, v146
	v_and_b32_e32 v163, 0xffff0000, v146
	v_lshlrev_b32_e32 v164, 16, v147
	v_and_b32_e32 v165, 0xffff0000, v147
	v_pk_mul_f32 v[162:163], v[162:163], v[252:253] op_sel_hi:[1,0]
	v_pk_mul_f32 v[164:165], v[164:165], v[252:253] op_sel_hi:[1,0]
	v_pk_mul_f32 v[162:163], v[162:163], v[214:215]
	v_pk_mul_f32 v[164:165], v[164:165], v[216:217]
	v_pk_fma_f32 v[34:35], v[218:219], v[162:163], v[34:35]
	v_pk_fma_f32 v[36:37], v[220:221], v[164:165], v[36:37]
	v_pk_fma_f32 v[170:171], v[34:35], v[34:35], v[170:171]
	v_pk_fma_f32 v[172:173], v[36:37], v[36:37], v[172:173]
	v_cvt_pk_bf16_f32 v166, v34, v35
	v_cvt_pk_bf16_f32 v167, v36, v37
	global_store_dwordx2 v245, v[166:167], s[22:23] offset:0
	ds_read_b128 v[214:217], v238 offset:10240
	ds_read_b128 v[218:221], v238 offset:43008
	s_waitcnt lgkmcnt(2)
	v_lshlrev_b32_e32 v162, 16, v148
	v_and_b32_e32 v163, 0xffff0000, v148
	v_lshlrev_b32_e32 v164, 16, v149
	v_and_b32_e32 v165, 0xffff0000, v149
	v_pk_mul_f32 v[162:163], v[162:163], v[252:253] op_sel_hi:[1,0]
	v_pk_mul_f32 v[164:165], v[164:165], v[252:253] op_sel_hi:[1,0]
	v_pk_mul_f32 v[162:163], v[162:163], v[226:227]
	v_pk_mul_f32 v[164:165], v[164:165], v[228:229]
	v_pk_fma_f32 v[38:39], v[230:231], v[162:163], v[38:39]
	v_pk_fma_f32 v[40:41], v[232:233], v[164:165], v[40:41]
	v_pk_fma_f32 v[170:171], v[38:39], v[38:39], v[170:171]
	v_pk_fma_f32 v[172:173], v[40:41], v[40:41], v[172:173]
	v_cvt_pk_bf16_f32 v168, v38, v39
	v_cvt_pk_bf16_f32 v169, v40, v41
	global_store_dwordx2 v245, v[168:169], s[22:23] offset:512
	ds_read_b128 v[226:229], v238 offset:11264
	ds_read_b128 v[230:233], v238 offset:44032
	s_waitcnt lgkmcnt(2)
	v_lshlrev_b32_e32 v162, 16, v150
	v_and_b32_e32 v163, 0xffff0000, v150
	v_lshlrev_b32_e32 v164, 16, v151
	v_and_b32_e32 v165, 0xffff0000, v151
	v_pk_mul_f32 v[162:163], v[162:163], v[252:253] op_sel_hi:[1,0]
	v_pk_mul_f32 v[164:165], v[164:165], v[252:253] op_sel_hi:[1,0]
	v_pk_mul_f32 v[162:163], v[162:163], v[214:215]
	v_pk_mul_f32 v[164:165], v[164:165], v[216:217]
	v_pk_fma_f32 v[42:43], v[218:219], v[162:163], v[42:43]
	v_pk_fma_f32 v[44:45], v[220:221], v[164:165], v[44:45]
	v_pk_fma_f32 v[170:171], v[42:43], v[42:43], v[170:171]
	v_pk_fma_f32 v[172:173], v[44:45], v[44:45], v[172:173]
	v_cvt_pk_bf16_f32 v166, v42, v43
	v_cvt_pk_bf16_f32 v167, v44, v45
	global_store_dwordx2 v245, v[166:167], s[22:23] offset:1024
	ds_read_b128 v[214:217], v238 offset:12288
	ds_read_b128 v[218:221], v238 offset:45056
	s_waitcnt lgkmcnt(2)
	v_lshlrev_b32_e32 v162, 16, v152
	v_and_b32_e32 v163, 0xffff0000, v152
	v_lshlrev_b32_e32 v164, 16, v153
	v_and_b32_e32 v165, 0xffff0000, v153
	v_pk_mul_f32 v[162:163], v[162:163], v[252:253] op_sel_hi:[1,0]
	v_pk_mul_f32 v[164:165], v[164:165], v[252:253] op_sel_hi:[1,0]
	v_pk_mul_f32 v[162:163], v[162:163], v[226:227]
	v_pk_mul_f32 v[164:165], v[164:165], v[228:229]
	v_pk_fma_f32 v[46:47], v[230:231], v[162:163], v[46:47]
	v_pk_fma_f32 v[48:49], v[232:233], v[164:165], v[48:49]
	v_pk_fma_f32 v[170:171], v[46:47], v[46:47], v[170:171]
	v_pk_fma_f32 v[172:173], v[48:49], v[48:49], v[172:173]
	v_cvt_pk_bf16_f32 v168, v46, v47
	v_cvt_pk_bf16_f32 v169, v48, v49
	global_store_dwordx2 v245, v[168:169], s[22:23] offset:1536
	ds_read_b128 v[226:229], v238 offset:13312
	ds_read_b128 v[230:233], v238 offset:46080
	s_waitcnt lgkmcnt(2)
	v_lshlrev_b32_e32 v162, 16, v154
	v_and_b32_e32 v163, 0xffff0000, v154
	v_lshlrev_b32_e32 v164, 16, v155
	v_and_b32_e32 v165, 0xffff0000, v155
	v_pk_mul_f32 v[162:163], v[162:163], v[252:253] op_sel_hi:[1,0]
	v_pk_mul_f32 v[164:165], v[164:165], v[252:253] op_sel_hi:[1,0]
	v_pk_mul_f32 v[162:163], v[162:163], v[214:215]
	v_pk_mul_f32 v[164:165], v[164:165], v[216:217]
	v_pk_fma_f32 v[50:51], v[218:219], v[162:163], v[50:51]
	v_pk_fma_f32 v[52:53], v[220:221], v[164:165], v[52:53]
	v_pk_fma_f32 v[170:171], v[50:51], v[50:51], v[170:171]
	v_pk_fma_f32 v[172:173], v[52:53], v[52:53], v[172:173]
	v_cvt_pk_bf16_f32 v166, v50, v51
	v_cvt_pk_bf16_f32 v167, v52, v53
	global_store_dwordx2 v245, v[166:167], s[22:23] offset:2048
	ds_read_b128 v[214:217], v238 offset:14336
	ds_read_b128 v[218:221], v238 offset:47104
	s_waitcnt lgkmcnt(2)
	v_lshlrev_b32_e32 v162, 16, v156
	v_and_b32_e32 v163, 0xffff0000, v156
	v_lshlrev_b32_e32 v164, 16, v157
	v_and_b32_e32 v165, 0xffff0000, v157
	v_pk_mul_f32 v[162:163], v[162:163], v[252:253] op_sel_hi:[1,0]
	v_pk_mul_f32 v[164:165], v[164:165], v[252:253] op_sel_hi:[1,0]
	v_pk_mul_f32 v[162:163], v[162:163], v[226:227]
	v_pk_mul_f32 v[164:165], v[164:165], v[228:229]
	v_pk_fma_f32 v[54:55], v[230:231], v[162:163], v[54:55]
	v_pk_fma_f32 v[56:57], v[232:233], v[164:165], v[56:57]
	v_pk_fma_f32 v[170:171], v[54:55], v[54:55], v[170:171]
	v_pk_fma_f32 v[172:173], v[56:57], v[56:57], v[172:173]
	v_cvt_pk_bf16_f32 v168, v54, v55
	v_cvt_pk_bf16_f32 v169, v56, v57
	global_store_dwordx2 v245, v[168:169], s[22:23] offset:2560
	ds_read_b128 v[226:229], v238 offset:15360
	ds_read_b128 v[230:233], v238 offset:48128
	s_waitcnt lgkmcnt(2)
	v_lshlrev_b32_e32 v162, 16, v158
	v_and_b32_e32 v163, 0xffff0000, v158
	v_lshlrev_b32_e32 v164, 16, v159
	v_and_b32_e32 v165, 0xffff0000, v159
	v_pk_mul_f32 v[162:163], v[162:163], v[252:253] op_sel_hi:[1,0]
	v_pk_mul_f32 v[164:165], v[164:165], v[252:253] op_sel_hi:[1,0]
	v_pk_mul_f32 v[162:163], v[162:163], v[214:215]
	v_pk_mul_f32 v[164:165], v[164:165], v[216:217]
	v_pk_fma_f32 v[58:59], v[218:219], v[162:163], v[58:59]
	v_pk_fma_f32 v[60:61], v[220:221], v[164:165], v[60:61]
	v_pk_fma_f32 v[170:171], v[58:59], v[58:59], v[170:171]
	v_pk_fma_f32 v[172:173], v[60:61], v[60:61], v[172:173]
	v_cvt_pk_bf16_f32 v166, v58, v59
	v_cvt_pk_bf16_f32 v167, v60, v61
	global_store_dwordx2 v245, v[166:167], s[22:23] offset:3072
	s_waitcnt lgkmcnt(0)
	v_lshlrev_b32_e32 v162, 16, v160
	v_and_b32_e32 v163, 0xffff0000, v160
	v_lshlrev_b32_e32 v164, 16, v161
	v_and_b32_e32 v165, 0xffff0000, v161
	v_pk_mul_f32 v[162:163], v[162:163], v[252:253] op_sel_hi:[1,0]
	v_pk_mul_f32 v[164:165], v[164:165], v[252:253] op_sel_hi:[1,0]
	v_pk_mul_f32 v[162:163], v[162:163], v[226:227]
	v_pk_mul_f32 v[164:165], v[164:165], v[228:229]
	v_pk_fma_f32 v[62:63], v[230:231], v[162:163], v[62:63]
	v_pk_fma_f32 v[64:65], v[232:233], v[164:165], v[64:65]
	v_pk_fma_f32 v[170:171], v[62:63], v[62:63], v[170:171]
	v_pk_fma_f32 v[172:173], v[64:65], v[64:65], v[172:173]
	v_cvt_pk_bf16_f32 v168, v62, v63
	v_cvt_pk_bf16_f32 v169, v64, v65
	global_store_dwordx2 v245, v[168:169], s[22:23] offset:3584
	ds_read_b128 v[214:217], v238 offset:16384
	ds_read_b128 v[218:221], v238 offset:49152
	ds_read_b128 v[222:225], v239 offset:0
	v_pk_add_f32 v[170:171], v[170:171], v[172:173]
	s_nop 0
	v_add_f32_e32 v252, v170, v171
	s_waitcnt lgkmcnt(0)
	ds_bpermute_b32 v254, v246, v252
	s_waitcnt lgkmcnt(0)
	v_add_f32_e32 v252, v252, v254
	ds_bpermute_b32 v254, v247, v252
	s_waitcnt lgkmcnt(0)
	v_add_f32_e32 v252, v252, v254
	ds_bpermute_b32 v254, v248, v252
	s_waitcnt lgkmcnt(0)
	v_add_f32_e32 v252, v252, v254
	ds_bpermute_b32 v254, v249, v252
	s_waitcnt lgkmcnt(0)
	v_add_f32_e32 v252, v252, v254
	ds_bpermute_b32 v254, v250, v252
	s_waitcnt lgkmcnt(0)
	v_add_f32_e32 v252, v252, v254
	ds_bpermute_b32 v254, v251, v252
	s_waitcnt lgkmcnt(0)
	v_add_f32_e32 v252, v252, v254
	v_mov_b32_e32 v254, 0x358637bd
	v_fmac_f32_e32 v254, 0x39800000, v252
	v_mul_f32_e32 v252, 0x4b800000, v254
	v_cmp_gt_f32_e32 vcc, s32, v254
	s_nop 1
	v_cndmask_b32_e32 v254, v254, v252, vcc
	v_rsq_f32_e32 v254, v254
	s_nop 0
	v_mul_f32_e32 v252, 0x45800000, v254
	v_cndmask_b32_e32 v252, v254, v252, vcc
	s_add_u32 s16, s16, 0x1000000
	s_addc_u32 s17, s17, 0
	global_load_dwordx2 v[130:131], v244, s[16:17] offset:0
	global_load_dwordx2 v[132:133], v244, s[16:17] offset:512
	global_load_dwordx2 v[134:135], v244, s[16:17] offset:1024
	global_load_dwordx2 v[136:137], v244, s[16:17] offset:1536
	global_load_dwordx2 v[138:139], v244, s[16:17] offset:2048
	global_load_dwordx2 v[140:141], v244, s[16:17] offset:2560
	global_load_dwordx2 v[142:143], v244, s[16:17] offset:3072
	global_load_dwordx2 v[144:145], v244, s[16:17] offset:3584
	global_load_dwordx2 v[146:147], v245, s[16:17] offset:0
	global_load_dwordx2 v[148:149], v245, s[16:17] offset:512
	global_load_dwordx2 v[150:151], v245, s[16:17] offset:1024
	global_load_dwordx2 v[152:153], v245, s[16:17] offset:1536
	global_load_dwordx2 v[154:155], v245, s[16:17] offset:2048
	global_load_dwordx2 v[156:157], v245, s[16:17] offset:2560
	global_load_dwordx2 v[158:159], v245, s[16:17] offset:3072
	global_load_dwordx2 v[160:161], v245, s[16:17] offset:3584
	ds_read_b128 v[226:229], v238 offset:17408
	ds_read_b128 v[230:233], v238 offset:50176
	ds_read_b128 v[234:237], v239 offset:1024
	s_waitcnt lgkmcnt(3)
	v_pk_mul_f32 v[2:3], v[2:3], v[252:253] op_sel_hi:[1,0]
	v_pk_mul_f32 v[4:5], v[4:5], v[252:253] op_sel_hi:[1,0]
	v_pk_mul_f32 v[2:3], v[2:3], v[214:215]
	v_pk_mul_f32 v[4:5], v[4:5], v[216:217]
	v_pk_add_f32 v[222:223], v[222:223], 1.0 op_sel_hi:[1,0]
	v_pk_add_f32 v[224:225], v[224:225], 1.0 op_sel_hi:[1,0]
	v_pk_fma_f32 v[2:3], v[2:3], v[222:223], v[218:219]
	v_pk_fma_f32 v[4:5], v[4:5], v[224:225], v[220:221]
	s_nop 0
	v_cvt_pk_bf16_f32 v2, v2, v3
	v_cvt_pk_bf16_f32 v3, v4, v5
	global_store_dwordx2 v244, v[2:3], s[38:39] offset:0
	ds_read_b128 v[214:217], v238 offset:18432
	ds_read_b128 v[218:221], v238 offset:51200
	ds_read_b128 v[222:225], v239 offset:2048
	s_waitcnt lgkmcnt(3)
	v_pk_mul_f32 v[6:7], v[6:7], v[252:253] op_sel_hi:[1,0]
	v_pk_mul_f32 v[8:9], v[8:9], v[252:253] op_sel_hi:[1,0]
	v_pk_mul_f32 v[6:7], v[6:7], v[226:227]
	v_pk_mul_f32 v[8:9], v[8:9], v[228:229]
	v_pk_add_f32 v[234:235], v[234:235], 1.0 op_sel_hi:[1,0]
	v_pk_add_f32 v[236:237], v[236:237], 1.0 op_sel_hi:[1,0]
	v_pk_fma_f32 v[6:7], v[6:7], v[234:235], v[230:231]
	v_pk_fma_f32 v[8:9], v[8:9], v[236:237], v[232:233]
	s_nop 0
	v_cvt_pk_bf16_f32 v6, v6, v7
	v_cvt_pk_bf16_f32 v7, v8, v9
	global_store_dwordx2 v244, v[6:7], s[38:39] offset:512
	ds_read_b128 v[226:229], v238 offset:19456
	ds_read_b128 v[230:233], v238 offset:52224
	ds_read_b128 v[234:237], v239 offset:3072
	s_waitcnt lgkmcnt(3)
	v_pk_mul_f32 v[10:11], v[10:11], v[252:253] op_sel_hi:[1,0]
	v_pk_mul_f32 v[12:13], v[12:13], v[252:253] op_sel_hi:[1,0]
	v_pk_mul_f32 v[10:11], v[10:11], v[214:215]
	v_pk_mul_f32 v[12:13], v[12:13], v[216:217]
	v_pk_add_f32 v[222:223], v[222:223], 1.0 op_sel_hi:[1,0]
	v_pk_add_f32 v[224:225], v[224:225], 1.0 op_sel_hi:[1,0]
	v_pk_fma_f32 v[10:11], v[10:11], v[222:223], v[218:219]
	v_pk_fma_f32 v[12:13], v[12:13], v[224:225], v[220:221]
	s_nop 0
	v_cvt_pk_bf16_f32 v10, v10, v11
	v_cvt_pk_bf16_f32 v11, v12, v13
	global_store_dwordx2 v244, v[10:11], s[38:39] offset:1024
	ds_read_b128 v[214:217], v238 offset:20480
	ds_read_b128 v[218:221], v238 offset:53248
	ds_read_b128 v[222:225], v239 offset:4096
	s_waitcnt lgkmcnt(3)
	v_pk_mul_f32 v[14:15], v[14:15], v[252:253] op_sel_hi:[1,0]
	v_pk_mul_f32 v[16:17], v[16:17], v[252:253] op_sel_hi:[1,0]
	v_pk_mul_f32 v[14:15], v[14:15], v[226:227]
	v_pk_mul_f32 v[16:17], v[16:17], v[228:229]
	v_pk_add_f32 v[234:235], v[234:235], 1.0 op_sel_hi:[1,0]
	v_pk_add_f32 v[236:237], v[236:237], 1.0 op_sel_hi:[1,0]
	v_pk_fma_f32 v[14:15], v[14:15], v[234:235], v[230:231]
	v_pk_fma_f32 v[16:17], v[16:17], v[236:237], v[232:233]
	s_nop 0
	v_cvt_pk_bf16_f32 v14, v14, v15
	v_cvt_pk_bf16_f32 v15, v16, v17
	global_store_dwordx2 v244, v[14:15], s[38:39] offset:1536
	ds_read_b128 v[226:229], v238 offset:21504
	ds_read_b128 v[230:233], v238 offset:54272
	ds_read_b128 v[234:237], v239 offset:5120
	s_waitcnt lgkmcnt(3)
	v_pk_mul_f32 v[18:19], v[18:19], v[252:253] op_sel_hi:[1,0]
	v_pk_mul_f32 v[20:21], v[20:21], v[252:253] op_sel_hi:[1,0]
	v_pk_mul_f32 v[18:19], v[18:19], v[214:215]
	v_pk_mul_f32 v[20:21], v[20:21], v[216:217]
	v_pk_add_f32 v[222:223], v[222:223], 1.0 op_sel_hi:[1,0]
	v_pk_add_f32 v[224:225], v[224:225], 1.0 op_sel_hi:[1,0]
	v_pk_fma_f32 v[18:19], v[18:19], v[222:223], v[218:219]
	v_pk_fma_f32 v[20:21], v[20:21], v[224:225], v[220:221]
	s_nop 0
	v_cvt_pk_bf16_f32 v18, v18, v19
	v_cvt_pk_bf16_f32 v19, v20, v21
	global_store_dwordx2 v244, v[18:19], s[38:39] offset:2048
	ds_read_b128 v[214:217], v238 offset:22528
	ds_read_b128 v[218:221], v238 offset:55296
	ds_read_b128 v[222:225], v239 offset:6144
	s_waitcnt lgkmcnt(3)
	v_pk_mul_f32 v[22:23], v[22:23], v[252:253] op_sel_hi:[1,0]
	v_pk_mul_f32 v[24:25], v[24:25], v[252:253] op_sel_hi:[1,0]
	v_pk_mul_f32 v[22:23], v[22:23], v[226:227]
	v_pk_mul_f32 v[24:25], v[24:25], v[228:229]
	v_pk_add_f32 v[234:235], v[234:235], 1.0 op_sel_hi:[1,0]
	v_pk_add_f32 v[236:237], v[236:237], 1.0 op_sel_hi:[1,0]
	v_pk_fma_f32 v[22:23], v[22:23], v[234:235], v[230:231]
	v_pk_fma_f32 v[24:25], v[24:25], v[236:237], v[232:233]
	s_nop 0
	v_cvt_pk_bf16_f32 v22, v22, v23
	v_cvt_pk_bf16_f32 v23, v24, v25
	global_store_dwordx2 v244, v[22:23], s[38:39] offset:2560
	ds_read_b128 v[226:229], v238 offset:23552
	ds_read_b128 v[230:233], v238 offset:56320
	ds_read_b128 v[234:237], v239 offset:7168
	s_waitcnt lgkmcnt(3)
	v_pk_mul_f32 v[26:27], v[26:27], v[252:253] op_sel_hi:[1,0]
	v_pk_mul_f32 v[28:29], v[28:29], v[252:253] op_sel_hi:[1,0]
	v_pk_mul_f32 v[26:27], v[26:27], v[214:215]
	v_pk_mul_f32 v[28:29], v[28:29], v[216:217]
	v_pk_add_f32 v[222:223], v[222:223], 1.0 op_sel_hi:[1,0]
	v_pk_add_f32 v[224:225], v[224:225], 1.0 op_sel_hi:[1,0]
	v_pk_fma_f32 v[26:27], v[26:27], v[222:223], v[218:219]
	v_pk_fma_f32 v[28:29], v[28:29], v[224:225], v[220:221]
	s_nop 0
	v_cvt_pk_bf16_f32 v26, v26, v27
	v_cvt_pk_bf16_f32 v27, v28, v29
	global_store_dwordx2 v244, v[26:27], s[38:39] offset:3072
	ds_read_b128 v[214:217], v238 offset:24576
	ds_read_b128 v[218:221], v238 offset:57344
	ds_read_b128 v[222:225], v239 offset:8192
	s_waitcnt lgkmcnt(3)
	v_pk_mul_f32 v[30:31], v[30:31], v[252:253] op_sel_hi:[1,0]
	v_pk_mul_f32 v[32:33], v[32:33], v[252:253] op_sel_hi:[1,0]
	v_pk_mul_f32 v[30:31], v[30:31], v[226:227]
	v_pk_mul_f32 v[32:33], v[32:33], v[228:229]
	v_pk_add_f32 v[234:235], v[234:235], 1.0 op_sel_hi:[1,0]
	v_pk_add_f32 v[236:237], v[236:237], 1.0 op_sel_hi:[1,0]
	v_pk_fma_f32 v[30:31], v[30:31], v[234:235], v[230:231]
	v_pk_fma_f32 v[32:33], v[32:33], v[236:237], v[232:233]
	s_nop 0
	v_cvt_pk_bf16_f32 v30, v30, v31
	v_cvt_pk_bf16_f32 v31, v32, v33
	global_store_dwordx2 v244, v[30:31], s[38:39] offset:3584
	ds_read_b128 v[226:229], v238 offset:25600
	ds_read_b128 v[230:233], v238 offset:58368
	ds_read_b128 v[234:237], v239 offset:9216
	s_waitcnt lgkmcnt(3)
	v_pk_mul_f32 v[34:35], v[34:35], v[252:253] op_sel_hi:[1,0]
	v_pk_mul_f32 v[36:37], v[36:37], v[252:253] op_sel_hi:[1,0]
	v_pk_mul_f32 v[34:35], v[34:35], v[214:215]
	v_pk_mul_f32 v[36:37], v[36:37], v[216:217]
	v_pk_add_f32 v[222:223], v[222:223], 1.0 op_sel_hi:[1,0]
	v_pk_add_f32 v[224:225], v[224:225], 1.0 op_sel_hi:[1,0]
	v_pk_fma_f32 v[34:35], v[34:35], v[222:223], v[218:219]
	v_pk_fma_f32 v[36:37], v[36:37], v[224:225], v[220:221]
	s_nop 0
	v_cvt_pk_bf16_f32 v34, v34, v35
	v_cvt_pk_bf16_f32 v35, v36, v37
	global_store_dwordx2 v245, v[34:35], s[38:39] offset:0
	ds_read_b128 v[214:217], v238 offset:26624
	ds_read_b128 v[218:221], v238 offset:59392
	ds_read_b128 v[222:225], v239 offset:10240
	s_waitcnt lgkmcnt(3)
	v_pk_mul_f32 v[38:39], v[38:39], v[252:253] op_sel_hi:[1,0]
	v_pk_mul_f32 v[40:41], v[40:41], v[252:253] op_sel_hi:[1,0]
	v_pk_mul_f32 v[38:39], v[38:39], v[226:227]
	v_pk_mul_f32 v[40:41], v[40:41], v[228:229]
	v_pk_add_f32 v[234:235], v[234:235], 1.0 op_sel_hi:[1,0]
	v_pk_add_f32 v[236:237], v[236:237], 1.0 op_sel_hi:[1,0]
	v_pk_fma_f32 v[38:39], v[38:39], v[234:235], v[230:231]
	v_pk_fma_f32 v[40:41], v[40:41], v[236:237], v[232:233]
	s_nop 0
	v_cvt_pk_bf16_f32 v38, v38, v39
	v_cvt_pk_bf16_f32 v39, v40, v41
	global_store_dwordx2 v245, v[38:39], s[38:39] offset:512
	ds_read_b128 v[226:229], v238 offset:27648
	ds_read_b128 v[230:233], v238 offset:60416
	ds_read_b128 v[234:237], v239 offset:11264
	s_waitcnt lgkmcnt(3)
	v_pk_mul_f32 v[42:43], v[42:43], v[252:253] op_sel_hi:[1,0]
	v_pk_mul_f32 v[44:45], v[44:45], v[252:253] op_sel_hi:[1,0]
	v_pk_mul_f32 v[42:43], v[42:43], v[214:215]
	v_pk_mul_f32 v[44:45], v[44:45], v[216:217]
	v_pk_add_f32 v[222:223], v[222:223], 1.0 op_sel_hi:[1,0]
	v_pk_add_f32 v[224:225], v[224:225], 1.0 op_sel_hi:[1,0]
	v_pk_fma_f32 v[42:43], v[42:43], v[222:223], v[218:219]
	v_pk_fma_f32 v[44:45], v[44:45], v[224:225], v[220:221]
	s_nop 0
	v_cvt_pk_bf16_f32 v42, v42, v43
	v_cvt_pk_bf16_f32 v43, v44, v45
	global_store_dwordx2 v245, v[42:43], s[38:39] offset:1024
	ds_read_b128 v[214:217], v238 offset:28672
	ds_read_b128 v[218:221], v238 offset:61440
	ds_read_b128 v[222:225], v239 offset:12288
	s_waitcnt lgkmcnt(3)
	v_pk_mul_f32 v[46:47], v[46:47], v[252:253] op_sel_hi:[1,0]
	v_pk_mul_f32 v[48:49], v[48:49], v[252:253] op_sel_hi:[1,0]
	v_pk_mul_f32 v[46:47], v[46:47], v[226:227]
	v_pk_mul_f32 v[48:49], v[48:49], v[228:229]
	v_pk_add_f32 v[234:235], v[234:235], 1.0 op_sel_hi:[1,0]
	v_pk_add_f32 v[236:237], v[236:237], 1.0 op_sel_hi:[1,0]
	v_pk_fma_f32 v[46:47], v[46:47], v[234:235], v[230:231]
	v_pk_fma_f32 v[48:49], v[48:49], v[236:237], v[232:233]
	s_nop 0
	v_cvt_pk_bf16_f32 v46, v46, v47
	v_cvt_pk_bf16_f32 v47, v48, v49
	global_store_dwordx2 v245, v[46:47], s[38:39] offset:1536
	ds_read_b128 v[226:229], v238 offset:29696
	ds_read_b128 v[230:233], v238 offset:62464
	ds_read_b128 v[234:237], v239 offset:13312
	s_waitcnt lgkmcnt(3)
	v_pk_mul_f32 v[50:51], v[50:51], v[252:253] op_sel_hi:[1,0]
	v_pk_mul_f32 v[52:53], v[52:53], v[252:253] op_sel_hi:[1,0]
	v_pk_mul_f32 v[50:51], v[50:51], v[214:215]
	v_pk_mul_f32 v[52:53], v[52:53], v[216:217]
	v_pk_add_f32 v[222:223], v[222:223], 1.0 op_sel_hi:[1,0]
	v_pk_add_f32 v[224:225], v[224:225], 1.0 op_sel_hi:[1,0]
	v_pk_fma_f32 v[50:51], v[50:51], v[222:223], v[218:219]
	v_pk_fma_f32 v[52:53], v[52:53], v[224:225], v[220:221]
	s_nop 0
	v_cvt_pk_bf16_f32 v50, v50, v51
	v_cvt_pk_bf16_f32 v51, v52, v53
	global_store_dwordx2 v245, v[50:51], s[38:39] offset:2048
	ds_read_b128 v[214:217], v238 offset:30720
	ds_read_b128 v[218:221], v238 offset:63488
	ds_read_b128 v[222:225], v239 offset:14336
	s_waitcnt lgkmcnt(3)
	v_pk_mul_f32 v[54:55], v[54:55], v[252:253] op_sel_hi:[1,0]
	v_pk_mul_f32 v[56:57], v[56:57], v[252:253] op_sel_hi:[1,0]
	v_pk_mul_f32 v[54:55], v[54:55], v[226:227]
	v_pk_mul_f32 v[56:57], v[56:57], v[228:229]
	v_pk_add_f32 v[234:235], v[234:235], 1.0 op_sel_hi:[1,0]
	v_pk_add_f32 v[236:237], v[236:237], 1.0 op_sel_hi:[1,0]
	v_pk_fma_f32 v[54:55], v[54:55], v[234:235], v[230:231]
	v_pk_fma_f32 v[56:57], v[56:57], v[236:237], v[232:233]
	s_nop 0
	v_cvt_pk_bf16_f32 v54, v54, v55
	v_cvt_pk_bf16_f32 v55, v56, v57
	global_store_dwordx2 v245, v[54:55], s[38:39] offset:2560
	ds_read_b128 v[226:229], v238 offset:31744
	ds_read_b128 v[230:233], v238 offset:64512
	ds_read_b128 v[234:237], v239 offset:15360
	s_waitcnt lgkmcnt(3)
	v_pk_mul_f32 v[58:59], v[58:59], v[252:253] op_sel_hi:[1,0]
	v_pk_mul_f32 v[60:61], v[60:61], v[252:253] op_sel_hi:[1,0]
	v_pk_mul_f32 v[58:59], v[58:59], v[214:215]
	v_pk_mul_f32 v[60:61], v[60:61], v[216:217]
	v_pk_add_f32 v[222:223], v[222:223], 1.0 op_sel_hi:[1,0]
	v_pk_add_f32 v[224:225], v[224:225], 1.0 op_sel_hi:[1,0]
	v_pk_fma_f32 v[58:59], v[58:59], v[222:223], v[218:219]
	v_pk_fma_f32 v[60:61], v[60:61], v[224:225], v[220:221]
	s_nop 0
	v_cvt_pk_bf16_f32 v58, v58, v59
	v_cvt_pk_bf16_f32 v59, v60, v61
	global_store_dwordx2 v245, v[58:59], s[38:39] offset:3072
	s_waitcnt lgkmcnt(0)
	v_pk_mul_f32 v[62:63], v[62:63], v[252:253] op_sel_hi:[1,0]
	v_pk_mul_f32 v[64:65], v[64:65], v[252:253] op_sel_hi:[1,0]
	v_pk_mul_f32 v[62:63], v[62:63], v[226:227]
	v_pk_mul_f32 v[64:65], v[64:65], v[228:229]
	v_pk_add_f32 v[234:235], v[234:235], 1.0 op_sel_hi:[1,0]
	v_pk_add_f32 v[236:237], v[236:237], 1.0 op_sel_hi:[1,0]
	v_pk_fma_f32 v[62:63], v[62:63], v[234:235], v[230:231]
	v_pk_fma_f32 v[64:65], v[64:65], v[236:237], v[232:233]
	s_nop 0
	v_cvt_pk_bf16_f32 v62, v62, v63
	v_cvt_pk_bf16_f32 v63, v64, v65
	global_store_dwordx2 v245, v[62:63], s[38:39] offset:3584
	s_add_u32 s22, s22, 0x1000000
	s_addc_u32 s23, s23, 0
	s_add_u32 s38, s38, 0x1000000
	s_addc_u32 s39, s39, 0
	s_waitcnt vmcnt(16)
	s_add_u32 s14, s14, 0x2000000
	s_addc_u32 s15, s15, 0
	global_load_dwordx4 v[2:5], v238, s[14:15] offset:0
	global_load_dwordx4 v[6:9], v238, s[14:15] offset:1024
	global_load_dwordx4 v[10:13], v238, s[14:15] offset:2048
	global_load_dwordx4 v[14:17], v238, s[14:15] offset:3072
	global_load_dwordx4 v[18:21], v241, s[14:15] offset:0
	global_load_dwordx4 v[22:25], v241, s[14:15] offset:1024
	global_load_dwordx4 v[26:29], v241, s[14:15] offset:2048
	global_load_dwordx4 v[30:33], v241, s[14:15] offset:3072
	global_load_dwordx4 v[34:37], v242, s[14:15] offset:0
	global_load_dwordx4 v[38:41], v242, s[14:15] offset:1024
	global_load_dwordx4 v[42:45], v242, s[14:15] offset:2048
	global_load_dwordx4 v[46:49], v242, s[14:15] offset:3072
	global_load_dwordx4 v[50:53], v243, s[14:15] offset:0
	global_load_dwordx4 v[54:57], v243, s[14:15] offset:1024
	global_load_dwordx4 v[58:61], v243, s[14:15] offset:2048
	global_load_dwordx4 v[62:65], v243, s[14:15] offset:3072
	ds_read_b128 v[214:217], v238 offset:0
	ds_read_b128 v[218:221], v238 offset:32768
	v_lshlrev_b32_e32 v162, 16, v130
	v_and_b32_e32 v163, 0xffff0000, v130
	v_lshlrev_b32_e32 v164, 16, v131
	v_and_b32_e32 v165, 0xffff0000, v131
	v_pk_mul_f32 v[170:171], v[162:163], v[162:163]
	v_pk_mul_f32 v[172:173], v[164:165], v[164:165]
	v_lshlrev_b32_e32 v166, 16, v132
	v_and_b32_e32 v167, 0xffff0000, v132
	v_lshlrev_b32_e32 v168, 16, v133
	v_and_b32_e32 v169, 0xffff0000, v133
	v_pk_fma_f32 v[170:171], v[166:167], v[166:167], v[170:171]
	v_pk_fma_f32 v[172:173], v[168:169], v[168:169], v[172:173]
	v_lshlrev_b32_e32 v162, 16, v134
	v_and_b32_e32 v163, 0xffff0000, v134
	v_lshlrev_b32_e32 v164, 16, v135
	v_and_b32_e32 v165, 0xffff0000, v135
	v_pk_fma_f32 v[170:171], v[162:163], v[162:163], v[170:171]
	v_pk_fma_f32 v[172:173], v[164:165], v[164:165], v[172:173]
	v_lshlrev_b32_e32 v166, 16, v136
	v_and_b32_e32 v167, 0xffff0000, v136
	v_lshlrev_b32_e32 v168, 16, v137
	v_and_b32_e32 v169, 0xffff0000, v137
	v_pk_fma_f32 v[170:171], v[166:167], v[166:167], v[170:171]
	v_pk_fma_f32 v[172:173], v[168:169], v[168:169], v[172:173]
	v_lshlrev_b32_e32 v162, 16, v138
	v_and_b32_e32 v163, 0xffff0000, v138
	v_lshlrev_b32_e32 v164, 16, v139
	v_and_b32_e32 v165, 0xffff0000, v139
	v_pk_fma_f32 v[170:171], v[162:163], v[162:163], v[170:171]
	v_pk_fma_f32 v[172:173], v[164:165], v[164:165], v[172:173]
	v_lshlrev_b32_e32 v166, 16, v140
	v_and_b32_e32 v167, 0xffff0000, v140
	v_lshlrev_b32_e32 v168, 16, v141
	v_and_b32_e32 v169, 0xffff0000, v141
	v_pk_fma_f32 v[170:171], v[166:167], v[166:167], v[170:171]
	v_pk_fma_f32 v[172:173], v[168:169], v[168:169], v[172:173]
	v_lshlrev_b32_e32 v162, 16, v142
	v_and_b32_e32 v163, 0xffff0000, v142
	v_lshlrev_b32_e32 v164, 16, v143
	v_and_b32_e32 v165, 0xffff0000, v143
	v_pk_fma_f32 v[170:171], v[162:163], v[162:163], v[170:171]
	v_pk_fma_f32 v[172:173], v[164:165], v[164:165], v[172:173]
	v_lshlrev_b32_e32 v166, 16, v144
	v_and_b32_e32 v167, 0xffff0000, v144
	v_lshlrev_b32_e32 v168, 16, v145
	v_and_b32_e32 v169, 0xffff0000, v145
	v_pk_fma_f32 v[170:171], v[166:167], v[166:167], v[170:171]
	v_pk_fma_f32 v[172:173], v[168:169], v[168:169], v[172:173]
	v_lshlrev_b32_e32 v162, 16, v146
	v_and_b32_e32 v163, 0xffff0000, v146
	v_lshlrev_b32_e32 v164, 16, v147
	v_and_b32_e32 v165, 0xffff0000, v147
	v_pk_fma_f32 v[170:171], v[162:163], v[162:163], v[170:171]
	v_pk_fma_f32 v[172:173], v[164:165], v[164:165], v[172:173]
	v_lshlrev_b32_e32 v166, 16, v148
	v_and_b32_e32 v167, 0xffff0000, v148
	v_lshlrev_b32_e32 v168, 16, v149
	v_and_b32_e32 v169, 0xffff0000, v149
	v_pk_fma_f32 v[170:171], v[166:167], v[166:167], v[170:171]
	v_pk_fma_f32 v[172:173], v[168:169], v[168:169], v[172:173]
	v_lshlrev_b32_e32 v162, 16, v150
	v_and_b32_e32 v163, 0xffff0000, v150
	v_lshlrev_b32_e32 v164, 16, v151
	v_and_b32_e32 v165, 0xffff0000, v151
	v_pk_fma_f32 v[170:171], v[162:163], v[162:163], v[170:171]
	v_pk_fma_f32 v[172:173], v[164:165], v[164:165], v[172:173]
	v_lshlrev_b32_e32 v166, 16, v152
	v_and_b32_e32 v167, 0xffff0000, v152
	v_lshlrev_b32_e32 v168, 16, v153
	v_and_b32_e32 v169, 0xffff0000, v153
	v_pk_fma_f32 v[170:171], v[166:167], v[166:167], v[170:171]
	v_pk_fma_f32 v[172:173], v[168:169], v[168:169], v[172:173]
	v_lshlrev_b32_e32 v162, 16, v154
	v_and_b32_e32 v163, 0xffff0000, v154
	v_lshlrev_b32_e32 v164, 16, v155
	v_and_b32_e32 v165, 0xffff0000, v155
	v_pk_fma_f32 v[170:171], v[162:163], v[162:163], v[170:171]
	v_pk_fma_f32 v[172:173], v[164:165], v[164:165], v[172:173]
	v_lshlrev_b32_e32 v166, 16, v156
	v_and_b32_e32 v167, 0xffff0000, v156
	v_lshlrev_b32_e32 v168, 16, v157
	v_and_b32_e32 v169, 0xffff0000, v157
	v_pk_fma_f32 v[170:171], v[166:167], v[166:167], v[170:171]
	v_pk_fma_f32 v[172:173], v[168:169], v[168:169], v[172:173]
	v_lshlrev_b32_e32 v162, 16, v158
	v_and_b32_e32 v163, 0xffff0000, v158
	v_lshlrev_b32_e32 v164, 16, v159
	v_and_b32_e32 v165, 0xffff0000, v159
	v_pk_fma_f32 v[170:171], v[162:163], v[162:163], v[170:171]
	v_pk_fma_f32 v[172:173], v[164:165], v[164:165], v[172:173]
	v_lshlrev_b32_e32 v166, 16, v160
	v_and_b32_e32 v167, 0xffff0000, v160
	v_lshlrev_b32_e32 v168, 16, v161
	v_and_b32_e32 v169, 0xffff0000, v161
	v_pk_fma_f32 v[170:171], v[166:167], v[166:167], v[170:171]
	v_pk_fma_f32 v[172:173], v[168:169], v[168:169], v[172:173]
	v_pk_add_f32 v[170:171], v[170:171], v[172:173]
	s_nop 0
	v_add_f32_e32 v252, v170, v171
	s_waitcnt lgkmcnt(0)
	ds_bpermute_b32 v254, v246, v252
	s_waitcnt lgkmcnt(0)
	v_add_f32_e32 v252, v252, v254
	ds_bpermute_b32 v254, v247, v252
	s_waitcnt lgkmcnt(0)
	v_add_f32_e32 v252, v252, v254
	ds_bpermute_b32 v254, v248, v252
	s_waitcnt lgkmcnt(0)
	v_add_f32_e32 v252, v252, v254
	ds_bpermute_b32 v254, v249, v252
	s_waitcnt lgkmcnt(0)
	v_add_f32_e32 v252, v252, v254
	ds_bpermute_b32 v254, v250, v252
	s_waitcnt lgkmcnt(0)
	v_add_f32_e32 v252, v252, v254
	ds_bpermute_b32 v254, v251, v252
	s_waitcnt lgkmcnt(0)
	v_add_f32_e32 v252, v252, v254
	v_mov_b32_e32 v254, 0x358637bd
	v_fmac_f32_e32 v254, 0x39800000, v252
	v_mul_f32_e32 v252, 0x4b800000, v254
	v_cmp_gt_f32_e32 vcc, s32, v254
	s_nop 1
	v_cndmask_b32_e32 v254, v254, v252, vcc
	v_rsq_f32_e32 v254, v254
	s_nop 0
	v_mul_f32_e32 v252, 0x45800000, v254
	v_cndmask_b32_e32 v252, v254, v252, vcc
	ds_read_b128 v[226:229], v238 offset:1024
	ds_read_b128 v[230:233], v238 offset:33792
	s_waitcnt lgkmcnt(2)
	v_lshlrev_b32_e32 v162, 16, v130
	v_and_b32_e32 v163, 0xffff0000, v130
	v_lshlrev_b32_e32 v164, 16, v131
	v_and_b32_e32 v165, 0xffff0000, v131
	v_pk_mul_f32 v[162:163], v[162:163], v[252:253] op_sel_hi:[1,0]
	v_pk_mul_f32 v[164:165], v[164:165], v[252:253] op_sel_hi:[1,0]
	v_pk_mul_f32 v[162:163], v[162:163], v[214:215]
	v_pk_mul_f32 v[164:165], v[164:165], v[216:217]
	v_pk_fma_f32 v[66:67], v[218:219], v[162:163], v[66:67]
	v_pk_fma_f32 v[68:69], v[220:221], v[164:165], v[68:69]
	v_pk_mul_f32 v[170:171], v[66:67], v[66:67]
	v_pk_mul_f32 v[172:173], v[68:69], v[68:69]
	v_cvt_pk_bf16_f32 v166, v66, v67
	v_cvt_pk_bf16_f32 v167, v68, v69
	global_store_dwordx2 v244, v[166:167], s[22:23] offset:0
	ds_read_b128 v[214:217], v238 offset:2048
	ds_read_b128 v[218:221], v238 offset:34816
	s_waitcnt lgkmcnt(2)
	v_lshlrev_b32_e32 v162, 16, v132
	v_and_b32_e32 v163, 0xffff0000, v132
	v_lshlrev_b32_e32 v164, 16, v133
	v_and_b32_e32 v165, 0xffff0000, v133
	v_pk_mul_f32 v[162:163], v[162:163], v[252:253] op_sel_hi:[1,0]
	v_pk_mul_f32 v[164:165], v[164:165], v[252:253] op_sel_hi:[1,0]
	v_pk_mul_f32 v[162:163], v[162:163], v[226:227]
	v_pk_mul_f32 v[164:165], v[164:165], v[228:229]
	v_pk_fma_f32 v[70:71], v[230:231], v[162:163], v[70:71]
	v_pk_fma_f32 v[72:73], v[232:233], v[164:165], v[72:73]
	v_pk_fma_f32 v[170:171], v[70:71], v[70:71], v[170:171]
	v_pk_fma_f32 v[172:173], v[72:73], v[72:73], v[172:173]
	v_cvt_pk_bf16_f32 v168, v70, v71
	v_cvt_pk_bf16_f32 v169, v72, v73
	global_store_dwordx2 v244, v[168:169], s[22:23] offset:512
	ds_read_b128 v[226:229], v238 offset:3072
	ds_read_b128 v[230:233], v238 offset:35840
	s_waitcnt lgkmcnt(2)
	v_lshlrev_b32_e32 v162, 16, v134
	v_and_b32_e32 v163, 0xffff0000, v134
	v_lshlrev_b32_e32 v164, 16, v135
	v_and_b32_e32 v165, 0xffff0000, v135
	v_pk_mul_f32 v[162:163], v[162:163], v[252:253] op_sel_hi:[1,0]
	v_pk_mul_f32 v[164:165], v[164:165], v[252:253] op_sel_hi:[1,0]
	v_pk_mul_f32 v[162:163], v[162:163], v[214:215]
	v_pk_mul_f32 v[164:165], v[164:165], v[216:217]
	v_pk_fma_f32 v[74:75], v[218:219], v[162:163], v[74:75]
	v_pk_fma_f32 v[76:77], v[220:221], v[164:165], v[76:77]
	v_pk_fma_f32 v[170:171], v[74:75], v[74:75], v[170:171]
	v_pk_fma_f32 v[172:173], v[76:77], v[76:77], v[172:173]
	v_cvt_pk_bf16_f32 v166, v74, v75
	v_cvt_pk_bf16_f32 v167, v76, v77
	global_store_dwordx2 v244, v[166:167], s[22:23] offset:1024
	ds_read_b128 v[214:217], v238 offset:4096
	ds_read_b128 v[218:221], v238 offset:36864
	s_waitcnt lgkmcnt(2)
	v_lshlrev_b32_e32 v162, 16, v136
	v_and_b32_e32 v163, 0xffff0000, v136
	v_lshlrev_b32_e32 v164, 16, v137
	v_and_b32_e32 v165, 0xffff0000, v137
	v_pk_mul_f32 v[162:163], v[162:163], v[252:253] op_sel_hi:[1,0]
	v_pk_mul_f32 v[164:165], v[164:165], v[252:253] op_sel_hi:[1,0]
	v_pk_mul_f32 v[162:163], v[162:163], v[226:227]
	v_pk_mul_f32 v[164:165], v[164:165], v[228:229]
	v_pk_fma_f32 v[78:79], v[230:231], v[162:163], v[78:79]
	v_pk_fma_f32 v[80:81], v[232:233], v[164:165], v[80:81]
	v_pk_fma_f32 v[170:171], v[78:79], v[78:79], v[170:171]
	v_pk_fma_f32 v[172:173], v[80:81], v[80:81], v[172:173]
	v_cvt_pk_bf16_f32 v168, v78, v79
	v_cvt_pk_bf16_f32 v169, v80, v81
	global_store_dwordx2 v244, v[168:169], s[22:23] offset:1536
	ds_read_b128 v[226:229], v238 offset:5120
	ds_read_b128 v[230:233], v238 offset:37888
	s_waitcnt lgkmcnt(2)
	v_lshlrev_b32_e32 v162, 16, v138
	v_and_b32_e32 v163, 0xffff0000, v138
	v_lshlrev_b32_e32 v164, 16, v139
	v_and_b32_e32 v165, 0xffff0000, v139
	v_pk_mul_f32 v[162:163], v[162:163], v[252:253] op_sel_hi:[1,0]
	v_pk_mul_f32 v[164:165], v[164:165], v[252:253] op_sel_hi:[1,0]
	v_pk_mul_f32 v[162:163], v[162:163], v[214:215]
	v_pk_mul_f32 v[164:165], v[164:165], v[216:217]
	v_pk_fma_f32 v[82:83], v[218:219], v[162:163], v[82:83]
	v_pk_fma_f32 v[84:85], v[220:221], v[164:165], v[84:85]
	v_pk_fma_f32 v[170:171], v[82:83], v[82:83], v[170:171]
	v_pk_fma_f32 v[172:173], v[84:85], v[84:85], v[172:173]
	v_cvt_pk_bf16_f32 v166, v82, v83
	v_cvt_pk_bf16_f32 v167, v84, v85
	global_store_dwordx2 v244, v[166:167], s[22:23] offset:2048
	ds_read_b128 v[214:217], v238 offset:6144
	ds_read_b128 v[218:221], v238 offset:38912
	s_waitcnt lgkmcnt(2)
	v_lshlrev_b32_e32 v162, 16, v140
	v_and_b32_e32 v163, 0xffff0000, v140
	v_lshlrev_b32_e32 v164, 16, v141
	v_and_b32_e32 v165, 0xffff0000, v141
	v_pk_mul_f32 v[162:163], v[162:163], v[252:253] op_sel_hi:[1,0]
	v_pk_mul_f32 v[164:165], v[164:165], v[252:253] op_sel_hi:[1,0]
	v_pk_mul_f32 v[162:163], v[162:163], v[226:227]
	v_pk_mul_f32 v[164:165], v[164:165], v[228:229]
	v_pk_fma_f32 v[86:87], v[230:231], v[162:163], v[86:87]
	v_pk_fma_f32 v[88:89], v[232:233], v[164:165], v[88:89]
	v_pk_fma_f32 v[170:171], v[86:87], v[86:87], v[170:171]
	v_pk_fma_f32 v[172:173], v[88:89], v[88:89], v[172:173]
	v_cvt_pk_bf16_f32 v168, v86, v87
	v_cvt_pk_bf16_f32 v169, v88, v89
	global_store_dwordx2 v244, v[168:169], s[22:23] offset:2560
	ds_read_b128 v[226:229], v238 offset:7168
	ds_read_b128 v[230:233], v238 offset:39936
	s_waitcnt lgkmcnt(2)
	v_lshlrev_b32_e32 v162, 16, v142
	v_and_b32_e32 v163, 0xffff0000, v142
	v_lshlrev_b32_e32 v164, 16, v143
	v_and_b32_e32 v165, 0xffff0000, v143
	v_pk_mul_f32 v[162:163], v[162:163], v[252:253] op_sel_hi:[1,0]
	v_pk_mul_f32 v[164:165], v[164:165], v[252:253] op_sel_hi:[1,0]
	v_pk_mul_f32 v[162:163], v[162:163], v[214:215]
	v_pk_mul_f32 v[164:165], v[164:165], v[216:217]
	v_pk_fma_f32 v[90:91], v[218:219], v[162:163], v[90:91]
	v_pk_fma_f32 v[92:93], v[220:221], v[164:165], v[92:93]
	v_pk_fma_f32 v[170:171], v[90:91], v[90:91], v[170:171]
	v_pk_fma_f32 v[172:173], v[92:93], v[92:93], v[172:173]
	v_cvt_pk_bf16_f32 v166, v90, v91
	v_cvt_pk_bf16_f32 v167, v92, v93
	global_store_dwordx2 v244, v[166:167], s[22:23] offset:3072
	ds_read_b128 v[214:217], v238 offset:8192
	ds_read_b128 v[218:221], v238 offset:40960
	s_waitcnt lgkmcnt(2)
	v_lshlrev_b32_e32 v162, 16, v144
	v_and_b32_e32 v163, 0xffff0000, v144
	v_lshlrev_b32_e32 v164, 16, v145
	v_and_b32_e32 v165, 0xffff0000, v145
	v_pk_mul_f32 v[162:163], v[162:163], v[252:253] op_sel_hi:[1,0]
	v_pk_mul_f32 v[164:165], v[164:165], v[252:253] op_sel_hi:[1,0]
	v_pk_mul_f32 v[162:163], v[162:163], v[226:227]
	v_pk_mul_f32 v[164:165], v[164:165], v[228:229]
	v_pk_fma_f32 v[94:95], v[230:231], v[162:163], v[94:95]
	v_pk_fma_f32 v[96:97], v[232:233], v[164:165], v[96:97]
	v_pk_fma_f32 v[170:171], v[94:95], v[94:95], v[170:171]
	v_pk_fma_f32 v[172:173], v[96:97], v[96:97], v[172:173]
	v_cvt_pk_bf16_f32 v168, v94, v95
	v_cvt_pk_bf16_f32 v169, v96, v97
	global_store_dwordx2 v244, v[168:169], s[22:23] offset:3584
	ds_read_b128 v[226:229], v238 offset:9216
	ds_read_b128 v[230:233], v238 offset:41984
	s_waitcnt lgkmcnt(2)
	v_lshlrev_b32_e32 v162, 16, v146
	v_and_b32_e32 v163, 0xffff0000, v146
	v_lshlrev_b32_e32 v164, 16, v147
	v_and_b32_e32 v165, 0xffff0000, v147
	v_pk_mul_f32 v[162:163], v[162:163], v[252:253] op_sel_hi:[1,0]
	v_pk_mul_f32 v[164:165], v[164:165], v[252:253] op_sel_hi:[1,0]
	v_pk_mul_f32 v[162:163], v[162:163], v[214:215]
	v_pk_mul_f32 v[164:165], v[164:165], v[216:217]
	v_pk_fma_f32 v[98:99], v[218:219], v[162:163], v[98:99]
	v_pk_fma_f32 v[100:101], v[220:221], v[164:165], v[100:101]
	v_pk_fma_f32 v[170:171], v[98:99], v[98:99], v[170:171]
	v_pk_fma_f32 v[172:173], v[100:101], v[100:101], v[172:173]
	v_cvt_pk_bf16_f32 v166, v98, v99
	v_cvt_pk_bf16_f32 v167, v100, v101
	global_store_dwordx2 v245, v[166:167], s[22:23] offset:0
	ds_read_b128 v[214:217], v238 offset:10240
	ds_read_b128 v[218:221], v238 offset:43008
	s_waitcnt lgkmcnt(2)
	v_lshlrev_b32_e32 v162, 16, v148
	v_and_b32_e32 v163, 0xffff0000, v148
	v_lshlrev_b32_e32 v164, 16, v149
	v_and_b32_e32 v165, 0xffff0000, v149
	v_pk_mul_f32 v[162:163], v[162:163], v[252:253] op_sel_hi:[1,0]
	v_pk_mul_f32 v[164:165], v[164:165], v[252:253] op_sel_hi:[1,0]
	v_pk_mul_f32 v[162:163], v[162:163], v[226:227]
	v_pk_mul_f32 v[164:165], v[164:165], v[228:229]
	v_pk_fma_f32 v[102:103], v[230:231], v[162:163], v[102:103]
	v_pk_fma_f32 v[104:105], v[232:233], v[164:165], v[104:105]
	v_pk_fma_f32 v[170:171], v[102:103], v[102:103], v[170:171]
	v_pk_fma_f32 v[172:173], v[104:105], v[104:105], v[172:173]
	v_cvt_pk_bf16_f32 v168, v102, v103
	v_cvt_pk_bf16_f32 v169, v104, v105
	global_store_dwordx2 v245, v[168:169], s[22:23] offset:512
	ds_read_b128 v[226:229], v238 offset:11264
	ds_read_b128 v[230:233], v238 offset:44032
	s_waitcnt lgkmcnt(2)
	v_lshlrev_b32_e32 v162, 16, v150
	v_and_b32_e32 v163, 0xffff0000, v150
	v_lshlrev_b32_e32 v164, 16, v151
	v_and_b32_e32 v165, 0xffff0000, v151
	v_pk_mul_f32 v[162:163], v[162:163], v[252:253] op_sel_hi:[1,0]
	v_pk_mul_f32 v[164:165], v[164:165], v[252:253] op_sel_hi:[1,0]
	v_pk_mul_f32 v[162:163], v[162:163], v[214:215]
	v_pk_mul_f32 v[164:165], v[164:165], v[216:217]
	v_pk_fma_f32 v[106:107], v[218:219], v[162:163], v[106:107]
	v_pk_fma_f32 v[108:109], v[220:221], v[164:165], v[108:109]
	v_pk_fma_f32 v[170:171], v[106:107], v[106:107], v[170:171]
	v_pk_fma_f32 v[172:173], v[108:109], v[108:109], v[172:173]
	v_cvt_pk_bf16_f32 v166, v106, v107
	v_cvt_pk_bf16_f32 v167, v108, v109
	global_store_dwordx2 v245, v[166:167], s[22:23] offset:1024
	ds_read_b128 v[214:217], v238 offset:12288
	ds_read_b128 v[218:221], v238 offset:45056
	s_waitcnt lgkmcnt(2)
	v_lshlrev_b32_e32 v162, 16, v152
	v_and_b32_e32 v163, 0xffff0000, v152
	v_lshlrev_b32_e32 v164, 16, v153
	v_and_b32_e32 v165, 0xffff0000, v153
	v_pk_mul_f32 v[162:163], v[162:163], v[252:253] op_sel_hi:[1,0]
	v_pk_mul_f32 v[164:165], v[164:165], v[252:253] op_sel_hi:[1,0]
	v_pk_mul_f32 v[162:163], v[162:163], v[226:227]
	v_pk_mul_f32 v[164:165], v[164:165], v[228:229]
	v_pk_fma_f32 v[110:111], v[230:231], v[162:163], v[110:111]
	v_pk_fma_f32 v[112:113], v[232:233], v[164:165], v[112:113]
	v_pk_fma_f32 v[170:171], v[110:111], v[110:111], v[170:171]
	v_pk_fma_f32 v[172:173], v[112:113], v[112:113], v[172:173]
	v_cvt_pk_bf16_f32 v168, v110, v111
	v_cvt_pk_bf16_f32 v169, v112, v113
	global_store_dwordx2 v245, v[168:169], s[22:23] offset:1536
	ds_read_b128 v[226:229], v238 offset:13312
	ds_read_b128 v[230:233], v238 offset:46080
	s_waitcnt lgkmcnt(2)
	v_lshlrev_b32_e32 v162, 16, v154
	v_and_b32_e32 v163, 0xffff0000, v154
	v_lshlrev_b32_e32 v164, 16, v155
	v_and_b32_e32 v165, 0xffff0000, v155
	v_pk_mul_f32 v[162:163], v[162:163], v[252:253] op_sel_hi:[1,0]
	v_pk_mul_f32 v[164:165], v[164:165], v[252:253] op_sel_hi:[1,0]
	v_pk_mul_f32 v[162:163], v[162:163], v[214:215]
	v_pk_mul_f32 v[164:165], v[164:165], v[216:217]
	v_pk_fma_f32 v[114:115], v[218:219], v[162:163], v[114:115]
	v_pk_fma_f32 v[116:117], v[220:221], v[164:165], v[116:117]
	v_pk_fma_f32 v[170:171], v[114:115], v[114:115], v[170:171]
	v_pk_fma_f32 v[172:173], v[116:117], v[116:117], v[172:173]
	v_cvt_pk_bf16_f32 v166, v114, v115
	v_cvt_pk_bf16_f32 v167, v116, v117
	global_store_dwordx2 v245, v[166:167], s[22:23] offset:2048
	ds_read_b128 v[214:217], v238 offset:14336
	ds_read_b128 v[218:221], v238 offset:47104
	s_waitcnt lgkmcnt(2)
	v_lshlrev_b32_e32 v162, 16, v156
	v_and_b32_e32 v163, 0xffff0000, v156
	v_lshlrev_b32_e32 v164, 16, v157
	v_and_b32_e32 v165, 0xffff0000, v157
	v_pk_mul_f32 v[162:163], v[162:163], v[252:253] op_sel_hi:[1,0]
	v_pk_mul_f32 v[164:165], v[164:165], v[252:253] op_sel_hi:[1,0]
	v_pk_mul_f32 v[162:163], v[162:163], v[226:227]
	v_pk_mul_f32 v[164:165], v[164:165], v[228:229]
	v_pk_fma_f32 v[118:119], v[230:231], v[162:163], v[118:119]
	v_pk_fma_f32 v[120:121], v[232:233], v[164:165], v[120:121]
	v_pk_fma_f32 v[170:171], v[118:119], v[118:119], v[170:171]
	v_pk_fma_f32 v[172:173], v[120:121], v[120:121], v[172:173]
	v_cvt_pk_bf16_f32 v168, v118, v119
	v_cvt_pk_bf16_f32 v169, v120, v121
	global_store_dwordx2 v245, v[168:169], s[22:23] offset:2560
	ds_read_b128 v[226:229], v238 offset:15360
	ds_read_b128 v[230:233], v238 offset:48128
	s_waitcnt lgkmcnt(2)
	v_lshlrev_b32_e32 v162, 16, v158
	v_and_b32_e32 v163, 0xffff0000, v158
	v_lshlrev_b32_e32 v164, 16, v159
	v_and_b32_e32 v165, 0xffff0000, v159
	v_pk_mul_f32 v[162:163], v[162:163], v[252:253] op_sel_hi:[1,0]
	v_pk_mul_f32 v[164:165], v[164:165], v[252:253] op_sel_hi:[1,0]
	v_pk_mul_f32 v[162:163], v[162:163], v[214:215]
	v_pk_mul_f32 v[164:165], v[164:165], v[216:217]
	v_pk_fma_f32 v[122:123], v[218:219], v[162:163], v[122:123]
	v_pk_fma_f32 v[124:125], v[220:221], v[164:165], v[124:125]
	v_pk_fma_f32 v[170:171], v[122:123], v[122:123], v[170:171]
	v_pk_fma_f32 v[172:173], v[124:125], v[124:125], v[172:173]
	v_cvt_pk_bf16_f32 v166, v122, v123
	v_cvt_pk_bf16_f32 v167, v124, v125
	global_store_dwordx2 v245, v[166:167], s[22:23] offset:3072
	s_waitcnt lgkmcnt(0)
	v_lshlrev_b32_e32 v162, 16, v160
	v_and_b32_e32 v163, 0xffff0000, v160
	v_lshlrev_b32_e32 v164, 16, v161
	v_and_b32_e32 v165, 0xffff0000, v161
	v_pk_mul_f32 v[162:163], v[162:163], v[252:253] op_sel_hi:[1,0]
	v_pk_mul_f32 v[164:165], v[164:165], v[252:253] op_sel_hi:[1,0]
	v_pk_mul_f32 v[162:163], v[162:163], v[226:227]
	v_pk_mul_f32 v[164:165], v[164:165], v[228:229]
	v_pk_fma_f32 v[126:127], v[230:231], v[162:163], v[126:127]
	v_pk_fma_f32 v[128:129], v[232:233], v[164:165], v[128:129]
	v_pk_fma_f32 v[170:171], v[126:127], v[126:127], v[170:171]
	v_pk_fma_f32 v[172:173], v[128:129], v[128:129], v[172:173]
	v_cvt_pk_bf16_f32 v168, v126, v127
	v_cvt_pk_bf16_f32 v169, v128, v129
	global_store_dwordx2 v245, v[168:169], s[22:23] offset:3584
	ds_read_b128 v[214:217], v238 offset:16384
	ds_read_b128 v[218:221], v238 offset:49152
	ds_read_b128 v[222:225], v239 offset:0
	v_pk_add_f32 v[170:171], v[170:171], v[172:173]
	s_nop 0
	v_add_f32_e32 v252, v170, v171
	s_waitcnt lgkmcnt(0)
	ds_bpermute_b32 v254, v246, v252
	s_waitcnt lgkmcnt(0)
	v_add_f32_e32 v252, v252, v254
	ds_bpermute_b32 v254, v247, v252
	s_waitcnt lgkmcnt(0)
	v_add_f32_e32 v252, v252, v254
	ds_bpermute_b32 v254, v248, v252
	s_waitcnt lgkmcnt(0)
	v_add_f32_e32 v252, v252, v254
	ds_bpermute_b32 v254, v249, v252
	s_waitcnt lgkmcnt(0)
	v_add_f32_e32 v252, v252, v254
	ds_bpermute_b32 v254, v250, v252
	s_waitcnt lgkmcnt(0)
	v_add_f32_e32 v252, v252, v254
	ds_bpermute_b32 v254, v251, v252
	s_waitcnt lgkmcnt(0)
	v_add_f32_e32 v252, v252, v254
	v_mov_b32_e32 v254, 0x358637bd
	v_fmac_f32_e32 v254, 0x39800000, v252
	v_mul_f32_e32 v252, 0x4b800000, v254
	v_cmp_gt_f32_e32 vcc, s32, v254
	s_nop 1
	v_cndmask_b32_e32 v254, v254, v252, vcc
	v_rsq_f32_e32 v254, v254
	s_nop 0
	v_mul_f32_e32 v252, 0x45800000, v254
	v_cndmask_b32_e32 v252, v254, v252, vcc
	s_add_u32 s16, s16, 0x1000000
	s_addc_u32 s17, s17, 0
	global_load_dwordx2 v[130:131], v244, s[16:17] offset:0
	global_load_dwordx2 v[132:133], v244, s[16:17] offset:512
	global_load_dwordx2 v[134:135], v244, s[16:17] offset:1024
	global_load_dwordx2 v[136:137], v244, s[16:17] offset:1536
	global_load_dwordx2 v[138:139], v244, s[16:17] offset:2048
	global_load_dwordx2 v[140:141], v244, s[16:17] offset:2560
	global_load_dwordx2 v[142:143], v244, s[16:17] offset:3072
	global_load_dwordx2 v[144:145], v244, s[16:17] offset:3584
	global_load_dwordx2 v[146:147], v245, s[16:17] offset:0
	global_load_dwordx2 v[148:149], v245, s[16:17] offset:512
	global_load_dwordx2 v[150:151], v245, s[16:17] offset:1024
	global_load_dwordx2 v[152:153], v245, s[16:17] offset:1536
	global_load_dwordx2 v[154:155], v245, s[16:17] offset:2048
	global_load_dwordx2 v[156:157], v245, s[16:17] offset:2560
	global_load_dwordx2 v[158:159], v245, s[16:17] offset:3072
	global_load_dwordx2 v[160:161], v245, s[16:17] offset:3584
	ds_read_b128 v[226:229], v238 offset:17408
	ds_read_b128 v[230:233], v238 offset:50176
	ds_read_b128 v[234:237], v239 offset:1024
	s_waitcnt lgkmcnt(3)
	v_pk_mul_f32 v[66:67], v[66:67], v[252:253] op_sel_hi:[1,0]
	v_pk_mul_f32 v[68:69], v[68:69], v[252:253] op_sel_hi:[1,0]
	v_pk_mul_f32 v[66:67], v[66:67], v[214:215]
	v_pk_mul_f32 v[68:69], v[68:69], v[216:217]
	v_pk_add_f32 v[222:223], v[222:223], 1.0 op_sel_hi:[1,0]
	v_pk_add_f32 v[224:225], v[224:225], 1.0 op_sel_hi:[1,0]
	v_pk_fma_f32 v[66:67], v[66:67], v[222:223], v[218:219]
	v_pk_fma_f32 v[68:69], v[68:69], v[224:225], v[220:221]
	s_nop 0
	v_cvt_pk_bf16_f32 v66, v66, v67
	v_cvt_pk_bf16_f32 v67, v68, v69
	global_store_dwordx2 v244, v[66:67], s[38:39] offset:0
	ds_read_b128 v[214:217], v238 offset:18432
	ds_read_b128 v[218:221], v238 offset:51200
	ds_read_b128 v[222:225], v239 offset:2048
	s_waitcnt lgkmcnt(3)
	v_pk_mul_f32 v[70:71], v[70:71], v[252:253] op_sel_hi:[1,0]
	v_pk_mul_f32 v[72:73], v[72:73], v[252:253] op_sel_hi:[1,0]
	v_pk_mul_f32 v[70:71], v[70:71], v[226:227]
	v_pk_mul_f32 v[72:73], v[72:73], v[228:229]
	v_pk_add_f32 v[234:235], v[234:235], 1.0 op_sel_hi:[1,0]
	v_pk_add_f32 v[236:237], v[236:237], 1.0 op_sel_hi:[1,0]
	v_pk_fma_f32 v[70:71], v[70:71], v[234:235], v[230:231]
	v_pk_fma_f32 v[72:73], v[72:73], v[236:237], v[232:233]
	s_nop 0
	v_cvt_pk_bf16_f32 v70, v70, v71
	v_cvt_pk_bf16_f32 v71, v72, v73
	global_store_dwordx2 v244, v[70:71], s[38:39] offset:512
	ds_read_b128 v[226:229], v238 offset:19456
	ds_read_b128 v[230:233], v238 offset:52224
	ds_read_b128 v[234:237], v239 offset:3072
	s_waitcnt lgkmcnt(3)
	v_pk_mul_f32 v[74:75], v[74:75], v[252:253] op_sel_hi:[1,0]
	v_pk_mul_f32 v[76:77], v[76:77], v[252:253] op_sel_hi:[1,0]
	v_pk_mul_f32 v[74:75], v[74:75], v[214:215]
	v_pk_mul_f32 v[76:77], v[76:77], v[216:217]
	v_pk_add_f32 v[222:223], v[222:223], 1.0 op_sel_hi:[1,0]
	v_pk_add_f32 v[224:225], v[224:225], 1.0 op_sel_hi:[1,0]
	v_pk_fma_f32 v[74:75], v[74:75], v[222:223], v[218:219]
	v_pk_fma_f32 v[76:77], v[76:77], v[224:225], v[220:221]
	s_nop 0
	v_cvt_pk_bf16_f32 v74, v74, v75
	v_cvt_pk_bf16_f32 v75, v76, v77
	global_store_dwordx2 v244, v[74:75], s[38:39] offset:1024
	ds_read_b128 v[214:217], v238 offset:20480
	ds_read_b128 v[218:221], v238 offset:53248
	ds_read_b128 v[222:225], v239 offset:4096
	s_waitcnt lgkmcnt(3)
	v_pk_mul_f32 v[78:79], v[78:79], v[252:253] op_sel_hi:[1,0]
	v_pk_mul_f32 v[80:81], v[80:81], v[252:253] op_sel_hi:[1,0]
	v_pk_mul_f32 v[78:79], v[78:79], v[226:227]
	v_pk_mul_f32 v[80:81], v[80:81], v[228:229]
	v_pk_add_f32 v[234:235], v[234:235], 1.0 op_sel_hi:[1,0]
	v_pk_add_f32 v[236:237], v[236:237], 1.0 op_sel_hi:[1,0]
	v_pk_fma_f32 v[78:79], v[78:79], v[234:235], v[230:231]
	v_pk_fma_f32 v[80:81], v[80:81], v[236:237], v[232:233]
	s_nop 0
	v_cvt_pk_bf16_f32 v78, v78, v79
	v_cvt_pk_bf16_f32 v79, v80, v81
	global_store_dwordx2 v244, v[78:79], s[38:39] offset:1536
	ds_read_b128 v[226:229], v238 offset:21504
	ds_read_b128 v[230:233], v238 offset:54272
	ds_read_b128 v[234:237], v239 offset:5120
	s_waitcnt lgkmcnt(3)
	v_pk_mul_f32 v[82:83], v[82:83], v[252:253] op_sel_hi:[1,0]
	v_pk_mul_f32 v[84:85], v[84:85], v[252:253] op_sel_hi:[1,0]
	v_pk_mul_f32 v[82:83], v[82:83], v[214:215]
	v_pk_mul_f32 v[84:85], v[84:85], v[216:217]
	v_pk_add_f32 v[222:223], v[222:223], 1.0 op_sel_hi:[1,0]
	v_pk_add_f32 v[224:225], v[224:225], 1.0 op_sel_hi:[1,0]
	v_pk_fma_f32 v[82:83], v[82:83], v[222:223], v[218:219]
	v_pk_fma_f32 v[84:85], v[84:85], v[224:225], v[220:221]
	s_nop 0
	v_cvt_pk_bf16_f32 v82, v82, v83
	v_cvt_pk_bf16_f32 v83, v84, v85
	global_store_dwordx2 v244, v[82:83], s[38:39] offset:2048
	ds_read_b128 v[214:217], v238 offset:22528
	ds_read_b128 v[218:221], v238 offset:55296
	ds_read_b128 v[222:225], v239 offset:6144
	s_waitcnt lgkmcnt(3)
	v_pk_mul_f32 v[86:87], v[86:87], v[252:253] op_sel_hi:[1,0]
	v_pk_mul_f32 v[88:89], v[88:89], v[252:253] op_sel_hi:[1,0]
	v_pk_mul_f32 v[86:87], v[86:87], v[226:227]
	v_pk_mul_f32 v[88:89], v[88:89], v[228:229]
	v_pk_add_f32 v[234:235], v[234:235], 1.0 op_sel_hi:[1,0]
	v_pk_add_f32 v[236:237], v[236:237], 1.0 op_sel_hi:[1,0]
	v_pk_fma_f32 v[86:87], v[86:87], v[234:235], v[230:231]
	v_pk_fma_f32 v[88:89], v[88:89], v[236:237], v[232:233]
	s_nop 0
	v_cvt_pk_bf16_f32 v86, v86, v87
	v_cvt_pk_bf16_f32 v87, v88, v89
	global_store_dwordx2 v244, v[86:87], s[38:39] offset:2560
	ds_read_b128 v[226:229], v238 offset:23552
	ds_read_b128 v[230:233], v238 offset:56320
	ds_read_b128 v[234:237], v239 offset:7168
	s_waitcnt lgkmcnt(3)
	v_pk_mul_f32 v[90:91], v[90:91], v[252:253] op_sel_hi:[1,0]
	v_pk_mul_f32 v[92:93], v[92:93], v[252:253] op_sel_hi:[1,0]
	v_pk_mul_f32 v[90:91], v[90:91], v[214:215]
	v_pk_mul_f32 v[92:93], v[92:93], v[216:217]
	v_pk_add_f32 v[222:223], v[222:223], 1.0 op_sel_hi:[1,0]
	v_pk_add_f32 v[224:225], v[224:225], 1.0 op_sel_hi:[1,0]
	v_pk_fma_f32 v[90:91], v[90:91], v[222:223], v[218:219]
	v_pk_fma_f32 v[92:93], v[92:93], v[224:225], v[220:221]
	s_nop 0
	v_cvt_pk_bf16_f32 v90, v90, v91
	v_cvt_pk_bf16_f32 v91, v92, v93
	global_store_dwordx2 v244, v[90:91], s[38:39] offset:3072
	ds_read_b128 v[214:217], v238 offset:24576
	ds_read_b128 v[218:221], v238 offset:57344
	ds_read_b128 v[222:225], v239 offset:8192
	s_waitcnt lgkmcnt(3)
	v_pk_mul_f32 v[94:95], v[94:95], v[252:253] op_sel_hi:[1,0]
	v_pk_mul_f32 v[96:97], v[96:97], v[252:253] op_sel_hi:[1,0]
	v_pk_mul_f32 v[94:95], v[94:95], v[226:227]
	v_pk_mul_f32 v[96:97], v[96:97], v[228:229]
	v_pk_add_f32 v[234:235], v[234:235], 1.0 op_sel_hi:[1,0]
	v_pk_add_f32 v[236:237], v[236:237], 1.0 op_sel_hi:[1,0]
	v_pk_fma_f32 v[94:95], v[94:95], v[234:235], v[230:231]
	v_pk_fma_f32 v[96:97], v[96:97], v[236:237], v[232:233]
	s_nop 0
	v_cvt_pk_bf16_f32 v94, v94, v95
	v_cvt_pk_bf16_f32 v95, v96, v97
	global_store_dwordx2 v244, v[94:95], s[38:39] offset:3584
	ds_read_b128 v[226:229], v238 offset:25600
	ds_read_b128 v[230:233], v238 offset:58368
	ds_read_b128 v[234:237], v239 offset:9216
	s_waitcnt lgkmcnt(3)
	v_pk_mul_f32 v[98:99], v[98:99], v[252:253] op_sel_hi:[1,0]
	v_pk_mul_f32 v[100:101], v[100:101], v[252:253] op_sel_hi:[1,0]
	v_pk_mul_f32 v[98:99], v[98:99], v[214:215]
	v_pk_mul_f32 v[100:101], v[100:101], v[216:217]
	v_pk_add_f32 v[222:223], v[222:223], 1.0 op_sel_hi:[1,0]
	v_pk_add_f32 v[224:225], v[224:225], 1.0 op_sel_hi:[1,0]
	v_pk_fma_f32 v[98:99], v[98:99], v[222:223], v[218:219]
	v_pk_fma_f32 v[100:101], v[100:101], v[224:225], v[220:221]
	s_nop 0
	v_cvt_pk_bf16_f32 v98, v98, v99
	v_cvt_pk_bf16_f32 v99, v100, v101
	global_store_dwordx2 v245, v[98:99], s[38:39] offset:0
	ds_read_b128 v[214:217], v238 offset:26624
	ds_read_b128 v[218:221], v238 offset:59392
	ds_read_b128 v[222:225], v239 offset:10240
	s_waitcnt lgkmcnt(3)
	v_pk_mul_f32 v[102:103], v[102:103], v[252:253] op_sel_hi:[1,0]
	v_pk_mul_f32 v[104:105], v[104:105], v[252:253] op_sel_hi:[1,0]
	v_pk_mul_f32 v[102:103], v[102:103], v[226:227]
	v_pk_mul_f32 v[104:105], v[104:105], v[228:229]
	v_pk_add_f32 v[234:235], v[234:235], 1.0 op_sel_hi:[1,0]
	v_pk_add_f32 v[236:237], v[236:237], 1.0 op_sel_hi:[1,0]
	v_pk_fma_f32 v[102:103], v[102:103], v[234:235], v[230:231]
	v_pk_fma_f32 v[104:105], v[104:105], v[236:237], v[232:233]
	s_nop 0
	v_cvt_pk_bf16_f32 v102, v102, v103
	v_cvt_pk_bf16_f32 v103, v104, v105
	global_store_dwordx2 v245, v[102:103], s[38:39] offset:512
	ds_read_b128 v[226:229], v238 offset:27648
	ds_read_b128 v[230:233], v238 offset:60416
	ds_read_b128 v[234:237], v239 offset:11264
	s_waitcnt lgkmcnt(3)
	v_pk_mul_f32 v[106:107], v[106:107], v[252:253] op_sel_hi:[1,0]
	v_pk_mul_f32 v[108:109], v[108:109], v[252:253] op_sel_hi:[1,0]
	v_pk_mul_f32 v[106:107], v[106:107], v[214:215]
	v_pk_mul_f32 v[108:109], v[108:109], v[216:217]
	v_pk_add_f32 v[222:223], v[222:223], 1.0 op_sel_hi:[1,0]
	v_pk_add_f32 v[224:225], v[224:225], 1.0 op_sel_hi:[1,0]
	v_pk_fma_f32 v[106:107], v[106:107], v[222:223], v[218:219]
	v_pk_fma_f32 v[108:109], v[108:109], v[224:225], v[220:221]
	s_nop 0
	v_cvt_pk_bf16_f32 v106, v106, v107
	v_cvt_pk_bf16_f32 v107, v108, v109
	global_store_dwordx2 v245, v[106:107], s[38:39] offset:1024
	ds_read_b128 v[214:217], v238 offset:28672
	ds_read_b128 v[218:221], v238 offset:61440
	ds_read_b128 v[222:225], v239 offset:12288
	s_waitcnt lgkmcnt(3)
	v_pk_mul_f32 v[110:111], v[110:111], v[252:253] op_sel_hi:[1,0]
	v_pk_mul_f32 v[112:113], v[112:113], v[252:253] op_sel_hi:[1,0]
	v_pk_mul_f32 v[110:111], v[110:111], v[226:227]
	v_pk_mul_f32 v[112:113], v[112:113], v[228:229]
	v_pk_add_f32 v[234:235], v[234:235], 1.0 op_sel_hi:[1,0]
	v_pk_add_f32 v[236:237], v[236:237], 1.0 op_sel_hi:[1,0]
	v_pk_fma_f32 v[110:111], v[110:111], v[234:235], v[230:231]
	v_pk_fma_f32 v[112:113], v[112:113], v[236:237], v[232:233]
	s_nop 0
	v_cvt_pk_bf16_f32 v110, v110, v111
	v_cvt_pk_bf16_f32 v111, v112, v113
	global_store_dwordx2 v245, v[110:111], s[38:39] offset:1536
	ds_read_b128 v[226:229], v238 offset:29696
	ds_read_b128 v[230:233], v238 offset:62464
	ds_read_b128 v[234:237], v239 offset:13312
	s_waitcnt lgkmcnt(3)
	v_pk_mul_f32 v[114:115], v[114:115], v[252:253] op_sel_hi:[1,0]
	v_pk_mul_f32 v[116:117], v[116:117], v[252:253] op_sel_hi:[1,0]
	v_pk_mul_f32 v[114:115], v[114:115], v[214:215]
	v_pk_mul_f32 v[116:117], v[116:117], v[216:217]
	v_pk_add_f32 v[222:223], v[222:223], 1.0 op_sel_hi:[1,0]
	v_pk_add_f32 v[224:225], v[224:225], 1.0 op_sel_hi:[1,0]
	v_pk_fma_f32 v[114:115], v[114:115], v[222:223], v[218:219]
	v_pk_fma_f32 v[116:117], v[116:117], v[224:225], v[220:221]
	s_nop 0
	v_cvt_pk_bf16_f32 v114, v114, v115
	v_cvt_pk_bf16_f32 v115, v116, v117
	global_store_dwordx2 v245, v[114:115], s[38:39] offset:2048
	ds_read_b128 v[214:217], v238 offset:30720
	ds_read_b128 v[218:221], v238 offset:63488
	ds_read_b128 v[222:225], v239 offset:14336
	s_waitcnt lgkmcnt(3)
	v_pk_mul_f32 v[118:119], v[118:119], v[252:253] op_sel_hi:[1,0]
	v_pk_mul_f32 v[120:121], v[120:121], v[252:253] op_sel_hi:[1,0]
	v_pk_mul_f32 v[118:119], v[118:119], v[226:227]
	v_pk_mul_f32 v[120:121], v[120:121], v[228:229]
	v_pk_add_f32 v[234:235], v[234:235], 1.0 op_sel_hi:[1,0]
	v_pk_add_f32 v[236:237], v[236:237], 1.0 op_sel_hi:[1,0]
	v_pk_fma_f32 v[118:119], v[118:119], v[234:235], v[230:231]
	v_pk_fma_f32 v[120:121], v[120:121], v[236:237], v[232:233]
	s_nop 0
	v_cvt_pk_bf16_f32 v118, v118, v119
	v_cvt_pk_bf16_f32 v119, v120, v121
	global_store_dwordx2 v245, v[118:119], s[38:39] offset:2560
	ds_read_b128 v[226:229], v238 offset:31744
	ds_read_b128 v[230:233], v238 offset:64512
	ds_read_b128 v[234:237], v239 offset:15360
	s_waitcnt lgkmcnt(3)
	v_pk_mul_f32 v[122:123], v[122:123], v[252:253] op_sel_hi:[1,0]
	v_pk_mul_f32 v[124:125], v[124:125], v[252:253] op_sel_hi:[1,0]
	v_pk_mul_f32 v[122:123], v[122:123], v[214:215]
	v_pk_mul_f32 v[124:125], v[124:125], v[216:217]
	v_pk_add_f32 v[222:223], v[222:223], 1.0 op_sel_hi:[1,0]
	v_pk_add_f32 v[224:225], v[224:225], 1.0 op_sel_hi:[1,0]
	v_pk_fma_f32 v[122:123], v[122:123], v[222:223], v[218:219]
	v_pk_fma_f32 v[124:125], v[124:125], v[224:225], v[220:221]
	s_nop 0
	v_cvt_pk_bf16_f32 v122, v122, v123
	v_cvt_pk_bf16_f32 v123, v124, v125
	global_store_dwordx2 v245, v[122:123], s[38:39] offset:3072
	s_waitcnt lgkmcnt(0)
	v_pk_mul_f32 v[126:127], v[126:127], v[252:253] op_sel_hi:[1,0]
	v_pk_mul_f32 v[128:129], v[128:129], v[252:253] op_sel_hi:[1,0]
	v_pk_mul_f32 v[126:127], v[126:127], v[226:227]
	v_pk_mul_f32 v[128:129], v[128:129], v[228:229]
	v_pk_add_f32 v[234:235], v[234:235], 1.0 op_sel_hi:[1,0]
	v_pk_add_f32 v[236:237], v[236:237], 1.0 op_sel_hi:[1,0]
	v_pk_fma_f32 v[126:127], v[126:127], v[234:235], v[230:231]
	v_pk_fma_f32 v[128:129], v[128:129], v[236:237], v[232:233]
	s_nop 0
	v_cvt_pk_bf16_f32 v126, v126, v127
	v_cvt_pk_bf16_f32 v127, v128, v129
	global_store_dwordx2 v245, v[126:127], s[38:39] offset:3584
	s_add_u32 s22, s22, 0x1000000
	s_addc_u32 s23, s23, 0
	s_add_u32 s38, s38, 0x1000000
	s_addc_u32 s39, s39, 0
	s_waitcnt vmcnt(16)
	s_add_u32 s14, s14, 0x2000000
	s_addc_u32 s15, s15, 0
	global_load_dwordx4 v[66:69], v238, s[14:15] offset:0
	global_load_dwordx4 v[70:73], v238, s[14:15] offset:1024
	global_load_dwordx4 v[74:77], v238, s[14:15] offset:2048
	global_load_dwordx4 v[78:81], v238, s[14:15] offset:3072
	global_load_dwordx4 v[82:85], v241, s[14:15] offset:0
	global_load_dwordx4 v[86:89], v241, s[14:15] offset:1024
	global_load_dwordx4 v[90:93], v241, s[14:15] offset:2048
	global_load_dwordx4 v[94:97], v241, s[14:15] offset:3072
	global_load_dwordx4 v[98:101], v242, s[14:15] offset:0
	global_load_dwordx4 v[102:105], v242, s[14:15] offset:1024
	global_load_dwordx4 v[106:109], v242, s[14:15] offset:2048
	global_load_dwordx4 v[110:113], v242, s[14:15] offset:3072
	global_load_dwordx4 v[114:117], v243, s[14:15] offset:0
	global_load_dwordx4 v[118:121], v243, s[14:15] offset:1024
	global_load_dwordx4 v[122:125], v243, s[14:15] offset:2048
	global_load_dwordx4 v[126:129], v243, s[14:15] offset:3072
	ds_read_b128 v[214:217], v238 offset:0
	ds_read_b128 v[218:221], v238 offset:32768
	v_lshlrev_b32_e32 v162, 16, v130
	v_and_b32_e32 v163, 0xffff0000, v130
	v_lshlrev_b32_e32 v164, 16, v131
	v_and_b32_e32 v165, 0xffff0000, v131
	v_pk_mul_f32 v[170:171], v[162:163], v[162:163]
	v_pk_mul_f32 v[172:173], v[164:165], v[164:165]
	v_lshlrev_b32_e32 v166, 16, v132
	v_and_b32_e32 v167, 0xffff0000, v132
	v_lshlrev_b32_e32 v168, 16, v133
	v_and_b32_e32 v169, 0xffff0000, v133
	v_pk_fma_f32 v[170:171], v[166:167], v[166:167], v[170:171]
	v_pk_fma_f32 v[172:173], v[168:169], v[168:169], v[172:173]
	v_lshlrev_b32_e32 v162, 16, v134
	v_and_b32_e32 v163, 0xffff0000, v134
	v_lshlrev_b32_e32 v164, 16, v135
	v_and_b32_e32 v165, 0xffff0000, v135
	v_pk_fma_f32 v[170:171], v[162:163], v[162:163], v[170:171]
	v_pk_fma_f32 v[172:173], v[164:165], v[164:165], v[172:173]
	v_lshlrev_b32_e32 v166, 16, v136
	v_and_b32_e32 v167, 0xffff0000, v136
	v_lshlrev_b32_e32 v168, 16, v137
	v_and_b32_e32 v169, 0xffff0000, v137
	v_pk_fma_f32 v[170:171], v[166:167], v[166:167], v[170:171]
	v_pk_fma_f32 v[172:173], v[168:169], v[168:169], v[172:173]
	v_lshlrev_b32_e32 v162, 16, v138
	v_and_b32_e32 v163, 0xffff0000, v138
	v_lshlrev_b32_e32 v164, 16, v139
	v_and_b32_e32 v165, 0xffff0000, v139
	v_pk_fma_f32 v[170:171], v[162:163], v[162:163], v[170:171]
	v_pk_fma_f32 v[172:173], v[164:165], v[164:165], v[172:173]
	v_lshlrev_b32_e32 v166, 16, v140
	v_and_b32_e32 v167, 0xffff0000, v140
	v_lshlrev_b32_e32 v168, 16, v141
	v_and_b32_e32 v169, 0xffff0000, v141
	v_pk_fma_f32 v[170:171], v[166:167], v[166:167], v[170:171]
	v_pk_fma_f32 v[172:173], v[168:169], v[168:169], v[172:173]
	v_lshlrev_b32_e32 v162, 16, v142
	v_and_b32_e32 v163, 0xffff0000, v142
	v_lshlrev_b32_e32 v164, 16, v143
	v_and_b32_e32 v165, 0xffff0000, v143
	v_pk_fma_f32 v[170:171], v[162:163], v[162:163], v[170:171]
	v_pk_fma_f32 v[172:173], v[164:165], v[164:165], v[172:173]
	v_lshlrev_b32_e32 v166, 16, v144
	v_and_b32_e32 v167, 0xffff0000, v144
	v_lshlrev_b32_e32 v168, 16, v145
	v_and_b32_e32 v169, 0xffff0000, v145
	v_pk_fma_f32 v[170:171], v[166:167], v[166:167], v[170:171]
	v_pk_fma_f32 v[172:173], v[168:169], v[168:169], v[172:173]
	v_lshlrev_b32_e32 v162, 16, v146
	v_and_b32_e32 v163, 0xffff0000, v146
	v_lshlrev_b32_e32 v164, 16, v147
	v_and_b32_e32 v165, 0xffff0000, v147
	v_pk_fma_f32 v[170:171], v[162:163], v[162:163], v[170:171]
	v_pk_fma_f32 v[172:173], v[164:165], v[164:165], v[172:173]
	v_lshlrev_b32_e32 v166, 16, v148
	v_and_b32_e32 v167, 0xffff0000, v148
	v_lshlrev_b32_e32 v168, 16, v149
	v_and_b32_e32 v169, 0xffff0000, v149
	v_pk_fma_f32 v[170:171], v[166:167], v[166:167], v[170:171]
	v_pk_fma_f32 v[172:173], v[168:169], v[168:169], v[172:173]
	v_lshlrev_b32_e32 v162, 16, v150
	v_and_b32_e32 v163, 0xffff0000, v150
	v_lshlrev_b32_e32 v164, 16, v151
	v_and_b32_e32 v165, 0xffff0000, v151
	v_pk_fma_f32 v[170:171], v[162:163], v[162:163], v[170:171]
	v_pk_fma_f32 v[172:173], v[164:165], v[164:165], v[172:173]
	v_lshlrev_b32_e32 v166, 16, v152
	v_and_b32_e32 v167, 0xffff0000, v152
	v_lshlrev_b32_e32 v168, 16, v153
	v_and_b32_e32 v169, 0xffff0000, v153
	v_pk_fma_f32 v[170:171], v[166:167], v[166:167], v[170:171]
	v_pk_fma_f32 v[172:173], v[168:169], v[168:169], v[172:173]
	v_lshlrev_b32_e32 v162, 16, v154
	v_and_b32_e32 v163, 0xffff0000, v154
	v_lshlrev_b32_e32 v164, 16, v155
	v_and_b32_e32 v165, 0xffff0000, v155
	v_pk_fma_f32 v[170:171], v[162:163], v[162:163], v[170:171]
	v_pk_fma_f32 v[172:173], v[164:165], v[164:165], v[172:173]
	v_lshlrev_b32_e32 v166, 16, v156
	v_and_b32_e32 v167, 0xffff0000, v156
	v_lshlrev_b32_e32 v168, 16, v157
	v_and_b32_e32 v169, 0xffff0000, v157
	v_pk_fma_f32 v[170:171], v[166:167], v[166:167], v[170:171]
	v_pk_fma_f32 v[172:173], v[168:169], v[168:169], v[172:173]
	v_lshlrev_b32_e32 v162, 16, v158
	v_and_b32_e32 v163, 0xffff0000, v158
	v_lshlrev_b32_e32 v164, 16, v159
	v_and_b32_e32 v165, 0xffff0000, v159
	v_pk_fma_f32 v[170:171], v[162:163], v[162:163], v[170:171]
	v_pk_fma_f32 v[172:173], v[164:165], v[164:165], v[172:173]
	v_lshlrev_b32_e32 v166, 16, v160
	v_and_b32_e32 v167, 0xffff0000, v160
	v_lshlrev_b32_e32 v168, 16, v161
	v_and_b32_e32 v169, 0xffff0000, v161
	v_pk_fma_f32 v[170:171], v[166:167], v[166:167], v[170:171]
	v_pk_fma_f32 v[172:173], v[168:169], v[168:169], v[172:173]
	v_pk_add_f32 v[170:171], v[170:171], v[172:173]
	s_nop 0
	v_add_f32_e32 v252, v170, v171
	s_waitcnt lgkmcnt(0)
	ds_bpermute_b32 v254, v246, v252
	s_waitcnt lgkmcnt(0)
	v_add_f32_e32 v252, v252, v254
	ds_bpermute_b32 v254, v247, v252
	s_waitcnt lgkmcnt(0)
	v_add_f32_e32 v252, v252, v254
	ds_bpermute_b32 v254, v248, v252
	s_waitcnt lgkmcnt(0)
	v_add_f32_e32 v252, v252, v254
	ds_bpermute_b32 v254, v249, v252
	s_waitcnt lgkmcnt(0)
	v_add_f32_e32 v252, v252, v254
	ds_bpermute_b32 v254, v250, v252
	s_waitcnt lgkmcnt(0)
	v_add_f32_e32 v252, v252, v254
	ds_bpermute_b32 v254, v251, v252
	s_waitcnt lgkmcnt(0)
	v_add_f32_e32 v252, v252, v254
	v_mov_b32_e32 v254, 0x358637bd
	v_fmac_f32_e32 v254, 0x39800000, v252
	v_mul_f32_e32 v252, 0x4b800000, v254
	v_cmp_gt_f32_e32 vcc, s32, v254
	s_nop 1
	v_cndmask_b32_e32 v254, v254, v252, vcc
	v_rsq_f32_e32 v254, v254
	s_nop 0
	v_mul_f32_e32 v252, 0x45800000, v254
	v_cndmask_b32_e32 v252, v254, v252, vcc
	ds_read_b128 v[226:229], v238 offset:1024
	ds_read_b128 v[230:233], v238 offset:33792
	s_waitcnt lgkmcnt(2)
	v_lshlrev_b32_e32 v162, 16, v130
	v_and_b32_e32 v163, 0xffff0000, v130
	v_lshlrev_b32_e32 v164, 16, v131
	v_and_b32_e32 v165, 0xffff0000, v131
	v_pk_mul_f32 v[162:163], v[162:163], v[252:253] op_sel_hi:[1,0]
	v_pk_mul_f32 v[164:165], v[164:165], v[252:253] op_sel_hi:[1,0]
	v_pk_mul_f32 v[162:163], v[162:163], v[214:215]
	v_pk_mul_f32 v[164:165], v[164:165], v[216:217]
	v_pk_fma_f32 v[2:3], v[218:219], v[162:163], v[2:3]
	v_pk_fma_f32 v[4:5], v[220:221], v[164:165], v[4:5]
	v_pk_mul_f32 v[170:171], v[2:3], v[2:3]
	v_pk_mul_f32 v[172:173], v[4:5], v[4:5]
	v_cvt_pk_bf16_f32 v166, v2, v3
	v_cvt_pk_bf16_f32 v167, v4, v5
	global_store_dwordx2 v244, v[166:167], s[22:23] offset:0
	ds_read_b128 v[214:217], v238 offset:2048
	ds_read_b128 v[218:221], v238 offset:34816
	s_waitcnt lgkmcnt(2)
	v_lshlrev_b32_e32 v162, 16, v132
	v_and_b32_e32 v163, 0xffff0000, v132
	v_lshlrev_b32_e32 v164, 16, v133
	v_and_b32_e32 v165, 0xffff0000, v133
	v_pk_mul_f32 v[162:163], v[162:163], v[252:253] op_sel_hi:[1,0]
	v_pk_mul_f32 v[164:165], v[164:165], v[252:253] op_sel_hi:[1,0]
	v_pk_mul_f32 v[162:163], v[162:163], v[226:227]
	v_pk_mul_f32 v[164:165], v[164:165], v[228:229]
	v_pk_fma_f32 v[6:7], v[230:231], v[162:163], v[6:7]
	v_pk_fma_f32 v[8:9], v[232:233], v[164:165], v[8:9]
	v_pk_fma_f32 v[170:171], v[6:7], v[6:7], v[170:171]
	v_pk_fma_f32 v[172:173], v[8:9], v[8:9], v[172:173]
	v_cvt_pk_bf16_f32 v168, v6, v7
	v_cvt_pk_bf16_f32 v169, v8, v9
	global_store_dwordx2 v244, v[168:169], s[22:23] offset:512
	ds_read_b128 v[226:229], v238 offset:3072
	ds_read_b128 v[230:233], v238 offset:35840
	s_waitcnt lgkmcnt(2)
	v_lshlrev_b32_e32 v162, 16, v134
	v_and_b32_e32 v163, 0xffff0000, v134
	v_lshlrev_b32_e32 v164, 16, v135
	v_and_b32_e32 v165, 0xffff0000, v135
	v_pk_mul_f32 v[162:163], v[162:163], v[252:253] op_sel_hi:[1,0]
	v_pk_mul_f32 v[164:165], v[164:165], v[252:253] op_sel_hi:[1,0]
	v_pk_mul_f32 v[162:163], v[162:163], v[214:215]
	v_pk_mul_f32 v[164:165], v[164:165], v[216:217]
	v_pk_fma_f32 v[10:11], v[218:219], v[162:163], v[10:11]
	v_pk_fma_f32 v[12:13], v[220:221], v[164:165], v[12:13]
	v_pk_fma_f32 v[170:171], v[10:11], v[10:11], v[170:171]
	v_pk_fma_f32 v[172:173], v[12:13], v[12:13], v[172:173]
	v_cvt_pk_bf16_f32 v166, v10, v11
	v_cvt_pk_bf16_f32 v167, v12, v13
	global_store_dwordx2 v244, v[166:167], s[22:23] offset:1024
	ds_read_b128 v[214:217], v238 offset:4096
	ds_read_b128 v[218:221], v238 offset:36864
	s_waitcnt lgkmcnt(2)
	v_lshlrev_b32_e32 v162, 16, v136
	v_and_b32_e32 v163, 0xffff0000, v136
	v_lshlrev_b32_e32 v164, 16, v137
	v_and_b32_e32 v165, 0xffff0000, v137
	v_pk_mul_f32 v[162:163], v[162:163], v[252:253] op_sel_hi:[1,0]
	v_pk_mul_f32 v[164:165], v[164:165], v[252:253] op_sel_hi:[1,0]
	v_pk_mul_f32 v[162:163], v[162:163], v[226:227]
	v_pk_mul_f32 v[164:165], v[164:165], v[228:229]
	v_pk_fma_f32 v[14:15], v[230:231], v[162:163], v[14:15]
	v_pk_fma_f32 v[16:17], v[232:233], v[164:165], v[16:17]
	v_pk_fma_f32 v[170:171], v[14:15], v[14:15], v[170:171]
	v_pk_fma_f32 v[172:173], v[16:17], v[16:17], v[172:173]
	v_cvt_pk_bf16_f32 v168, v14, v15
	v_cvt_pk_bf16_f32 v169, v16, v17
	global_store_dwordx2 v244, v[168:169], s[22:23] offset:1536
	ds_read_b128 v[226:229], v238 offset:5120
	ds_read_b128 v[230:233], v238 offset:37888
	s_waitcnt lgkmcnt(2)
	v_lshlrev_b32_e32 v162, 16, v138
	v_and_b32_e32 v163, 0xffff0000, v138
	v_lshlrev_b32_e32 v164, 16, v139
	v_and_b32_e32 v165, 0xffff0000, v139
	v_pk_mul_f32 v[162:163], v[162:163], v[252:253] op_sel_hi:[1,0]
	v_pk_mul_f32 v[164:165], v[164:165], v[252:253] op_sel_hi:[1,0]
	v_pk_mul_f32 v[162:163], v[162:163], v[214:215]
	v_pk_mul_f32 v[164:165], v[164:165], v[216:217]
	v_pk_fma_f32 v[18:19], v[218:219], v[162:163], v[18:19]
	v_pk_fma_f32 v[20:21], v[220:221], v[164:165], v[20:21]
	v_pk_fma_f32 v[170:171], v[18:19], v[18:19], v[170:171]
	v_pk_fma_f32 v[172:173], v[20:21], v[20:21], v[172:173]
	v_cvt_pk_bf16_f32 v166, v18, v19
	v_cvt_pk_bf16_f32 v167, v20, v21
	global_store_dwordx2 v244, v[166:167], s[22:23] offset:2048
	ds_read_b128 v[214:217], v238 offset:6144
	ds_read_b128 v[218:221], v238 offset:38912
	s_waitcnt lgkmcnt(2)
	v_lshlrev_b32_e32 v162, 16, v140
	v_and_b32_e32 v163, 0xffff0000, v140
	v_lshlrev_b32_e32 v164, 16, v141
	v_and_b32_e32 v165, 0xffff0000, v141
	v_pk_mul_f32 v[162:163], v[162:163], v[252:253] op_sel_hi:[1,0]
	v_pk_mul_f32 v[164:165], v[164:165], v[252:253] op_sel_hi:[1,0]
	v_pk_mul_f32 v[162:163], v[162:163], v[226:227]
	v_pk_mul_f32 v[164:165], v[164:165], v[228:229]
	v_pk_fma_f32 v[22:23], v[230:231], v[162:163], v[22:23]
	v_pk_fma_f32 v[24:25], v[232:233], v[164:165], v[24:25]
	v_pk_fma_f32 v[170:171], v[22:23], v[22:23], v[170:171]
	v_pk_fma_f32 v[172:173], v[24:25], v[24:25], v[172:173]
	v_cvt_pk_bf16_f32 v168, v22, v23
	v_cvt_pk_bf16_f32 v169, v24, v25
	global_store_dwordx2 v244, v[168:169], s[22:23] offset:2560
	ds_read_b128 v[226:229], v238 offset:7168
	ds_read_b128 v[230:233], v238 offset:39936
	s_waitcnt lgkmcnt(2)
	v_lshlrev_b32_e32 v162, 16, v142
	v_and_b32_e32 v163, 0xffff0000, v142
	v_lshlrev_b32_e32 v164, 16, v143
	v_and_b32_e32 v165, 0xffff0000, v143
	v_pk_mul_f32 v[162:163], v[162:163], v[252:253] op_sel_hi:[1,0]
	v_pk_mul_f32 v[164:165], v[164:165], v[252:253] op_sel_hi:[1,0]
	v_pk_mul_f32 v[162:163], v[162:163], v[214:215]
	v_pk_mul_f32 v[164:165], v[164:165], v[216:217]
	v_pk_fma_f32 v[26:27], v[218:219], v[162:163], v[26:27]
	v_pk_fma_f32 v[28:29], v[220:221], v[164:165], v[28:29]
	v_pk_fma_f32 v[170:171], v[26:27], v[26:27], v[170:171]
	v_pk_fma_f32 v[172:173], v[28:29], v[28:29], v[172:173]
	v_cvt_pk_bf16_f32 v166, v26, v27
	v_cvt_pk_bf16_f32 v167, v28, v29
	global_store_dwordx2 v244, v[166:167], s[22:23] offset:3072
	ds_read_b128 v[214:217], v238 offset:8192
	ds_read_b128 v[218:221], v238 offset:40960
	s_waitcnt lgkmcnt(2)
	v_lshlrev_b32_e32 v162, 16, v144
	v_and_b32_e32 v163, 0xffff0000, v144
	v_lshlrev_b32_e32 v164, 16, v145
	v_and_b32_e32 v165, 0xffff0000, v145
	v_pk_mul_f32 v[162:163], v[162:163], v[252:253] op_sel_hi:[1,0]
	v_pk_mul_f32 v[164:165], v[164:165], v[252:253] op_sel_hi:[1,0]
	v_pk_mul_f32 v[162:163], v[162:163], v[226:227]
	v_pk_mul_f32 v[164:165], v[164:165], v[228:229]
	v_pk_fma_f32 v[30:31], v[230:231], v[162:163], v[30:31]
	v_pk_fma_f32 v[32:33], v[232:233], v[164:165], v[32:33]
	v_pk_fma_f32 v[170:171], v[30:31], v[30:31], v[170:171]
	v_pk_fma_f32 v[172:173], v[32:33], v[32:33], v[172:173]
	v_cvt_pk_bf16_f32 v168, v30, v31
	v_cvt_pk_bf16_f32 v169, v32, v33
	global_store_dwordx2 v244, v[168:169], s[22:23] offset:3584
	ds_read_b128 v[226:229], v238 offset:9216
	ds_read_b128 v[230:233], v238 offset:41984
	s_waitcnt lgkmcnt(2)
	v_lshlrev_b32_e32 v162, 16, v146
	v_and_b32_e32 v163, 0xffff0000, v146
	v_lshlrev_b32_e32 v164, 16, v147
	v_and_b32_e32 v165, 0xffff0000, v147
	v_pk_mul_f32 v[162:163], v[162:163], v[252:253] op_sel_hi:[1,0]
	v_pk_mul_f32 v[164:165], v[164:165], v[252:253] op_sel_hi:[1,0]
	v_pk_mul_f32 v[162:163], v[162:163], v[214:215]
	v_pk_mul_f32 v[164:165], v[164:165], v[216:217]
	v_pk_fma_f32 v[34:35], v[218:219], v[162:163], v[34:35]
	v_pk_fma_f32 v[36:37], v[220:221], v[164:165], v[36:37]
	v_pk_fma_f32 v[170:171], v[34:35], v[34:35], v[170:171]
	v_pk_fma_f32 v[172:173], v[36:37], v[36:37], v[172:173]
	v_cvt_pk_bf16_f32 v166, v34, v35
	v_cvt_pk_bf16_f32 v167, v36, v37
	global_store_dwordx2 v245, v[166:167], s[22:23] offset:0
	ds_read_b128 v[214:217], v238 offset:10240
	ds_read_b128 v[218:221], v238 offset:43008
	s_waitcnt lgkmcnt(2)
	v_lshlrev_b32_e32 v162, 16, v148
	v_and_b32_e32 v163, 0xffff0000, v148
	v_lshlrev_b32_e32 v164, 16, v149
	v_and_b32_e32 v165, 0xffff0000, v149
	v_pk_mul_f32 v[162:163], v[162:163], v[252:253] op_sel_hi:[1,0]
	v_pk_mul_f32 v[164:165], v[164:165], v[252:253] op_sel_hi:[1,0]
	v_pk_mul_f32 v[162:163], v[162:163], v[226:227]
	v_pk_mul_f32 v[164:165], v[164:165], v[228:229]
	v_pk_fma_f32 v[38:39], v[230:231], v[162:163], v[38:39]
	v_pk_fma_f32 v[40:41], v[232:233], v[164:165], v[40:41]
	v_pk_fma_f32 v[170:171], v[38:39], v[38:39], v[170:171]
	v_pk_fma_f32 v[172:173], v[40:41], v[40:41], v[172:173]
	v_cvt_pk_bf16_f32 v168, v38, v39
	v_cvt_pk_bf16_f32 v169, v40, v41
	global_store_dwordx2 v245, v[168:169], s[22:23] offset:512
	ds_read_b128 v[226:229], v238 offset:11264
	ds_read_b128 v[230:233], v238 offset:44032
	s_waitcnt lgkmcnt(2)
	v_lshlrev_b32_e32 v162, 16, v150
	v_and_b32_e32 v163, 0xffff0000, v150
	v_lshlrev_b32_e32 v164, 16, v151
	v_and_b32_e32 v165, 0xffff0000, v151
	v_pk_mul_f32 v[162:163], v[162:163], v[252:253] op_sel_hi:[1,0]
	v_pk_mul_f32 v[164:165], v[164:165], v[252:253] op_sel_hi:[1,0]
	v_pk_mul_f32 v[162:163], v[162:163], v[214:215]
	v_pk_mul_f32 v[164:165], v[164:165], v[216:217]
	v_pk_fma_f32 v[42:43], v[218:219], v[162:163], v[42:43]
	v_pk_fma_f32 v[44:45], v[220:221], v[164:165], v[44:45]
	v_pk_fma_f32 v[170:171], v[42:43], v[42:43], v[170:171]
	v_pk_fma_f32 v[172:173], v[44:45], v[44:45], v[172:173]
	v_cvt_pk_bf16_f32 v166, v42, v43
	v_cvt_pk_bf16_f32 v167, v44, v45
	global_store_dwordx2 v245, v[166:167], s[22:23] offset:1024
	ds_read_b128 v[214:217], v238 offset:12288
	ds_read_b128 v[218:221], v238 offset:45056
	s_waitcnt lgkmcnt(2)
	v_lshlrev_b32_e32 v162, 16, v152
	v_and_b32_e32 v163, 0xffff0000, v152
	v_lshlrev_b32_e32 v164, 16, v153
	v_and_b32_e32 v165, 0xffff0000, v153
	v_pk_mul_f32 v[162:163], v[162:163], v[252:253] op_sel_hi:[1,0]
	v_pk_mul_f32 v[164:165], v[164:165], v[252:253] op_sel_hi:[1,0]
	v_pk_mul_f32 v[162:163], v[162:163], v[226:227]
	v_pk_mul_f32 v[164:165], v[164:165], v[228:229]
	v_pk_fma_f32 v[46:47], v[230:231], v[162:163], v[46:47]
	v_pk_fma_f32 v[48:49], v[232:233], v[164:165], v[48:49]
	v_pk_fma_f32 v[170:171], v[46:47], v[46:47], v[170:171]
	v_pk_fma_f32 v[172:173], v[48:49], v[48:49], v[172:173]
	v_cvt_pk_bf16_f32 v168, v46, v47
	v_cvt_pk_bf16_f32 v169, v48, v49
	global_store_dwordx2 v245, v[168:169], s[22:23] offset:1536
	ds_read_b128 v[226:229], v238 offset:13312
	ds_read_b128 v[230:233], v238 offset:46080
	s_waitcnt lgkmcnt(2)
	v_lshlrev_b32_e32 v162, 16, v154
	v_and_b32_e32 v163, 0xffff0000, v154
	v_lshlrev_b32_e32 v164, 16, v155
	v_and_b32_e32 v165, 0xffff0000, v155
	v_pk_mul_f32 v[162:163], v[162:163], v[252:253] op_sel_hi:[1,0]
	v_pk_mul_f32 v[164:165], v[164:165], v[252:253] op_sel_hi:[1,0]
	v_pk_mul_f32 v[162:163], v[162:163], v[214:215]
	v_pk_mul_f32 v[164:165], v[164:165], v[216:217]
	v_pk_fma_f32 v[50:51], v[218:219], v[162:163], v[50:51]
	v_pk_fma_f32 v[52:53], v[220:221], v[164:165], v[52:53]
	v_pk_fma_f32 v[170:171], v[50:51], v[50:51], v[170:171]
	v_pk_fma_f32 v[172:173], v[52:53], v[52:53], v[172:173]
	v_cvt_pk_bf16_f32 v166, v50, v51
	v_cvt_pk_bf16_f32 v167, v52, v53
	global_store_dwordx2 v245, v[166:167], s[22:23] offset:2048
	ds_read_b128 v[214:217], v238 offset:14336
	ds_read_b128 v[218:221], v238 offset:47104
	s_waitcnt lgkmcnt(2)
	v_lshlrev_b32_e32 v162, 16, v156
	v_and_b32_e32 v163, 0xffff0000, v156
	v_lshlrev_b32_e32 v164, 16, v157
	v_and_b32_e32 v165, 0xffff0000, v157
	v_pk_mul_f32 v[162:163], v[162:163], v[252:253] op_sel_hi:[1,0]
	v_pk_mul_f32 v[164:165], v[164:165], v[252:253] op_sel_hi:[1,0]
	v_pk_mul_f32 v[162:163], v[162:163], v[226:227]
	v_pk_mul_f32 v[164:165], v[164:165], v[228:229]
	v_pk_fma_f32 v[54:55], v[230:231], v[162:163], v[54:55]
	v_pk_fma_f32 v[56:57], v[232:233], v[164:165], v[56:57]
	v_pk_fma_f32 v[170:171], v[54:55], v[54:55], v[170:171]
	v_pk_fma_f32 v[172:173], v[56:57], v[56:57], v[172:173]
	v_cvt_pk_bf16_f32 v168, v54, v55
	v_cvt_pk_bf16_f32 v169, v56, v57
	global_store_dwordx2 v245, v[168:169], s[22:23] offset:2560
	ds_read_b128 v[226:229], v238 offset:15360
	ds_read_b128 v[230:233], v238 offset:48128
	s_waitcnt lgkmcnt(2)
	v_lshlrev_b32_e32 v162, 16, v158
	v_and_b32_e32 v163, 0xffff0000, v158
	v_lshlrev_b32_e32 v164, 16, v159
	v_and_b32_e32 v165, 0xffff0000, v159
	v_pk_mul_f32 v[162:163], v[162:163], v[252:253] op_sel_hi:[1,0]
	v_pk_mul_f32 v[164:165], v[164:165], v[252:253] op_sel_hi:[1,0]
	v_pk_mul_f32 v[162:163], v[162:163], v[214:215]
	v_pk_mul_f32 v[164:165], v[164:165], v[216:217]
	v_pk_fma_f32 v[58:59], v[218:219], v[162:163], v[58:59]
	v_pk_fma_f32 v[60:61], v[220:221], v[164:165], v[60:61]
	v_pk_fma_f32 v[170:171], v[58:59], v[58:59], v[170:171]
	v_pk_fma_f32 v[172:173], v[60:61], v[60:61], v[172:173]
	v_cvt_pk_bf16_f32 v166, v58, v59
	v_cvt_pk_bf16_f32 v167, v60, v61
	global_store_dwordx2 v245, v[166:167], s[22:23] offset:3072
	s_waitcnt lgkmcnt(0)
	v_lshlrev_b32_e32 v162, 16, v160
	v_and_b32_e32 v163, 0xffff0000, v160
	v_lshlrev_b32_e32 v164, 16, v161
	v_and_b32_e32 v165, 0xffff0000, v161
	v_pk_mul_f32 v[162:163], v[162:163], v[252:253] op_sel_hi:[1,0]
	v_pk_mul_f32 v[164:165], v[164:165], v[252:253] op_sel_hi:[1,0]
	v_pk_mul_f32 v[162:163], v[162:163], v[226:227]
	v_pk_mul_f32 v[164:165], v[164:165], v[228:229]
	v_pk_fma_f32 v[62:63], v[230:231], v[162:163], v[62:63]
	v_pk_fma_f32 v[64:65], v[232:233], v[164:165], v[64:65]
	v_pk_fma_f32 v[170:171], v[62:63], v[62:63], v[170:171]
	v_pk_fma_f32 v[172:173], v[64:65], v[64:65], v[172:173]
	v_cvt_pk_bf16_f32 v168, v62, v63
	v_cvt_pk_bf16_f32 v169, v64, v65
	global_store_dwordx2 v245, v[168:169], s[22:23] offset:3584
	ds_read_b128 v[214:217], v238 offset:16384
	ds_read_b128 v[218:221], v238 offset:49152
	ds_read_b128 v[222:225], v239 offset:0
	v_pk_add_f32 v[170:171], v[170:171], v[172:173]
	s_nop 0
	v_add_f32_e32 v252, v170, v171
	s_waitcnt lgkmcnt(0)
	ds_bpermute_b32 v254, v246, v252
	s_waitcnt lgkmcnt(0)
	v_add_f32_e32 v252, v252, v254
	ds_bpermute_b32 v254, v247, v252
	s_waitcnt lgkmcnt(0)
	v_add_f32_e32 v252, v252, v254
	ds_bpermute_b32 v254, v248, v252
	s_waitcnt lgkmcnt(0)
	v_add_f32_e32 v252, v252, v254
	ds_bpermute_b32 v254, v249, v252
	s_waitcnt lgkmcnt(0)
	v_add_f32_e32 v252, v252, v254
	ds_bpermute_b32 v254, v250, v252
	s_waitcnt lgkmcnt(0)
	v_add_f32_e32 v252, v252, v254
	ds_bpermute_b32 v254, v251, v252
	s_waitcnt lgkmcnt(0)
	v_add_f32_e32 v252, v252, v254
	v_mov_b32_e32 v254, 0x358637bd
	v_fmac_f32_e32 v254, 0x39800000, v252
	v_mul_f32_e32 v252, 0x4b800000, v254
	v_cmp_gt_f32_e32 vcc, s32, v254
	s_nop 1
	v_cndmask_b32_e32 v254, v254, v252, vcc
	v_rsq_f32_e32 v254, v254
	s_nop 0
	v_mul_f32_e32 v252, 0x45800000, v254
	v_cndmask_b32_e32 v252, v254, v252, vcc
	s_add_u32 s16, s16, 0x1000000
	s_addc_u32 s17, s17, 0
	global_load_dwordx2 v[130:131], v244, s[16:17] offset:0
	global_load_dwordx2 v[132:133], v244, s[16:17] offset:512
	global_load_dwordx2 v[134:135], v244, s[16:17] offset:1024
	global_load_dwordx2 v[136:137], v244, s[16:17] offset:1536
	global_load_dwordx2 v[138:139], v244, s[16:17] offset:2048
	global_load_dwordx2 v[140:141], v244, s[16:17] offset:2560
	global_load_dwordx2 v[142:143], v244, s[16:17] offset:3072
	global_load_dwordx2 v[144:145], v244, s[16:17] offset:3584
	global_load_dwordx2 v[146:147], v245, s[16:17] offset:0
	global_load_dwordx2 v[148:149], v245, s[16:17] offset:512
	global_load_dwordx2 v[150:151], v245, s[16:17] offset:1024
	global_load_dwordx2 v[152:153], v245, s[16:17] offset:1536
	global_load_dwordx2 v[154:155], v245, s[16:17] offset:2048
	global_load_dwordx2 v[156:157], v245, s[16:17] offset:2560
	global_load_dwordx2 v[158:159], v245, s[16:17] offset:3072
	global_load_dwordx2 v[160:161], v245, s[16:17] offset:3584
	ds_read_b128 v[226:229], v238 offset:17408
	ds_read_b128 v[230:233], v238 offset:50176
	ds_read_b128 v[234:237], v239 offset:1024
	s_waitcnt lgkmcnt(3)
	v_pk_mul_f32 v[2:3], v[2:3], v[252:253] op_sel_hi:[1,0]
	v_pk_mul_f32 v[4:5], v[4:5], v[252:253] op_sel_hi:[1,0]
	v_pk_mul_f32 v[2:3], v[2:3], v[214:215]
	v_pk_mul_f32 v[4:5], v[4:5], v[216:217]
	v_pk_add_f32 v[222:223], v[222:223], 1.0 op_sel_hi:[1,0]
	v_pk_add_f32 v[224:225], v[224:225], 1.0 op_sel_hi:[1,0]
	v_pk_fma_f32 v[2:3], v[2:3], v[222:223], v[218:219]
	v_pk_fma_f32 v[4:5], v[4:5], v[224:225], v[220:221]
	s_nop 0
	v_cvt_pk_bf16_f32 v2, v2, v3
	v_cvt_pk_bf16_f32 v3, v4, v5
	global_store_dwordx2 v244, v[2:3], s[38:39] offset:0
	ds_read_b128 v[214:217], v238 offset:18432
	ds_read_b128 v[218:221], v238 offset:51200
	ds_read_b128 v[222:225], v239 offset:2048
	s_waitcnt lgkmcnt(3)
	v_pk_mul_f32 v[6:7], v[6:7], v[252:253] op_sel_hi:[1,0]
	v_pk_mul_f32 v[8:9], v[8:9], v[252:253] op_sel_hi:[1,0]
	v_pk_mul_f32 v[6:7], v[6:7], v[226:227]
	v_pk_mul_f32 v[8:9], v[8:9], v[228:229]
	v_pk_add_f32 v[234:235], v[234:235], 1.0 op_sel_hi:[1,0]
	v_pk_add_f32 v[236:237], v[236:237], 1.0 op_sel_hi:[1,0]
	v_pk_fma_f32 v[6:7], v[6:7], v[234:235], v[230:231]
	v_pk_fma_f32 v[8:9], v[8:9], v[236:237], v[232:233]
	s_nop 0
	v_cvt_pk_bf16_f32 v6, v6, v7
	v_cvt_pk_bf16_f32 v7, v8, v9
	global_store_dwordx2 v244, v[6:7], s[38:39] offset:512
	ds_read_b128 v[226:229], v238 offset:19456
	ds_read_b128 v[230:233], v238 offset:52224
	ds_read_b128 v[234:237], v239 offset:3072
	s_waitcnt lgkmcnt(3)
	v_pk_mul_f32 v[10:11], v[10:11], v[252:253] op_sel_hi:[1,0]
	v_pk_mul_f32 v[12:13], v[12:13], v[252:253] op_sel_hi:[1,0]
	v_pk_mul_f32 v[10:11], v[10:11], v[214:215]
	v_pk_mul_f32 v[12:13], v[12:13], v[216:217]
	v_pk_add_f32 v[222:223], v[222:223], 1.0 op_sel_hi:[1,0]
	v_pk_add_f32 v[224:225], v[224:225], 1.0 op_sel_hi:[1,0]
	v_pk_fma_f32 v[10:11], v[10:11], v[222:223], v[218:219]
	v_pk_fma_f32 v[12:13], v[12:13], v[224:225], v[220:221]
	s_nop 0
	v_cvt_pk_bf16_f32 v10, v10, v11
	v_cvt_pk_bf16_f32 v11, v12, v13
	global_store_dwordx2 v244, v[10:11], s[38:39] offset:1024
	ds_read_b128 v[214:217], v238 offset:20480
	ds_read_b128 v[218:221], v238 offset:53248
	ds_read_b128 v[222:225], v239 offset:4096
	s_waitcnt lgkmcnt(3)
	v_pk_mul_f32 v[14:15], v[14:15], v[252:253] op_sel_hi:[1,0]
	v_pk_mul_f32 v[16:17], v[16:17], v[252:253] op_sel_hi:[1,0]
	v_pk_mul_f32 v[14:15], v[14:15], v[226:227]
	v_pk_mul_f32 v[16:17], v[16:17], v[228:229]
	v_pk_add_f32 v[234:235], v[234:235], 1.0 op_sel_hi:[1,0]
	v_pk_add_f32 v[236:237], v[236:237], 1.0 op_sel_hi:[1,0]
	v_pk_fma_f32 v[14:15], v[14:15], v[234:235], v[230:231]
	v_pk_fma_f32 v[16:17], v[16:17], v[236:237], v[232:233]
	s_nop 0
	v_cvt_pk_bf16_f32 v14, v14, v15
	v_cvt_pk_bf16_f32 v15, v16, v17
	global_store_dwordx2 v244, v[14:15], s[38:39] offset:1536
	ds_read_b128 v[226:229], v238 offset:21504
	ds_read_b128 v[230:233], v238 offset:54272
	ds_read_b128 v[234:237], v239 offset:5120
	s_waitcnt lgkmcnt(3)
	v_pk_mul_f32 v[18:19], v[18:19], v[252:253] op_sel_hi:[1,0]
	v_pk_mul_f32 v[20:21], v[20:21], v[252:253] op_sel_hi:[1,0]
	v_pk_mul_f32 v[18:19], v[18:19], v[214:215]
	v_pk_mul_f32 v[20:21], v[20:21], v[216:217]
	v_pk_add_f32 v[222:223], v[222:223], 1.0 op_sel_hi:[1,0]
	v_pk_add_f32 v[224:225], v[224:225], 1.0 op_sel_hi:[1,0]
	v_pk_fma_f32 v[18:19], v[18:19], v[222:223], v[218:219]
	v_pk_fma_f32 v[20:21], v[20:21], v[224:225], v[220:221]
	s_nop 0
	v_cvt_pk_bf16_f32 v18, v18, v19
	v_cvt_pk_bf16_f32 v19, v20, v21
	global_store_dwordx2 v244, v[18:19], s[38:39] offset:2048
	ds_read_b128 v[214:217], v238 offset:22528
	ds_read_b128 v[218:221], v238 offset:55296
	ds_read_b128 v[222:225], v239 offset:6144
	s_waitcnt lgkmcnt(3)
	v_pk_mul_f32 v[22:23], v[22:23], v[252:253] op_sel_hi:[1,0]
	v_pk_mul_f32 v[24:25], v[24:25], v[252:253] op_sel_hi:[1,0]
	v_pk_mul_f32 v[22:23], v[22:23], v[226:227]
	v_pk_mul_f32 v[24:25], v[24:25], v[228:229]
	v_pk_add_f32 v[234:235], v[234:235], 1.0 op_sel_hi:[1,0]
	v_pk_add_f32 v[236:237], v[236:237], 1.0 op_sel_hi:[1,0]
	v_pk_fma_f32 v[22:23], v[22:23], v[234:235], v[230:231]
	v_pk_fma_f32 v[24:25], v[24:25], v[236:237], v[232:233]
	s_nop 0
	v_cvt_pk_bf16_f32 v22, v22, v23
	v_cvt_pk_bf16_f32 v23, v24, v25
	global_store_dwordx2 v244, v[22:23], s[38:39] offset:2560
	ds_read_b128 v[226:229], v238 offset:23552
	ds_read_b128 v[230:233], v238 offset:56320
	ds_read_b128 v[234:237], v239 offset:7168
	s_waitcnt lgkmcnt(3)
	v_pk_mul_f32 v[26:27], v[26:27], v[252:253] op_sel_hi:[1,0]
	v_pk_mul_f32 v[28:29], v[28:29], v[252:253] op_sel_hi:[1,0]
	v_pk_mul_f32 v[26:27], v[26:27], v[214:215]
	v_pk_mul_f32 v[28:29], v[28:29], v[216:217]
	v_pk_add_f32 v[222:223], v[222:223], 1.0 op_sel_hi:[1,0]
	v_pk_add_f32 v[224:225], v[224:225], 1.0 op_sel_hi:[1,0]
	v_pk_fma_f32 v[26:27], v[26:27], v[222:223], v[218:219]
	v_pk_fma_f32 v[28:29], v[28:29], v[224:225], v[220:221]
	s_nop 0
	v_cvt_pk_bf16_f32 v26, v26, v27
	v_cvt_pk_bf16_f32 v27, v28, v29
	global_store_dwordx2 v244, v[26:27], s[38:39] offset:3072
	ds_read_b128 v[214:217], v238 offset:24576
	ds_read_b128 v[218:221], v238 offset:57344
	ds_read_b128 v[222:225], v239 offset:8192
	s_waitcnt lgkmcnt(3)
	v_pk_mul_f32 v[30:31], v[30:31], v[252:253] op_sel_hi:[1,0]
	v_pk_mul_f32 v[32:33], v[32:33], v[252:253] op_sel_hi:[1,0]
	v_pk_mul_f32 v[30:31], v[30:31], v[226:227]
	v_pk_mul_f32 v[32:33], v[32:33], v[228:229]
	v_pk_add_f32 v[234:235], v[234:235], 1.0 op_sel_hi:[1,0]
	v_pk_add_f32 v[236:237], v[236:237], 1.0 op_sel_hi:[1,0]
	v_pk_fma_f32 v[30:31], v[30:31], v[234:235], v[230:231]
	v_pk_fma_f32 v[32:33], v[32:33], v[236:237], v[232:233]
	s_nop 0
	v_cvt_pk_bf16_f32 v30, v30, v31
	v_cvt_pk_bf16_f32 v31, v32, v33
	global_store_dwordx2 v244, v[30:31], s[38:39] offset:3584
	ds_read_b128 v[226:229], v238 offset:25600
	ds_read_b128 v[230:233], v238 offset:58368
	ds_read_b128 v[234:237], v239 offset:9216
	s_waitcnt lgkmcnt(3)
	v_pk_mul_f32 v[34:35], v[34:35], v[252:253] op_sel_hi:[1,0]
	v_pk_mul_f32 v[36:37], v[36:37], v[252:253] op_sel_hi:[1,0]
	v_pk_mul_f32 v[34:35], v[34:35], v[214:215]
	v_pk_mul_f32 v[36:37], v[36:37], v[216:217]
	v_pk_add_f32 v[222:223], v[222:223], 1.0 op_sel_hi:[1,0]
	v_pk_add_f32 v[224:225], v[224:225], 1.0 op_sel_hi:[1,0]
	v_pk_fma_f32 v[34:35], v[34:35], v[222:223], v[218:219]
	v_pk_fma_f32 v[36:37], v[36:37], v[224:225], v[220:221]
	s_nop 0
	v_cvt_pk_bf16_f32 v34, v34, v35
	v_cvt_pk_bf16_f32 v35, v36, v37
	global_store_dwordx2 v245, v[34:35], s[38:39] offset:0
	ds_read_b128 v[214:217], v238 offset:26624
	ds_read_b128 v[218:221], v238 offset:59392
	ds_read_b128 v[222:225], v239 offset:10240
	s_waitcnt lgkmcnt(3)
	v_pk_mul_f32 v[38:39], v[38:39], v[252:253] op_sel_hi:[1,0]
	v_pk_mul_f32 v[40:41], v[40:41], v[252:253] op_sel_hi:[1,0]
	v_pk_mul_f32 v[38:39], v[38:39], v[226:227]
	v_pk_mul_f32 v[40:41], v[40:41], v[228:229]
	v_pk_add_f32 v[234:235], v[234:235], 1.0 op_sel_hi:[1,0]
	v_pk_add_f32 v[236:237], v[236:237], 1.0 op_sel_hi:[1,0]
	v_pk_fma_f32 v[38:39], v[38:39], v[234:235], v[230:231]
	v_pk_fma_f32 v[40:41], v[40:41], v[236:237], v[232:233]
	s_nop 0
	v_cvt_pk_bf16_f32 v38, v38, v39
	v_cvt_pk_bf16_f32 v39, v40, v41
	global_store_dwordx2 v245, v[38:39], s[38:39] offset:512
	ds_read_b128 v[226:229], v238 offset:27648
	ds_read_b128 v[230:233], v238 offset:60416
	ds_read_b128 v[234:237], v239 offset:11264
	s_waitcnt lgkmcnt(3)
	v_pk_mul_f32 v[42:43], v[42:43], v[252:253] op_sel_hi:[1,0]
	v_pk_mul_f32 v[44:45], v[44:45], v[252:253] op_sel_hi:[1,0]
	v_pk_mul_f32 v[42:43], v[42:43], v[214:215]
	v_pk_mul_f32 v[44:45], v[44:45], v[216:217]
	v_pk_add_f32 v[222:223], v[222:223], 1.0 op_sel_hi:[1,0]
	v_pk_add_f32 v[224:225], v[224:225], 1.0 op_sel_hi:[1,0]
	v_pk_fma_f32 v[42:43], v[42:43], v[222:223], v[218:219]
	v_pk_fma_f32 v[44:45], v[44:45], v[224:225], v[220:221]
	s_nop 0
	v_cvt_pk_bf16_f32 v42, v42, v43
	v_cvt_pk_bf16_f32 v43, v44, v45
	global_store_dwordx2 v245, v[42:43], s[38:39] offset:1024
	ds_read_b128 v[214:217], v238 offset:28672
	ds_read_b128 v[218:221], v238 offset:61440
	ds_read_b128 v[222:225], v239 offset:12288
	s_waitcnt lgkmcnt(3)
	v_pk_mul_f32 v[46:47], v[46:47], v[252:253] op_sel_hi:[1,0]
	v_pk_mul_f32 v[48:49], v[48:49], v[252:253] op_sel_hi:[1,0]
	v_pk_mul_f32 v[46:47], v[46:47], v[226:227]
	v_pk_mul_f32 v[48:49], v[48:49], v[228:229]
	v_pk_add_f32 v[234:235], v[234:235], 1.0 op_sel_hi:[1,0]
	v_pk_add_f32 v[236:237], v[236:237], 1.0 op_sel_hi:[1,0]
	v_pk_fma_f32 v[46:47], v[46:47], v[234:235], v[230:231]
	v_pk_fma_f32 v[48:49], v[48:49], v[236:237], v[232:233]
	s_nop 0
	v_cvt_pk_bf16_f32 v46, v46, v47
	v_cvt_pk_bf16_f32 v47, v48, v49
	global_store_dwordx2 v245, v[46:47], s[38:39] offset:1536
	ds_read_b128 v[226:229], v238 offset:29696
	ds_read_b128 v[230:233], v238 offset:62464
	ds_read_b128 v[234:237], v239 offset:13312
	s_waitcnt lgkmcnt(3)
	v_pk_mul_f32 v[50:51], v[50:51], v[252:253] op_sel_hi:[1,0]
	v_pk_mul_f32 v[52:53], v[52:53], v[252:253] op_sel_hi:[1,0]
	v_pk_mul_f32 v[50:51], v[50:51], v[214:215]
	v_pk_mul_f32 v[52:53], v[52:53], v[216:217]
	v_pk_add_f32 v[222:223], v[222:223], 1.0 op_sel_hi:[1,0]
	v_pk_add_f32 v[224:225], v[224:225], 1.0 op_sel_hi:[1,0]
	v_pk_fma_f32 v[50:51], v[50:51], v[222:223], v[218:219]
	v_pk_fma_f32 v[52:53], v[52:53], v[224:225], v[220:221]
	s_nop 0
	v_cvt_pk_bf16_f32 v50, v50, v51
	v_cvt_pk_bf16_f32 v51, v52, v53
	global_store_dwordx2 v245, v[50:51], s[38:39] offset:2048
	ds_read_b128 v[214:217], v238 offset:30720
	ds_read_b128 v[218:221], v238 offset:63488
	ds_read_b128 v[222:225], v239 offset:14336
	s_waitcnt lgkmcnt(3)
	v_pk_mul_f32 v[54:55], v[54:55], v[252:253] op_sel_hi:[1,0]
	v_pk_mul_f32 v[56:57], v[56:57], v[252:253] op_sel_hi:[1,0]
	v_pk_mul_f32 v[54:55], v[54:55], v[226:227]
	v_pk_mul_f32 v[56:57], v[56:57], v[228:229]
	v_pk_add_f32 v[234:235], v[234:235], 1.0 op_sel_hi:[1,0]
	v_pk_add_f32 v[236:237], v[236:237], 1.0 op_sel_hi:[1,0]
	v_pk_fma_f32 v[54:55], v[54:55], v[234:235], v[230:231]
	v_pk_fma_f32 v[56:57], v[56:57], v[236:237], v[232:233]
	s_nop 0
	v_cvt_pk_bf16_f32 v54, v54, v55
	v_cvt_pk_bf16_f32 v55, v56, v57
	global_store_dwordx2 v245, v[54:55], s[38:39] offset:2560
	ds_read_b128 v[226:229], v238 offset:31744
	ds_read_b128 v[230:233], v238 offset:64512
	ds_read_b128 v[234:237], v239 offset:15360
	s_waitcnt lgkmcnt(3)
	v_pk_mul_f32 v[58:59], v[58:59], v[252:253] op_sel_hi:[1,0]
	v_pk_mul_f32 v[60:61], v[60:61], v[252:253] op_sel_hi:[1,0]
	v_pk_mul_f32 v[58:59], v[58:59], v[214:215]
	v_pk_mul_f32 v[60:61], v[60:61], v[216:217]
	v_pk_add_f32 v[222:223], v[222:223], 1.0 op_sel_hi:[1,0]
	v_pk_add_f32 v[224:225], v[224:225], 1.0 op_sel_hi:[1,0]
	v_pk_fma_f32 v[58:59], v[58:59], v[222:223], v[218:219]
	v_pk_fma_f32 v[60:61], v[60:61], v[224:225], v[220:221]
	s_nop 0
	v_cvt_pk_bf16_f32 v58, v58, v59
	v_cvt_pk_bf16_f32 v59, v60, v61
	global_store_dwordx2 v245, v[58:59], s[38:39] offset:3072
	s_waitcnt lgkmcnt(0)
	v_pk_mul_f32 v[62:63], v[62:63], v[252:253] op_sel_hi:[1,0]
	v_pk_mul_f32 v[64:65], v[64:65], v[252:253] op_sel_hi:[1,0]
	v_pk_mul_f32 v[62:63], v[62:63], v[226:227]
	v_pk_mul_f32 v[64:65], v[64:65], v[228:229]
	v_pk_add_f32 v[234:235], v[234:235], 1.0 op_sel_hi:[1,0]
	v_pk_add_f32 v[236:237], v[236:237], 1.0 op_sel_hi:[1,0]
	v_pk_fma_f32 v[62:63], v[62:63], v[234:235], v[230:231]
	v_pk_fma_f32 v[64:65], v[64:65], v[236:237], v[232:233]
	s_nop 0
	v_cvt_pk_bf16_f32 v62, v62, v63
	v_cvt_pk_bf16_f32 v63, v64, v65
	global_store_dwordx2 v245, v[62:63], s[38:39] offset:3584
	s_add_u32 s22, s22, 0x1000000
	s_addc_u32 s23, s23, 0
	s_add_u32 s38, s38, 0x1000000
	s_addc_u32 s39, s39, 0
	s_waitcnt vmcnt(16)
	global_load_dwordx4 v[2:5], v238, s[44:45] offset:0
	global_load_dwordx4 v[6:9], v238, s[44:45] offset:1024
	global_load_dwordx4 v[10:13], v238, s[44:45] offset:2048
	global_load_dwordx4 v[14:17], v238, s[44:45] offset:3072
	global_load_dwordx4 v[18:21], v241, s[44:45] offset:0
	global_load_dwordx4 v[22:25], v241, s[44:45] offset:1024
	global_load_dwordx4 v[26:29], v241, s[44:45] offset:2048
	global_load_dwordx4 v[30:33], v241, s[44:45] offset:3072
	global_load_dwordx4 v[34:37], v242, s[44:45] offset:0
	global_load_dwordx4 v[38:41], v242, s[44:45] offset:1024
	global_load_dwordx4 v[42:45], v242, s[44:45] offset:2048
	global_load_dwordx4 v[46:49], v242, s[44:45] offset:3072
	global_load_dwordx4 v[50:53], v243, s[44:45] offset:0
	global_load_dwordx4 v[54:57], v243, s[44:45] offset:1024
	global_load_dwordx4 v[58:61], v243, s[44:45] offset:2048
	global_load_dwordx4 v[62:65], v243, s[44:45] offset:3072
	ds_read_b128 v[214:217], v238 offset:0
	ds_read_b128 v[218:221], v238 offset:32768
	v_lshlrev_b32_e32 v162, 16, v130
	v_and_b32_e32 v163, 0xffff0000, v130
	v_lshlrev_b32_e32 v164, 16, v131
	v_and_b32_e32 v165, 0xffff0000, v131
	v_pk_mul_f32 v[170:171], v[162:163], v[162:163]
	v_pk_mul_f32 v[172:173], v[164:165], v[164:165]
	v_lshlrev_b32_e32 v166, 16, v132
	v_and_b32_e32 v167, 0xffff0000, v132
	v_lshlrev_b32_e32 v168, 16, v133
	v_and_b32_e32 v169, 0xffff0000, v133
	v_pk_fma_f32 v[170:171], v[166:167], v[166:167], v[170:171]
	v_pk_fma_f32 v[172:173], v[168:169], v[168:169], v[172:173]
	v_lshlrev_b32_e32 v162, 16, v134
	v_and_b32_e32 v163, 0xffff0000, v134
	v_lshlrev_b32_e32 v164, 16, v135
	v_and_b32_e32 v165, 0xffff0000, v135
	v_pk_fma_f32 v[170:171], v[162:163], v[162:163], v[170:171]
	v_pk_fma_f32 v[172:173], v[164:165], v[164:165], v[172:173]
	v_lshlrev_b32_e32 v166, 16, v136
	v_and_b32_e32 v167, 0xffff0000, v136
	v_lshlrev_b32_e32 v168, 16, v137
	v_and_b32_e32 v169, 0xffff0000, v137
	v_pk_fma_f32 v[170:171], v[166:167], v[166:167], v[170:171]
	v_pk_fma_f32 v[172:173], v[168:169], v[168:169], v[172:173]
	v_lshlrev_b32_e32 v162, 16, v138
	v_and_b32_e32 v163, 0xffff0000, v138
	v_lshlrev_b32_e32 v164, 16, v139
	v_and_b32_e32 v165, 0xffff0000, v139
	v_pk_fma_f32 v[170:171], v[162:163], v[162:163], v[170:171]
	v_pk_fma_f32 v[172:173], v[164:165], v[164:165], v[172:173]
	v_lshlrev_b32_e32 v166, 16, v140
	v_and_b32_e32 v167, 0xffff0000, v140
	v_lshlrev_b32_e32 v168, 16, v141
	v_and_b32_e32 v169, 0xffff0000, v141
	v_pk_fma_f32 v[170:171], v[166:167], v[166:167], v[170:171]
	v_pk_fma_f32 v[172:173], v[168:169], v[168:169], v[172:173]
	v_lshlrev_b32_e32 v162, 16, v142
	v_and_b32_e32 v163, 0xffff0000, v142
	v_lshlrev_b32_e32 v164, 16, v143
	v_and_b32_e32 v165, 0xffff0000, v143
	v_pk_fma_f32 v[170:171], v[162:163], v[162:163], v[170:171]
	v_pk_fma_f32 v[172:173], v[164:165], v[164:165], v[172:173]
	v_lshlrev_b32_e32 v166, 16, v144
	v_and_b32_e32 v167, 0xffff0000, v144
	v_lshlrev_b32_e32 v168, 16, v145
	v_and_b32_e32 v169, 0xffff0000, v145
	v_pk_fma_f32 v[170:171], v[166:167], v[166:167], v[170:171]
	v_pk_fma_f32 v[172:173], v[168:169], v[168:169], v[172:173]
	v_lshlrev_b32_e32 v162, 16, v146
	v_and_b32_e32 v163, 0xffff0000, v146
	v_lshlrev_b32_e32 v164, 16, v147
	v_and_b32_e32 v165, 0xffff0000, v147
	v_pk_fma_f32 v[170:171], v[162:163], v[162:163], v[170:171]
	v_pk_fma_f32 v[172:173], v[164:165], v[164:165], v[172:173]
	v_lshlrev_b32_e32 v166, 16, v148
	v_and_b32_e32 v167, 0xffff0000, v148
	v_lshlrev_b32_e32 v168, 16, v149
	v_and_b32_e32 v169, 0xffff0000, v149
	v_pk_fma_f32 v[170:171], v[166:167], v[166:167], v[170:171]
	v_pk_fma_f32 v[172:173], v[168:169], v[168:169], v[172:173]
	v_lshlrev_b32_e32 v162, 16, v150
	v_and_b32_e32 v163, 0xffff0000, v150
	v_lshlrev_b32_e32 v164, 16, v151
	v_and_b32_e32 v165, 0xffff0000, v151
	v_pk_fma_f32 v[170:171], v[162:163], v[162:163], v[170:171]
	v_pk_fma_f32 v[172:173], v[164:165], v[164:165], v[172:173]
	v_lshlrev_b32_e32 v166, 16, v152
	v_and_b32_e32 v167, 0xffff0000, v152
	v_lshlrev_b32_e32 v168, 16, v153
	v_and_b32_e32 v169, 0xffff0000, v153
	v_pk_fma_f32 v[170:171], v[166:167], v[166:167], v[170:171]
	v_pk_fma_f32 v[172:173], v[168:169], v[168:169], v[172:173]
	v_lshlrev_b32_e32 v162, 16, v154
	v_and_b32_e32 v163, 0xffff0000, v154
	v_lshlrev_b32_e32 v164, 16, v155
	v_and_b32_e32 v165, 0xffff0000, v155
	v_pk_fma_f32 v[170:171], v[162:163], v[162:163], v[170:171]
	v_pk_fma_f32 v[172:173], v[164:165], v[164:165], v[172:173]
	v_lshlrev_b32_e32 v166, 16, v156
	v_and_b32_e32 v167, 0xffff0000, v156
	v_lshlrev_b32_e32 v168, 16, v157
	v_and_b32_e32 v169, 0xffff0000, v157
	v_pk_fma_f32 v[170:171], v[166:167], v[166:167], v[170:171]
	v_pk_fma_f32 v[172:173], v[168:169], v[168:169], v[172:173]
	v_lshlrev_b32_e32 v162, 16, v158
	v_and_b32_e32 v163, 0xffff0000, v158
	v_lshlrev_b32_e32 v164, 16, v159
	v_and_b32_e32 v165, 0xffff0000, v159
	v_pk_fma_f32 v[170:171], v[162:163], v[162:163], v[170:171]
	v_pk_fma_f32 v[172:173], v[164:165], v[164:165], v[172:173]
	v_lshlrev_b32_e32 v166, 16, v160
	v_and_b32_e32 v167, 0xffff0000, v160
	v_lshlrev_b32_e32 v168, 16, v161
	v_and_b32_e32 v169, 0xffff0000, v161
	v_pk_fma_f32 v[170:171], v[166:167], v[166:167], v[170:171]
	v_pk_fma_f32 v[172:173], v[168:169], v[168:169], v[172:173]
	v_pk_add_f32 v[170:171], v[170:171], v[172:173]
	s_nop 0
	v_add_f32_e32 v252, v170, v171
	s_waitcnt lgkmcnt(0)
	ds_bpermute_b32 v254, v246, v252
	s_waitcnt lgkmcnt(0)
	v_add_f32_e32 v252, v252, v254
	ds_bpermute_b32 v254, v247, v252
	s_waitcnt lgkmcnt(0)
	v_add_f32_e32 v252, v252, v254
	ds_bpermute_b32 v254, v248, v252
	s_waitcnt lgkmcnt(0)
	v_add_f32_e32 v252, v252, v254
	ds_bpermute_b32 v254, v249, v252
	s_waitcnt lgkmcnt(0)
	v_add_f32_e32 v252, v252, v254
	ds_bpermute_b32 v254, v250, v252
	s_waitcnt lgkmcnt(0)
	v_add_f32_e32 v252, v252, v254
	ds_bpermute_b32 v254, v251, v252
	s_waitcnt lgkmcnt(0)
	v_add_f32_e32 v252, v252, v254
	v_mov_b32_e32 v254, 0x358637bd
	v_fmac_f32_e32 v254, 0x39800000, v252
	v_mul_f32_e32 v252, 0x4b800000, v254
	v_cmp_gt_f32_e32 vcc, s32, v254
	s_nop 1
	v_cndmask_b32_e32 v254, v254, v252, vcc
	v_rsq_f32_e32 v254, v254
	s_nop 0
	v_mul_f32_e32 v252, 0x45800000, v254
	v_cndmask_b32_e32 v252, v254, v252, vcc
	ds_read_b128 v[226:229], v238 offset:1024
	ds_read_b128 v[230:233], v238 offset:33792
	s_waitcnt lgkmcnt(2)
	v_lshlrev_b32_e32 v162, 16, v130
	v_and_b32_e32 v163, 0xffff0000, v130
	v_lshlrev_b32_e32 v164, 16, v131
	v_and_b32_e32 v165, 0xffff0000, v131
	v_pk_mul_f32 v[162:163], v[162:163], v[252:253] op_sel_hi:[1,0]
	v_pk_mul_f32 v[164:165], v[164:165], v[252:253] op_sel_hi:[1,0]
	v_pk_mul_f32 v[162:163], v[162:163], v[214:215]
	v_pk_mul_f32 v[164:165], v[164:165], v[216:217]
	v_pk_fma_f32 v[66:67], v[218:219], v[162:163], v[66:67]
	v_pk_fma_f32 v[68:69], v[220:221], v[164:165], v[68:69]
	v_pk_mul_f32 v[170:171], v[66:67], v[66:67]
	v_pk_mul_f32 v[172:173], v[68:69], v[68:69]
	v_cvt_pk_bf16_f32 v166, v66, v67
	v_cvt_pk_bf16_f32 v167, v68, v69
	global_store_dwordx2 v244, v[166:167], s[22:23] offset:0
	ds_read_b128 v[214:217], v238 offset:2048
	ds_read_b128 v[218:221], v238 offset:34816
	s_waitcnt lgkmcnt(2)
	v_lshlrev_b32_e32 v162, 16, v132
	v_and_b32_e32 v163, 0xffff0000, v132
	v_lshlrev_b32_e32 v164, 16, v133
	v_and_b32_e32 v165, 0xffff0000, v133
	v_pk_mul_f32 v[162:163], v[162:163], v[252:253] op_sel_hi:[1,0]
	v_pk_mul_f32 v[164:165], v[164:165], v[252:253] op_sel_hi:[1,0]
	v_pk_mul_f32 v[162:163], v[162:163], v[226:227]
	v_pk_mul_f32 v[164:165], v[164:165], v[228:229]
	v_pk_fma_f32 v[70:71], v[230:231], v[162:163], v[70:71]
	v_pk_fma_f32 v[72:73], v[232:233], v[164:165], v[72:73]
	v_pk_fma_f32 v[170:171], v[70:71], v[70:71], v[170:171]
	v_pk_fma_f32 v[172:173], v[72:73], v[72:73], v[172:173]
	v_cvt_pk_bf16_f32 v168, v70, v71
	v_cvt_pk_bf16_f32 v169, v72, v73
	global_store_dwordx2 v244, v[168:169], s[22:23] offset:512
	ds_read_b128 v[226:229], v238 offset:3072
	ds_read_b128 v[230:233], v238 offset:35840
	s_waitcnt lgkmcnt(2)
	v_lshlrev_b32_e32 v162, 16, v134
	v_and_b32_e32 v163, 0xffff0000, v134
	v_lshlrev_b32_e32 v164, 16, v135
	v_and_b32_e32 v165, 0xffff0000, v135
	v_pk_mul_f32 v[162:163], v[162:163], v[252:253] op_sel_hi:[1,0]
	v_pk_mul_f32 v[164:165], v[164:165], v[252:253] op_sel_hi:[1,0]
	v_pk_mul_f32 v[162:163], v[162:163], v[214:215]
	v_pk_mul_f32 v[164:165], v[164:165], v[216:217]
	v_pk_fma_f32 v[74:75], v[218:219], v[162:163], v[74:75]
	v_pk_fma_f32 v[76:77], v[220:221], v[164:165], v[76:77]
	v_pk_fma_f32 v[170:171], v[74:75], v[74:75], v[170:171]
	v_pk_fma_f32 v[172:173], v[76:77], v[76:77], v[172:173]
	v_cvt_pk_bf16_f32 v166, v74, v75
	v_cvt_pk_bf16_f32 v167, v76, v77
	global_store_dwordx2 v244, v[166:167], s[22:23] offset:1024
	ds_read_b128 v[214:217], v238 offset:4096
	ds_read_b128 v[218:221], v238 offset:36864
	s_waitcnt lgkmcnt(2)
	v_lshlrev_b32_e32 v162, 16, v136
	v_and_b32_e32 v163, 0xffff0000, v136
	v_lshlrev_b32_e32 v164, 16, v137
	v_and_b32_e32 v165, 0xffff0000, v137
	v_pk_mul_f32 v[162:163], v[162:163], v[252:253] op_sel_hi:[1,0]
	v_pk_mul_f32 v[164:165], v[164:165], v[252:253] op_sel_hi:[1,0]
	v_pk_mul_f32 v[162:163], v[162:163], v[226:227]
	v_pk_mul_f32 v[164:165], v[164:165], v[228:229]
	v_pk_fma_f32 v[78:79], v[230:231], v[162:163], v[78:79]
	v_pk_fma_f32 v[80:81], v[232:233], v[164:165], v[80:81]
	v_pk_fma_f32 v[170:171], v[78:79], v[78:79], v[170:171]
	v_pk_fma_f32 v[172:173], v[80:81], v[80:81], v[172:173]
	v_cvt_pk_bf16_f32 v168, v78, v79
	v_cvt_pk_bf16_f32 v169, v80, v81
	global_store_dwordx2 v244, v[168:169], s[22:23] offset:1536
	ds_read_b128 v[226:229], v238 offset:5120
	ds_read_b128 v[230:233], v238 offset:37888
	s_waitcnt lgkmcnt(2)
	v_lshlrev_b32_e32 v162, 16, v138
	v_and_b32_e32 v163, 0xffff0000, v138
	v_lshlrev_b32_e32 v164, 16, v139
	v_and_b32_e32 v165, 0xffff0000, v139
	v_pk_mul_f32 v[162:163], v[162:163], v[252:253] op_sel_hi:[1,0]
	v_pk_mul_f32 v[164:165], v[164:165], v[252:253] op_sel_hi:[1,0]
	v_pk_mul_f32 v[162:163], v[162:163], v[214:215]
	v_pk_mul_f32 v[164:165], v[164:165], v[216:217]
	v_pk_fma_f32 v[82:83], v[218:219], v[162:163], v[82:83]
	v_pk_fma_f32 v[84:85], v[220:221], v[164:165], v[84:85]
	v_pk_fma_f32 v[170:171], v[82:83], v[82:83], v[170:171]
	v_pk_fma_f32 v[172:173], v[84:85], v[84:85], v[172:173]
	v_cvt_pk_bf16_f32 v166, v82, v83
	v_cvt_pk_bf16_f32 v167, v84, v85
	global_store_dwordx2 v244, v[166:167], s[22:23] offset:2048
	ds_read_b128 v[214:217], v238 offset:6144
	ds_read_b128 v[218:221], v238 offset:38912
	s_waitcnt lgkmcnt(2)
	v_lshlrev_b32_e32 v162, 16, v140
	v_and_b32_e32 v163, 0xffff0000, v140
	v_lshlrev_b32_e32 v164, 16, v141
	v_and_b32_e32 v165, 0xffff0000, v141
	v_pk_mul_f32 v[162:163], v[162:163], v[252:253] op_sel_hi:[1,0]
	v_pk_mul_f32 v[164:165], v[164:165], v[252:253] op_sel_hi:[1,0]
	v_pk_mul_f32 v[162:163], v[162:163], v[226:227]
	v_pk_mul_f32 v[164:165], v[164:165], v[228:229]
	v_pk_fma_f32 v[86:87], v[230:231], v[162:163], v[86:87]
	v_pk_fma_f32 v[88:89], v[232:233], v[164:165], v[88:89]
	v_pk_fma_f32 v[170:171], v[86:87], v[86:87], v[170:171]
	v_pk_fma_f32 v[172:173], v[88:89], v[88:89], v[172:173]
	v_cvt_pk_bf16_f32 v168, v86, v87
	v_cvt_pk_bf16_f32 v169, v88, v89
	global_store_dwordx2 v244, v[168:169], s[22:23] offset:2560
	ds_read_b128 v[226:229], v238 offset:7168
	ds_read_b128 v[230:233], v238 offset:39936
	s_waitcnt lgkmcnt(2)
	v_lshlrev_b32_e32 v162, 16, v142
	v_and_b32_e32 v163, 0xffff0000, v142
	v_lshlrev_b32_e32 v164, 16, v143
	v_and_b32_e32 v165, 0xffff0000, v143
	v_pk_mul_f32 v[162:163], v[162:163], v[252:253] op_sel_hi:[1,0]
	v_pk_mul_f32 v[164:165], v[164:165], v[252:253] op_sel_hi:[1,0]
	v_pk_mul_f32 v[162:163], v[162:163], v[214:215]
	v_pk_mul_f32 v[164:165], v[164:165], v[216:217]
	v_pk_fma_f32 v[90:91], v[218:219], v[162:163], v[90:91]
	v_pk_fma_f32 v[92:93], v[220:221], v[164:165], v[92:93]
	v_pk_fma_f32 v[170:171], v[90:91], v[90:91], v[170:171]
	v_pk_fma_f32 v[172:173], v[92:93], v[92:93], v[172:173]
	v_cvt_pk_bf16_f32 v166, v90, v91
	v_cvt_pk_bf16_f32 v167, v92, v93
	global_store_dwordx2 v244, v[166:167], s[22:23] offset:3072
	ds_read_b128 v[214:217], v238 offset:8192
	ds_read_b128 v[218:221], v238 offset:40960
	s_waitcnt lgkmcnt(2)
	v_lshlrev_b32_e32 v162, 16, v144
	v_and_b32_e32 v163, 0xffff0000, v144
	v_lshlrev_b32_e32 v164, 16, v145
	v_and_b32_e32 v165, 0xffff0000, v145
	v_pk_mul_f32 v[162:163], v[162:163], v[252:253] op_sel_hi:[1,0]
	v_pk_mul_f32 v[164:165], v[164:165], v[252:253] op_sel_hi:[1,0]
	v_pk_mul_f32 v[162:163], v[162:163], v[226:227]
	v_pk_mul_f32 v[164:165], v[164:165], v[228:229]
	v_pk_fma_f32 v[94:95], v[230:231], v[162:163], v[94:95]
	v_pk_fma_f32 v[96:97], v[232:233], v[164:165], v[96:97]
	v_pk_fma_f32 v[170:171], v[94:95], v[94:95], v[170:171]
	v_pk_fma_f32 v[172:173], v[96:97], v[96:97], v[172:173]
	v_cvt_pk_bf16_f32 v168, v94, v95
	v_cvt_pk_bf16_f32 v169, v96, v97
	global_store_dwordx2 v244, v[168:169], s[22:23] offset:3584
	ds_read_b128 v[226:229], v238 offset:9216
	ds_read_b128 v[230:233], v238 offset:41984
	s_waitcnt lgkmcnt(2)
	v_lshlrev_b32_e32 v162, 16, v146
	v_and_b32_e32 v163, 0xffff0000, v146
	v_lshlrev_b32_e32 v164, 16, v147
	v_and_b32_e32 v165, 0xffff0000, v147
	v_pk_mul_f32 v[162:163], v[162:163], v[252:253] op_sel_hi:[1,0]
	v_pk_mul_f32 v[164:165], v[164:165], v[252:253] op_sel_hi:[1,0]
	v_pk_mul_f32 v[162:163], v[162:163], v[214:215]
	v_pk_mul_f32 v[164:165], v[164:165], v[216:217]
	v_pk_fma_f32 v[98:99], v[218:219], v[162:163], v[98:99]
	v_pk_fma_f32 v[100:101], v[220:221], v[164:165], v[100:101]
	v_pk_fma_f32 v[170:171], v[98:99], v[98:99], v[170:171]
	v_pk_fma_f32 v[172:173], v[100:101], v[100:101], v[172:173]
	v_cvt_pk_bf16_f32 v166, v98, v99
	v_cvt_pk_bf16_f32 v167, v100, v101
	global_store_dwordx2 v245, v[166:167], s[22:23] offset:0
	ds_read_b128 v[214:217], v238 offset:10240
	ds_read_b128 v[218:221], v238 offset:43008
	s_waitcnt lgkmcnt(2)
	v_lshlrev_b32_e32 v162, 16, v148
	v_and_b32_e32 v163, 0xffff0000, v148
	v_lshlrev_b32_e32 v164, 16, v149
	v_and_b32_e32 v165, 0xffff0000, v149
	v_pk_mul_f32 v[162:163], v[162:163], v[252:253] op_sel_hi:[1,0]
	v_pk_mul_f32 v[164:165], v[164:165], v[252:253] op_sel_hi:[1,0]
	v_pk_mul_f32 v[162:163], v[162:163], v[226:227]
	v_pk_mul_f32 v[164:165], v[164:165], v[228:229]
	v_pk_fma_f32 v[102:103], v[230:231], v[162:163], v[102:103]
	v_pk_fma_f32 v[104:105], v[232:233], v[164:165], v[104:105]
	v_pk_fma_f32 v[170:171], v[102:103], v[102:103], v[170:171]
	v_pk_fma_f32 v[172:173], v[104:105], v[104:105], v[172:173]
	v_cvt_pk_bf16_f32 v168, v102, v103
	v_cvt_pk_bf16_f32 v169, v104, v105
	global_store_dwordx2 v245, v[168:169], s[22:23] offset:512
	ds_read_b128 v[226:229], v238 offset:11264
	ds_read_b128 v[230:233], v238 offset:44032
	s_waitcnt lgkmcnt(2)
	v_lshlrev_b32_e32 v162, 16, v150
	v_and_b32_e32 v163, 0xffff0000, v150
	v_lshlrev_b32_e32 v164, 16, v151
	v_and_b32_e32 v165, 0xffff0000, v151
	v_pk_mul_f32 v[162:163], v[162:163], v[252:253] op_sel_hi:[1,0]
	v_pk_mul_f32 v[164:165], v[164:165], v[252:253] op_sel_hi:[1,0]
	v_pk_mul_f32 v[162:163], v[162:163], v[214:215]
	v_pk_mul_f32 v[164:165], v[164:165], v[216:217]
	v_pk_fma_f32 v[106:107], v[218:219], v[162:163], v[106:107]
	v_pk_fma_f32 v[108:109], v[220:221], v[164:165], v[108:109]
	v_pk_fma_f32 v[170:171], v[106:107], v[106:107], v[170:171]
	v_pk_fma_f32 v[172:173], v[108:109], v[108:109], v[172:173]
	v_cvt_pk_bf16_f32 v166, v106, v107
	v_cvt_pk_bf16_f32 v167, v108, v109
	global_store_dwordx2 v245, v[166:167], s[22:23] offset:1024
	ds_read_b128 v[214:217], v238 offset:12288
	ds_read_b128 v[218:221], v238 offset:45056
	s_waitcnt lgkmcnt(2)
	v_lshlrev_b32_e32 v162, 16, v152
	v_and_b32_e32 v163, 0xffff0000, v152
	v_lshlrev_b32_e32 v164, 16, v153
	v_and_b32_e32 v165, 0xffff0000, v153
	v_pk_mul_f32 v[162:163], v[162:163], v[252:253] op_sel_hi:[1,0]
	v_pk_mul_f32 v[164:165], v[164:165], v[252:253] op_sel_hi:[1,0]
	v_pk_mul_f32 v[162:163], v[162:163], v[226:227]
	v_pk_mul_f32 v[164:165], v[164:165], v[228:229]
	v_pk_fma_f32 v[110:111], v[230:231], v[162:163], v[110:111]
	v_pk_fma_f32 v[112:113], v[232:233], v[164:165], v[112:113]
	v_pk_fma_f32 v[170:171], v[110:111], v[110:111], v[170:171]
	v_pk_fma_f32 v[172:173], v[112:113], v[112:113], v[172:173]
	v_cvt_pk_bf16_f32 v168, v110, v111
	v_cvt_pk_bf16_f32 v169, v112, v113
	global_store_dwordx2 v245, v[168:169], s[22:23] offset:1536
	ds_read_b128 v[226:229], v238 offset:13312
	ds_read_b128 v[230:233], v238 offset:46080
	s_waitcnt lgkmcnt(2)
	v_lshlrev_b32_e32 v162, 16, v154
	v_and_b32_e32 v163, 0xffff0000, v154
	v_lshlrev_b32_e32 v164, 16, v155
	v_and_b32_e32 v165, 0xffff0000, v155
	v_pk_mul_f32 v[162:163], v[162:163], v[252:253] op_sel_hi:[1,0]
	v_pk_mul_f32 v[164:165], v[164:165], v[252:253] op_sel_hi:[1,0]
	v_pk_mul_f32 v[162:163], v[162:163], v[214:215]
	v_pk_mul_f32 v[164:165], v[164:165], v[216:217]
	v_pk_fma_f32 v[114:115], v[218:219], v[162:163], v[114:115]
	v_pk_fma_f32 v[116:117], v[220:221], v[164:165], v[116:117]
	v_pk_fma_f32 v[170:171], v[114:115], v[114:115], v[170:171]
	v_pk_fma_f32 v[172:173], v[116:117], v[116:117], v[172:173]
	v_cvt_pk_bf16_f32 v166, v114, v115
	v_cvt_pk_bf16_f32 v167, v116, v117
	global_store_dwordx2 v245, v[166:167], s[22:23] offset:2048
	ds_read_b128 v[214:217], v238 offset:14336
	ds_read_b128 v[218:221], v238 offset:47104
	s_waitcnt lgkmcnt(2)
	v_lshlrev_b32_e32 v162, 16, v156
	v_and_b32_e32 v163, 0xffff0000, v156
	v_lshlrev_b32_e32 v164, 16, v157
	v_and_b32_e32 v165, 0xffff0000, v157
	v_pk_mul_f32 v[162:163], v[162:163], v[252:253] op_sel_hi:[1,0]
	v_pk_mul_f32 v[164:165], v[164:165], v[252:253] op_sel_hi:[1,0]
	v_pk_mul_f32 v[162:163], v[162:163], v[226:227]
	v_pk_mul_f32 v[164:165], v[164:165], v[228:229]
	v_pk_fma_f32 v[118:119], v[230:231], v[162:163], v[118:119]
	v_pk_fma_f32 v[120:121], v[232:233], v[164:165], v[120:121]
	v_pk_fma_f32 v[170:171], v[118:119], v[118:119], v[170:171]
	v_pk_fma_f32 v[172:173], v[120:121], v[120:121], v[172:173]
	v_cvt_pk_bf16_f32 v168, v118, v119
	v_cvt_pk_bf16_f32 v169, v120, v121
	global_store_dwordx2 v245, v[168:169], s[22:23] offset:2560
	ds_read_b128 v[226:229], v238 offset:15360
	ds_read_b128 v[230:233], v238 offset:48128
	s_waitcnt lgkmcnt(2)
	v_lshlrev_b32_e32 v162, 16, v158
	v_and_b32_e32 v163, 0xffff0000, v158
	v_lshlrev_b32_e32 v164, 16, v159
	v_and_b32_e32 v165, 0xffff0000, v159
	v_pk_mul_f32 v[162:163], v[162:163], v[252:253] op_sel_hi:[1,0]
	v_pk_mul_f32 v[164:165], v[164:165], v[252:253] op_sel_hi:[1,0]
	v_pk_mul_f32 v[162:163], v[162:163], v[214:215]
	v_pk_mul_f32 v[164:165], v[164:165], v[216:217]
	v_pk_fma_f32 v[122:123], v[218:219], v[162:163], v[122:123]
	v_pk_fma_f32 v[124:125], v[220:221], v[164:165], v[124:125]
	v_pk_fma_f32 v[170:171], v[122:123], v[122:123], v[170:171]
	v_pk_fma_f32 v[172:173], v[124:125], v[124:125], v[172:173]
	v_cvt_pk_bf16_f32 v166, v122, v123
	v_cvt_pk_bf16_f32 v167, v124, v125
	global_store_dwordx2 v245, v[166:167], s[22:23] offset:3072
	s_waitcnt lgkmcnt(0)
	v_lshlrev_b32_e32 v162, 16, v160
	v_and_b32_e32 v163, 0xffff0000, v160
	v_lshlrev_b32_e32 v164, 16, v161
	v_and_b32_e32 v165, 0xffff0000, v161
	v_pk_mul_f32 v[162:163], v[162:163], v[252:253] op_sel_hi:[1,0]
	v_pk_mul_f32 v[164:165], v[164:165], v[252:253] op_sel_hi:[1,0]
	v_pk_mul_f32 v[162:163], v[162:163], v[226:227]
	v_pk_mul_f32 v[164:165], v[164:165], v[228:229]
	v_pk_fma_f32 v[126:127], v[230:231], v[162:163], v[126:127]
	v_pk_fma_f32 v[128:129], v[232:233], v[164:165], v[128:129]
	v_pk_fma_f32 v[170:171], v[126:127], v[126:127], v[170:171]
	v_pk_fma_f32 v[172:173], v[128:129], v[128:129], v[172:173]
	v_cvt_pk_bf16_f32 v168, v126, v127
	v_cvt_pk_bf16_f32 v169, v128, v129
	global_store_dwordx2 v245, v[168:169], s[22:23] offset:3584
	ds_read_b128 v[214:217], v238 offset:16384
	ds_read_b128 v[218:221], v238 offset:49152
	ds_read_b128 v[222:225], v239 offset:0
	v_pk_add_f32 v[170:171], v[170:171], v[172:173]
	s_nop 0
	v_add_f32_e32 v252, v170, v171
	s_waitcnt lgkmcnt(0)
	ds_bpermute_b32 v254, v246, v252
	s_waitcnt lgkmcnt(0)
	v_add_f32_e32 v252, v252, v254
	ds_bpermute_b32 v254, v247, v252
	s_waitcnt lgkmcnt(0)
	v_add_f32_e32 v252, v252, v254
	ds_bpermute_b32 v254, v248, v252
	s_waitcnt lgkmcnt(0)
	v_add_f32_e32 v252, v252, v254
	ds_bpermute_b32 v254, v249, v252
	s_waitcnt lgkmcnt(0)
	v_add_f32_e32 v252, v252, v254
	ds_bpermute_b32 v254, v250, v252
	s_waitcnt lgkmcnt(0)
	v_add_f32_e32 v252, v252, v254
	ds_bpermute_b32 v254, v251, v252
	s_waitcnt lgkmcnt(0)
	v_add_f32_e32 v252, v252, v254
	v_mov_b32_e32 v254, 0x358637bd
	v_fmac_f32_e32 v254, 0x39800000, v252
	v_mul_f32_e32 v252, 0x4b800000, v254
	v_cmp_gt_f32_e32 vcc, s32, v254
	s_nop 1
	v_cndmask_b32_e32 v254, v254, v252, vcc
	v_rsq_f32_e32 v254, v254
	s_nop 0
	v_mul_f32_e32 v252, 0x45800000, v254
	v_cndmask_b32_e32 v252, v254, v252, vcc
	s_add_u32 s16, s16, 0x1000000
	s_addc_u32 s17, s17, 0
	global_load_dwordx2 v[130:131], v244, s[16:17] offset:0
	global_load_dwordx2 v[132:133], v244, s[16:17] offset:512
	global_load_dwordx2 v[134:135], v244, s[16:17] offset:1024
	global_load_dwordx2 v[136:137], v244, s[16:17] offset:1536
	global_load_dwordx2 v[138:139], v244, s[16:17] offset:2048
	global_load_dwordx2 v[140:141], v244, s[16:17] offset:2560
	global_load_dwordx2 v[142:143], v244, s[16:17] offset:3072
	global_load_dwordx2 v[144:145], v244, s[16:17] offset:3584
	global_load_dwordx2 v[146:147], v245, s[16:17] offset:0
	global_load_dwordx2 v[148:149], v245, s[16:17] offset:512
	global_load_dwordx2 v[150:151], v245, s[16:17] offset:1024
	global_load_dwordx2 v[152:153], v245, s[16:17] offset:1536
	global_load_dwordx2 v[154:155], v245, s[16:17] offset:2048
	global_load_dwordx2 v[156:157], v245, s[16:17] offset:2560
	global_load_dwordx2 v[158:159], v245, s[16:17] offset:3072
	global_load_dwordx2 v[160:161], v245, s[16:17] offset:3584
	ds_read_b128 v[226:229], v238 offset:17408
	ds_read_b128 v[230:233], v238 offset:50176
	ds_read_b128 v[234:237], v239 offset:1024
	s_waitcnt lgkmcnt(3)
	v_pk_mul_f32 v[66:67], v[66:67], v[252:253] op_sel_hi:[1,0]
	v_pk_mul_f32 v[68:69], v[68:69], v[252:253] op_sel_hi:[1,0]
	v_pk_mul_f32 v[66:67], v[66:67], v[214:215]
	v_pk_mul_f32 v[68:69], v[68:69], v[216:217]
	v_pk_add_f32 v[222:223], v[222:223], 1.0 op_sel_hi:[1,0]
	v_pk_add_f32 v[224:225], v[224:225], 1.0 op_sel_hi:[1,0]
	v_pk_fma_f32 v[66:67], v[66:67], v[222:223], v[218:219]
	v_pk_fma_f32 v[68:69], v[68:69], v[224:225], v[220:221]
	s_nop 0
	v_cvt_pk_bf16_f32 v66, v66, v67
	v_cvt_pk_bf16_f32 v67, v68, v69
	global_store_dwordx2 v244, v[66:67], s[38:39] offset:0
	ds_read_b128 v[214:217], v238 offset:18432
	ds_read_b128 v[218:221], v238 offset:51200
	ds_read_b128 v[222:225], v239 offset:2048
	s_waitcnt lgkmcnt(3)
	v_pk_mul_f32 v[70:71], v[70:71], v[252:253] op_sel_hi:[1,0]
	v_pk_mul_f32 v[72:73], v[72:73], v[252:253] op_sel_hi:[1,0]
	v_pk_mul_f32 v[70:71], v[70:71], v[226:227]
	v_pk_mul_f32 v[72:73], v[72:73], v[228:229]
	v_pk_add_f32 v[234:235], v[234:235], 1.0 op_sel_hi:[1,0]
	v_pk_add_f32 v[236:237], v[236:237], 1.0 op_sel_hi:[1,0]
	v_pk_fma_f32 v[70:71], v[70:71], v[234:235], v[230:231]
	v_pk_fma_f32 v[72:73], v[72:73], v[236:237], v[232:233]
	s_nop 0
	v_cvt_pk_bf16_f32 v70, v70, v71
	v_cvt_pk_bf16_f32 v71, v72, v73
	global_store_dwordx2 v244, v[70:71], s[38:39] offset:512
	ds_read_b128 v[226:229], v238 offset:19456
	ds_read_b128 v[230:233], v238 offset:52224
	ds_read_b128 v[234:237], v239 offset:3072
	s_waitcnt lgkmcnt(3)
	v_pk_mul_f32 v[74:75], v[74:75], v[252:253] op_sel_hi:[1,0]
	v_pk_mul_f32 v[76:77], v[76:77], v[252:253] op_sel_hi:[1,0]
	v_pk_mul_f32 v[74:75], v[74:75], v[214:215]
	v_pk_mul_f32 v[76:77], v[76:77], v[216:217]
	v_pk_add_f32 v[222:223], v[222:223], 1.0 op_sel_hi:[1,0]
	v_pk_add_f32 v[224:225], v[224:225], 1.0 op_sel_hi:[1,0]
	v_pk_fma_f32 v[74:75], v[74:75], v[222:223], v[218:219]
	v_pk_fma_f32 v[76:77], v[76:77], v[224:225], v[220:221]
	s_nop 0
	v_cvt_pk_bf16_f32 v74, v74, v75
	v_cvt_pk_bf16_f32 v75, v76, v77
	global_store_dwordx2 v244, v[74:75], s[38:39] offset:1024
	ds_read_b128 v[214:217], v238 offset:20480
	ds_read_b128 v[218:221], v238 offset:53248
	ds_read_b128 v[222:225], v239 offset:4096
	s_waitcnt lgkmcnt(3)
	v_pk_mul_f32 v[78:79], v[78:79], v[252:253] op_sel_hi:[1,0]
	v_pk_mul_f32 v[80:81], v[80:81], v[252:253] op_sel_hi:[1,0]
	v_pk_mul_f32 v[78:79], v[78:79], v[226:227]
	v_pk_mul_f32 v[80:81], v[80:81], v[228:229]
	v_pk_add_f32 v[234:235], v[234:235], 1.0 op_sel_hi:[1,0]
	v_pk_add_f32 v[236:237], v[236:237], 1.0 op_sel_hi:[1,0]
	v_pk_fma_f32 v[78:79], v[78:79], v[234:235], v[230:231]
	v_pk_fma_f32 v[80:81], v[80:81], v[236:237], v[232:233]
	s_nop 0
	v_cvt_pk_bf16_f32 v78, v78, v79
	v_cvt_pk_bf16_f32 v79, v80, v81
	global_store_dwordx2 v244, v[78:79], s[38:39] offset:1536
	ds_read_b128 v[226:229], v238 offset:21504
	ds_read_b128 v[230:233], v238 offset:54272
	ds_read_b128 v[234:237], v239 offset:5120
	s_waitcnt lgkmcnt(3)
	v_pk_mul_f32 v[82:83], v[82:83], v[252:253] op_sel_hi:[1,0]
	v_pk_mul_f32 v[84:85], v[84:85], v[252:253] op_sel_hi:[1,0]
	v_pk_mul_f32 v[82:83], v[82:83], v[214:215]
	v_pk_mul_f32 v[84:85], v[84:85], v[216:217]
	v_pk_add_f32 v[222:223], v[222:223], 1.0 op_sel_hi:[1,0]
	v_pk_add_f32 v[224:225], v[224:225], 1.0 op_sel_hi:[1,0]
	v_pk_fma_f32 v[82:83], v[82:83], v[222:223], v[218:219]
	v_pk_fma_f32 v[84:85], v[84:85], v[224:225], v[220:221]
	s_nop 0
	v_cvt_pk_bf16_f32 v82, v82, v83
	v_cvt_pk_bf16_f32 v83, v84, v85
	global_store_dwordx2 v244, v[82:83], s[38:39] offset:2048
	ds_read_b128 v[214:217], v238 offset:22528
	ds_read_b128 v[218:221], v238 offset:55296
	ds_read_b128 v[222:225], v239 offset:6144
	s_waitcnt lgkmcnt(3)
	v_pk_mul_f32 v[86:87], v[86:87], v[252:253] op_sel_hi:[1,0]
	v_pk_mul_f32 v[88:89], v[88:89], v[252:253] op_sel_hi:[1,0]
	v_pk_mul_f32 v[86:87], v[86:87], v[226:227]
	v_pk_mul_f32 v[88:89], v[88:89], v[228:229]
	v_pk_add_f32 v[234:235], v[234:235], 1.0 op_sel_hi:[1,0]
	v_pk_add_f32 v[236:237], v[236:237], 1.0 op_sel_hi:[1,0]
	v_pk_fma_f32 v[86:87], v[86:87], v[234:235], v[230:231]
	v_pk_fma_f32 v[88:89], v[88:89], v[236:237], v[232:233]
	s_nop 0
	v_cvt_pk_bf16_f32 v86, v86, v87
	v_cvt_pk_bf16_f32 v87, v88, v89
	global_store_dwordx2 v244, v[86:87], s[38:39] offset:2560
	ds_read_b128 v[226:229], v238 offset:23552
	ds_read_b128 v[230:233], v238 offset:56320
	ds_read_b128 v[234:237], v239 offset:7168
	s_waitcnt lgkmcnt(3)
	v_pk_mul_f32 v[90:91], v[90:91], v[252:253] op_sel_hi:[1,0]
	v_pk_mul_f32 v[92:93], v[92:93], v[252:253] op_sel_hi:[1,0]
	v_pk_mul_f32 v[90:91], v[90:91], v[214:215]
	v_pk_mul_f32 v[92:93], v[92:93], v[216:217]
	v_pk_add_f32 v[222:223], v[222:223], 1.0 op_sel_hi:[1,0]
	v_pk_add_f32 v[224:225], v[224:225], 1.0 op_sel_hi:[1,0]
	v_pk_fma_f32 v[90:91], v[90:91], v[222:223], v[218:219]
	v_pk_fma_f32 v[92:93], v[92:93], v[224:225], v[220:221]
	s_nop 0
	v_cvt_pk_bf16_f32 v90, v90, v91
	v_cvt_pk_bf16_f32 v91, v92, v93
	global_store_dwordx2 v244, v[90:91], s[38:39] offset:3072
	ds_read_b128 v[214:217], v238 offset:24576
	ds_read_b128 v[218:221], v238 offset:57344
	ds_read_b128 v[222:225], v239 offset:8192
	s_waitcnt lgkmcnt(3)
	v_pk_mul_f32 v[94:95], v[94:95], v[252:253] op_sel_hi:[1,0]
	v_pk_mul_f32 v[96:97], v[96:97], v[252:253] op_sel_hi:[1,0]
	v_pk_mul_f32 v[94:95], v[94:95], v[226:227]
	v_pk_mul_f32 v[96:97], v[96:97], v[228:229]
	v_pk_add_f32 v[234:235], v[234:235], 1.0 op_sel_hi:[1,0]
	v_pk_add_f32 v[236:237], v[236:237], 1.0 op_sel_hi:[1,0]
	v_pk_fma_f32 v[94:95], v[94:95], v[234:235], v[230:231]
	v_pk_fma_f32 v[96:97], v[96:97], v[236:237], v[232:233]
	s_nop 0
	v_cvt_pk_bf16_f32 v94, v94, v95
	v_cvt_pk_bf16_f32 v95, v96, v97
	global_store_dwordx2 v244, v[94:95], s[38:39] offset:3584
	ds_read_b128 v[226:229], v238 offset:25600
	ds_read_b128 v[230:233], v238 offset:58368
	ds_read_b128 v[234:237], v239 offset:9216
	s_waitcnt lgkmcnt(3)
	v_pk_mul_f32 v[98:99], v[98:99], v[252:253] op_sel_hi:[1,0]
	v_pk_mul_f32 v[100:101], v[100:101], v[252:253] op_sel_hi:[1,0]
	v_pk_mul_f32 v[98:99], v[98:99], v[214:215]
	v_pk_mul_f32 v[100:101], v[100:101], v[216:217]
	v_pk_add_f32 v[222:223], v[222:223], 1.0 op_sel_hi:[1,0]
	v_pk_add_f32 v[224:225], v[224:225], 1.0 op_sel_hi:[1,0]
	v_pk_fma_f32 v[98:99], v[98:99], v[222:223], v[218:219]
	v_pk_fma_f32 v[100:101], v[100:101], v[224:225], v[220:221]
	s_nop 0
	v_cvt_pk_bf16_f32 v98, v98, v99
	v_cvt_pk_bf16_f32 v99, v100, v101
	global_store_dwordx2 v245, v[98:99], s[38:39] offset:0
	ds_read_b128 v[214:217], v238 offset:26624
	ds_read_b128 v[218:221], v238 offset:59392
	ds_read_b128 v[222:225], v239 offset:10240
	s_waitcnt lgkmcnt(3)
	v_pk_mul_f32 v[102:103], v[102:103], v[252:253] op_sel_hi:[1,0]
	v_pk_mul_f32 v[104:105], v[104:105], v[252:253] op_sel_hi:[1,0]
	v_pk_mul_f32 v[102:103], v[102:103], v[226:227]
	v_pk_mul_f32 v[104:105], v[104:105], v[228:229]
	v_pk_add_f32 v[234:235], v[234:235], 1.0 op_sel_hi:[1,0]
	v_pk_add_f32 v[236:237], v[236:237], 1.0 op_sel_hi:[1,0]
	v_pk_fma_f32 v[102:103], v[102:103], v[234:235], v[230:231]
	v_pk_fma_f32 v[104:105], v[104:105], v[236:237], v[232:233]
	s_nop 0
	v_cvt_pk_bf16_f32 v102, v102, v103
	v_cvt_pk_bf16_f32 v103, v104, v105
	global_store_dwordx2 v245, v[102:103], s[38:39] offset:512
	ds_read_b128 v[226:229], v238 offset:27648
	ds_read_b128 v[230:233], v238 offset:60416
	ds_read_b128 v[234:237], v239 offset:11264
	s_waitcnt lgkmcnt(3)
	v_pk_mul_f32 v[106:107], v[106:107], v[252:253] op_sel_hi:[1,0]
	v_pk_mul_f32 v[108:109], v[108:109], v[252:253] op_sel_hi:[1,0]
	v_pk_mul_f32 v[106:107], v[106:107], v[214:215]
	v_pk_mul_f32 v[108:109], v[108:109], v[216:217]
	v_pk_add_f32 v[222:223], v[222:223], 1.0 op_sel_hi:[1,0]
	v_pk_add_f32 v[224:225], v[224:225], 1.0 op_sel_hi:[1,0]
	v_pk_fma_f32 v[106:107], v[106:107], v[222:223], v[218:219]
	v_pk_fma_f32 v[108:109], v[108:109], v[224:225], v[220:221]
	s_nop 0
	v_cvt_pk_bf16_f32 v106, v106, v107
	v_cvt_pk_bf16_f32 v107, v108, v109
	global_store_dwordx2 v245, v[106:107], s[38:39] offset:1024
	ds_read_b128 v[214:217], v238 offset:28672
	ds_read_b128 v[218:221], v238 offset:61440
	ds_read_b128 v[222:225], v239 offset:12288
	s_waitcnt lgkmcnt(3)
	v_pk_mul_f32 v[110:111], v[110:111], v[252:253] op_sel_hi:[1,0]
	v_pk_mul_f32 v[112:113], v[112:113], v[252:253] op_sel_hi:[1,0]
	v_pk_mul_f32 v[110:111], v[110:111], v[226:227]
	v_pk_mul_f32 v[112:113], v[112:113], v[228:229]
	v_pk_add_f32 v[234:235], v[234:235], 1.0 op_sel_hi:[1,0]
	v_pk_add_f32 v[236:237], v[236:237], 1.0 op_sel_hi:[1,0]
	v_pk_fma_f32 v[110:111], v[110:111], v[234:235], v[230:231]
	v_pk_fma_f32 v[112:113], v[112:113], v[236:237], v[232:233]
	s_nop 0
	v_cvt_pk_bf16_f32 v110, v110, v111
	v_cvt_pk_bf16_f32 v111, v112, v113
	global_store_dwordx2 v245, v[110:111], s[38:39] offset:1536
	ds_read_b128 v[226:229], v238 offset:29696
	ds_read_b128 v[230:233], v238 offset:62464
	ds_read_b128 v[234:237], v239 offset:13312
	s_waitcnt lgkmcnt(3)
	v_pk_mul_f32 v[114:115], v[114:115], v[252:253] op_sel_hi:[1,0]
	v_pk_mul_f32 v[116:117], v[116:117], v[252:253] op_sel_hi:[1,0]
	v_pk_mul_f32 v[114:115], v[114:115], v[214:215]
	v_pk_mul_f32 v[116:117], v[116:117], v[216:217]
	v_pk_add_f32 v[222:223], v[222:223], 1.0 op_sel_hi:[1,0]
	v_pk_add_f32 v[224:225], v[224:225], 1.0 op_sel_hi:[1,0]
	v_pk_fma_f32 v[114:115], v[114:115], v[222:223], v[218:219]
	v_pk_fma_f32 v[116:117], v[116:117], v[224:225], v[220:221]
	s_nop 0
	v_cvt_pk_bf16_f32 v114, v114, v115
	v_cvt_pk_bf16_f32 v115, v116, v117
	global_store_dwordx2 v245, v[114:115], s[38:39] offset:2048
	ds_read_b128 v[214:217], v238 offset:30720
	ds_read_b128 v[218:221], v238 offset:63488
	ds_read_b128 v[222:225], v239 offset:14336
	s_waitcnt lgkmcnt(3)
	v_pk_mul_f32 v[118:119], v[118:119], v[252:253] op_sel_hi:[1,0]
	v_pk_mul_f32 v[120:121], v[120:121], v[252:253] op_sel_hi:[1,0]
	v_pk_mul_f32 v[118:119], v[118:119], v[226:227]
	v_pk_mul_f32 v[120:121], v[120:121], v[228:229]
	v_pk_add_f32 v[234:235], v[234:235], 1.0 op_sel_hi:[1,0]
	v_pk_add_f32 v[236:237], v[236:237], 1.0 op_sel_hi:[1,0]
	v_pk_fma_f32 v[118:119], v[118:119], v[234:235], v[230:231]
	v_pk_fma_f32 v[120:121], v[120:121], v[236:237], v[232:233]
	s_nop 0
	v_cvt_pk_bf16_f32 v118, v118, v119
	v_cvt_pk_bf16_f32 v119, v120, v121
	global_store_dwordx2 v245, v[118:119], s[38:39] offset:2560
	ds_read_b128 v[226:229], v238 offset:31744
	ds_read_b128 v[230:233], v238 offset:64512
	ds_read_b128 v[234:237], v239 offset:15360
	s_waitcnt lgkmcnt(3)
	v_pk_mul_f32 v[122:123], v[122:123], v[252:253] op_sel_hi:[1,0]
	v_pk_mul_f32 v[124:125], v[124:125], v[252:253] op_sel_hi:[1,0]
	v_pk_mul_f32 v[122:123], v[122:123], v[214:215]
	v_pk_mul_f32 v[124:125], v[124:125], v[216:217]
	v_pk_add_f32 v[222:223], v[222:223], 1.0 op_sel_hi:[1,0]
	v_pk_add_f32 v[224:225], v[224:225], 1.0 op_sel_hi:[1,0]
	v_pk_fma_f32 v[122:123], v[122:123], v[222:223], v[218:219]
	v_pk_fma_f32 v[124:125], v[124:125], v[224:225], v[220:221]
	s_nop 0
	v_cvt_pk_bf16_f32 v122, v122, v123
	v_cvt_pk_bf16_f32 v123, v124, v125
	global_store_dwordx2 v245, v[122:123], s[38:39] offset:3072
	s_waitcnt lgkmcnt(0)
	v_pk_mul_f32 v[126:127], v[126:127], v[252:253] op_sel_hi:[1,0]
	v_pk_mul_f32 v[128:129], v[128:129], v[252:253] op_sel_hi:[1,0]
	v_pk_mul_f32 v[126:127], v[126:127], v[226:227]
	v_pk_mul_f32 v[128:129], v[128:129], v[228:229]
	v_pk_add_f32 v[234:235], v[234:235], 1.0 op_sel_hi:[1,0]
	v_pk_add_f32 v[236:237], v[236:237], 1.0 op_sel_hi:[1,0]
	v_pk_fma_f32 v[126:127], v[126:127], v[234:235], v[230:231]
	v_pk_fma_f32 v[128:129], v[128:129], v[236:237], v[232:233]
	s_nop 0
	v_cvt_pk_bf16_f32 v126, v126, v127
	v_cvt_pk_bf16_f32 v127, v128, v129
	global_store_dwordx2 v245, v[126:127], s[38:39] offset:3584
	s_add_u32 s22, s22, 0x1000000
	s_addc_u32 s23, s23, 0
	s_add_u32 s38, s38, 0x1000000
	s_addc_u32 s39, s39, 0
	s_waitcnt vmcnt(16)
	s_barrier
	s_add_u32 s44, s44, 0x2000000
	s_addc_u32 s45, s45, 0
	global_load_dwordx4 v[66:69], v238, s[44:45] offset:0
	global_load_dwordx4 v[70:73], v238, s[44:45] offset:1024
	global_load_dwordx4 v[74:77], v238, s[44:45] offset:2048
	global_load_dwordx4 v[78:81], v238, s[44:45] offset:3072
	global_load_dwordx4 v[82:85], v241, s[44:45] offset:0
	global_load_dwordx4 v[86:89], v241, s[44:45] offset:1024
	global_load_dwordx4 v[90:93], v241, s[44:45] offset:2048
	global_load_dwordx4 v[94:97], v241, s[44:45] offset:3072
	global_load_dwordx4 v[98:101], v242, s[44:45] offset:0
	global_load_dwordx4 v[102:105], v242, s[44:45] offset:1024
	global_load_dwordx4 v[106:109], v242, s[44:45] offset:2048
	global_load_dwordx4 v[110:113], v242, s[44:45] offset:3072
	global_load_dwordx4 v[114:117], v243, s[44:45] offset:0
	global_load_dwordx4 v[118:121], v243, s[44:45] offset:1024
	global_load_dwordx4 v[122:125], v243, s[44:45] offset:2048
	global_load_dwordx4 v[126:129], v243, s[44:45] offset:3072
	s_add_i32 s9, s3, 3
	s_mul_i32 s9, s9, 0x18000
	s_add_u32 s10, s28, s9
	s_addc_u32 s11, s29, 0
	s_add_u32 s12, s10, 0x8000
	s_addc_u32 s13, s11, 0
	s_add_u32 s8, s7, 0x8000
	s_mov_b32 m0, s8
	s_nop 0
	global_load_lds_dwordx4 v240, s[12:13]
	global_load_lds_dwordx4 v240, s[12:13] offset:1024
	s_add_u32 s12, s10, 0xc000
	s_addc_u32 s13, s11, 0
	s_add_u32 s8, s7, 0xc000
	s_mov_b32 m0, s8
	s_nop 0
	global_load_lds_dwordx4 v240, s[12:13]
	global_load_lds_dwordx4 v240, s[12:13] offset:1024
	s_add_u32 s12, s10, 0x10000
	s_addc_u32 s13, s11, 0
	s_add_u32 s8, s7, 0x10000
	s_mov_b32 m0, s8
	s_nop 0
	global_load_lds_dwordx4 v240, s[12:13]
	global_load_lds_dwordx4 v240, s[12:13] offset:1024
	ds_read_b128 v[214:217], v238 offset:0
	ds_read_b128 v[218:221], v239 offset:16384
	v_lshlrev_b32_e32 v162, 16, v130
	v_and_b32_e32 v163, 0xffff0000, v130
	v_lshlrev_b32_e32 v164, 16, v131
	v_and_b32_e32 v165, 0xffff0000, v131
	v_pk_mul_f32 v[170:171], v[162:163], v[162:163]
	v_pk_mul_f32 v[172:173], v[164:165], v[164:165]
	v_lshlrev_b32_e32 v166, 16, v132
	v_and_b32_e32 v167, 0xffff0000, v132
	v_lshlrev_b32_e32 v168, 16, v133
	v_and_b32_e32 v169, 0xffff0000, v133
	v_pk_fma_f32 v[170:171], v[166:167], v[166:167], v[170:171]
	v_pk_fma_f32 v[172:173], v[168:169], v[168:169], v[172:173]
	v_lshlrev_b32_e32 v162, 16, v134
	v_and_b32_e32 v163, 0xffff0000, v134
	v_lshlrev_b32_e32 v164, 16, v135
	v_and_b32_e32 v165, 0xffff0000, v135
	v_pk_fma_f32 v[170:171], v[162:163], v[162:163], v[170:171]
	v_pk_fma_f32 v[172:173], v[164:165], v[164:165], v[172:173]
	v_lshlrev_b32_e32 v166, 16, v136
	v_and_b32_e32 v167, 0xffff0000, v136
	v_lshlrev_b32_e32 v168, 16, v137
	v_and_b32_e32 v169, 0xffff0000, v137
	v_pk_fma_f32 v[170:171], v[166:167], v[166:167], v[170:171]
	v_pk_fma_f32 v[172:173], v[168:169], v[168:169], v[172:173]
	v_lshlrev_b32_e32 v162, 16, v138
	v_and_b32_e32 v163, 0xffff0000, v138
	v_lshlrev_b32_e32 v164, 16, v139
	v_and_b32_e32 v165, 0xffff0000, v139
	v_pk_fma_f32 v[170:171], v[162:163], v[162:163], v[170:171]
	v_pk_fma_f32 v[172:173], v[164:165], v[164:165], v[172:173]
	v_lshlrev_b32_e32 v166, 16, v140
	v_and_b32_e32 v167, 0xffff0000, v140
	v_lshlrev_b32_e32 v168, 16, v141
	v_and_b32_e32 v169, 0xffff0000, v141
	v_pk_fma_f32 v[170:171], v[166:167], v[166:167], v[170:171]
	v_pk_fma_f32 v[172:173], v[168:169], v[168:169], v[172:173]
	v_lshlrev_b32_e32 v162, 16, v142
	v_and_b32_e32 v163, 0xffff0000, v142
	v_lshlrev_b32_e32 v164, 16, v143
	v_and_b32_e32 v165, 0xffff0000, v143
	v_pk_fma_f32 v[170:171], v[162:163], v[162:163], v[170:171]
	v_pk_fma_f32 v[172:173], v[164:165], v[164:165], v[172:173]
	v_lshlrev_b32_e32 v166, 16, v144
	v_and_b32_e32 v167, 0xffff0000, v144
	v_lshlrev_b32_e32 v168, 16, v145
	v_and_b32_e32 v169, 0xffff0000, v145
	v_pk_fma_f32 v[170:171], v[166:167], v[166:167], v[170:171]
	v_pk_fma_f32 v[172:173], v[168:169], v[168:169], v[172:173]
	v_lshlrev_b32_e32 v162, 16, v146
	v_and_b32_e32 v163, 0xffff0000, v146
	v_lshlrev_b32_e32 v164, 16, v147
	v_and_b32_e32 v165, 0xffff0000, v147
	v_pk_fma_f32 v[170:171], v[162:163], v[162:163], v[170:171]
	v_pk_fma_f32 v[172:173], v[164:165], v[164:165], v[172:173]
	v_lshlrev_b32_e32 v166, 16, v148
	v_and_b32_e32 v167, 0xffff0000, v148
	v_lshlrev_b32_e32 v168, 16, v149
	v_and_b32_e32 v169, 0xffff0000, v149
	v_pk_fma_f32 v[170:171], v[166:167], v[166:167], v[170:171]
	v_pk_fma_f32 v[172:173], v[168:169], v[168:169], v[172:173]
	v_lshlrev_b32_e32 v162, 16, v150
	v_and_b32_e32 v163, 0xffff0000, v150
	v_lshlrev_b32_e32 v164, 16, v151
	v_and_b32_e32 v165, 0xffff0000, v151
	v_pk_fma_f32 v[170:171], v[162:163], v[162:163], v[170:171]
	v_pk_fma_f32 v[172:173], v[164:165], v[164:165], v[172:173]
	v_lshlrev_b32_e32 v166, 16, v152
	v_and_b32_e32 v167, 0xffff0000, v152
	v_lshlrev_b32_e32 v168, 16, v153
	v_and_b32_e32 v169, 0xffff0000, v153
	v_pk_fma_f32 v[170:171], v[166:167], v[166:167], v[170:171]
	v_pk_fma_f32 v[172:173], v[168:169], v[168:169], v[172:173]
	v_lshlrev_b32_e32 v162, 16, v154
	v_and_b32_e32 v163, 0xffff0000, v154
	v_lshlrev_b32_e32 v164, 16, v155
	v_and_b32_e32 v165, 0xffff0000, v155
	v_pk_fma_f32 v[170:171], v[162:163], v[162:163], v[170:171]
	v_pk_fma_f32 v[172:173], v[164:165], v[164:165], v[172:173]
	v_lshlrev_b32_e32 v166, 16, v156
	v_and_b32_e32 v167, 0xffff0000, v156
	v_lshlrev_b32_e32 v168, 16, v157
	v_and_b32_e32 v169, 0xffff0000, v157
	v_pk_fma_f32 v[170:171], v[166:167], v[166:167], v[170:171]
	v_pk_fma_f32 v[172:173], v[168:169], v[168:169], v[172:173]
	v_lshlrev_b32_e32 v162, 16, v158
	v_and_b32_e32 v163, 0xffff0000, v158
	v_lshlrev_b32_e32 v164, 16, v159
	v_and_b32_e32 v165, 0xffff0000, v159
	v_pk_fma_f32 v[170:171], v[162:163], v[162:163], v[170:171]
	v_pk_fma_f32 v[172:173], v[164:165], v[164:165], v[172:173]
	v_lshlrev_b32_e32 v166, 16, v160
	v_and_b32_e32 v167, 0xffff0000, v160
	v_lshlrev_b32_e32 v168, 16, v161
	v_and_b32_e32 v169, 0xffff0000, v161
	v_pk_fma_f32 v[170:171], v[166:167], v[166:167], v[170:171]
	v_pk_fma_f32 v[172:173], v[168:169], v[168:169], v[172:173]
	v_pk_add_f32 v[170:171], v[170:171], v[172:173]
	s_nop 0
	v_add_f32_e32 v252, v170, v171
	s_waitcnt lgkmcnt(0)
	ds_bpermute_b32 v254, v246, v252
	s_waitcnt lgkmcnt(0)
	v_add_f32_e32 v252, v252, v254
	ds_bpermute_b32 v254, v247, v252
	s_waitcnt lgkmcnt(0)
	v_add_f32_e32 v252, v252, v254
	ds_bpermute_b32 v254, v248, v252
	s_waitcnt lgkmcnt(0)
	v_add_f32_e32 v252, v252, v254
	ds_bpermute_b32 v254, v249, v252
	s_waitcnt lgkmcnt(0)
	v_add_f32_e32 v252, v252, v254
	ds_bpermute_b32 v254, v250, v252
	s_waitcnt lgkmcnt(0)
	v_add_f32_e32 v252, v252, v254
	ds_bpermute_b32 v254, v251, v252
	s_waitcnt lgkmcnt(0)
	v_add_f32_e32 v252, v252, v254
	v_mov_b32_e32 v254, 0x358637bd
	v_fmac_f32_e32 v254, 0x39800000, v252
	v_mul_f32_e32 v252, 0x4b800000, v254
	v_cmp_gt_f32_e32 vcc, s32, v254
	s_nop 1
	v_cndmask_b32_e32 v254, v254, v252, vcc
	v_rsq_f32_e32 v254, v254
	s_nop 0
	v_mul_f32_e32 v252, 0x45800000, v254
	v_cndmask_b32_e32 v252, v254, v252, vcc
	ds_read_b128 v[226:229], v238 offset:1024
	ds_read_b128 v[230:233], v239 offset:17408
	s_waitcnt lgkmcnt(2)
	v_lshlrev_b32_e32 v162, 16, v130
	v_and_b32_e32 v163, 0xffff0000, v130
	v_lshlrev_b32_e32 v164, 16, v131
	v_and_b32_e32 v165, 0xffff0000, v131
	v_pk_mul_f32 v[162:163], v[162:163], v[252:253] op_sel_hi:[1,0]
	v_pk_mul_f32 v[164:165], v[164:165], v[252:253] op_sel_hi:[1,0]
	v_pk_mul_f32 v[162:163], v[162:163], v[214:215]
	v_pk_mul_f32 v[164:165], v[164:165], v[216:217]
	v_pk_fma_f32 v[2:3], v[218:219], v[162:163], v[2:3]
	v_pk_fma_f32 v[4:5], v[220:221], v[164:165], v[4:5]
	v_pk_mul_f32 v[170:171], v[2:3], v[2:3]
	v_pk_mul_f32 v[172:173], v[4:5], v[4:5]
	v_cvt_pk_bf16_f32 v166, v2, v3
	v_cvt_pk_bf16_f32 v167, v4, v5
	global_store_dwordx2 v244, v[166:167], s[22:23] offset:0
	ds_read_b128 v[214:217], v238 offset:2048
	ds_read_b128 v[218:221], v239 offset:18432
	s_waitcnt lgkmcnt(2)
	v_lshlrev_b32_e32 v162, 16, v132
	v_and_b32_e32 v163, 0xffff0000, v132
	v_lshlrev_b32_e32 v164, 16, v133
	v_and_b32_e32 v165, 0xffff0000, v133
	v_pk_mul_f32 v[162:163], v[162:163], v[252:253] op_sel_hi:[1,0]
	v_pk_mul_f32 v[164:165], v[164:165], v[252:253] op_sel_hi:[1,0]
	v_pk_mul_f32 v[162:163], v[162:163], v[226:227]
	v_pk_mul_f32 v[164:165], v[164:165], v[228:229]
	v_pk_fma_f32 v[6:7], v[230:231], v[162:163], v[6:7]
	v_pk_fma_f32 v[8:9], v[232:233], v[164:165], v[8:9]
	v_pk_fma_f32 v[170:171], v[6:7], v[6:7], v[170:171]
	v_pk_fma_f32 v[172:173], v[8:9], v[8:9], v[172:173]
	v_cvt_pk_bf16_f32 v168, v6, v7
	v_cvt_pk_bf16_f32 v169, v8, v9
	global_store_dwordx2 v244, v[168:169], s[22:23] offset:512
	ds_read_b128 v[226:229], v238 offset:3072
	ds_read_b128 v[230:233], v239 offset:19456
	s_waitcnt lgkmcnt(2)
	v_lshlrev_b32_e32 v162, 16, v134
	v_and_b32_e32 v163, 0xffff0000, v134
	v_lshlrev_b32_e32 v164, 16, v135
	v_and_b32_e32 v165, 0xffff0000, v135
	v_pk_mul_f32 v[162:163], v[162:163], v[252:253] op_sel_hi:[1,0]
	v_pk_mul_f32 v[164:165], v[164:165], v[252:253] op_sel_hi:[1,0]
	v_pk_mul_f32 v[162:163], v[162:163], v[214:215]
	v_pk_mul_f32 v[164:165], v[164:165], v[216:217]
	v_pk_fma_f32 v[10:11], v[218:219], v[162:163], v[10:11]
	v_pk_fma_f32 v[12:13], v[220:221], v[164:165], v[12:13]
	v_pk_fma_f32 v[170:171], v[10:11], v[10:11], v[170:171]
	v_pk_fma_f32 v[172:173], v[12:13], v[12:13], v[172:173]
	v_cvt_pk_bf16_f32 v166, v10, v11
	v_cvt_pk_bf16_f32 v167, v12, v13
	global_store_dwordx2 v244, v[166:167], s[22:23] offset:1024
	ds_read_b128 v[214:217], v238 offset:4096
	ds_read_b128 v[218:221], v239 offset:20480
	s_waitcnt lgkmcnt(2)
	v_lshlrev_b32_e32 v162, 16, v136
	v_and_b32_e32 v163, 0xffff0000, v136
	v_lshlrev_b32_e32 v164, 16, v137
	v_and_b32_e32 v165, 0xffff0000, v137
	v_pk_mul_f32 v[162:163], v[162:163], v[252:253] op_sel_hi:[1,0]
	v_pk_mul_f32 v[164:165], v[164:165], v[252:253] op_sel_hi:[1,0]
	v_pk_mul_f32 v[162:163], v[162:163], v[226:227]
	v_pk_mul_f32 v[164:165], v[164:165], v[228:229]
	v_pk_fma_f32 v[14:15], v[230:231], v[162:163], v[14:15]
	v_pk_fma_f32 v[16:17], v[232:233], v[164:165], v[16:17]
	v_pk_fma_f32 v[170:171], v[14:15], v[14:15], v[170:171]
	v_pk_fma_f32 v[172:173], v[16:17], v[16:17], v[172:173]
	v_cvt_pk_bf16_f32 v168, v14, v15
	v_cvt_pk_bf16_f32 v169, v16, v17
	global_store_dwordx2 v244, v[168:169], s[22:23] offset:1536
	ds_read_b128 v[226:229], v238 offset:5120
	ds_read_b128 v[230:233], v239 offset:21504
	s_waitcnt lgkmcnt(2)
	v_lshlrev_b32_e32 v162, 16, v138
	v_and_b32_e32 v163, 0xffff0000, v138
	v_lshlrev_b32_e32 v164, 16, v139
	v_and_b32_e32 v165, 0xffff0000, v139
	v_pk_mul_f32 v[162:163], v[162:163], v[252:253] op_sel_hi:[1,0]
	v_pk_mul_f32 v[164:165], v[164:165], v[252:253] op_sel_hi:[1,0]
	v_pk_mul_f32 v[162:163], v[162:163], v[214:215]
	v_pk_mul_f32 v[164:165], v[164:165], v[216:217]
	v_pk_fma_f32 v[18:19], v[218:219], v[162:163], v[18:19]
	v_pk_fma_f32 v[20:21], v[220:221], v[164:165], v[20:21]
	v_pk_fma_f32 v[170:171], v[18:19], v[18:19], v[170:171]
	v_pk_fma_f32 v[172:173], v[20:21], v[20:21], v[172:173]
	v_cvt_pk_bf16_f32 v166, v18, v19
	v_cvt_pk_bf16_f32 v167, v20, v21
	global_store_dwordx2 v244, v[166:167], s[22:23] offset:2048
	ds_read_b128 v[214:217], v238 offset:6144
	ds_read_b128 v[218:221], v239 offset:22528
	s_waitcnt lgkmcnt(2)
	v_lshlrev_b32_e32 v162, 16, v140
	v_and_b32_e32 v163, 0xffff0000, v140
	v_lshlrev_b32_e32 v164, 16, v141
	v_and_b32_e32 v165, 0xffff0000, v141
	v_pk_mul_f32 v[162:163], v[162:163], v[252:253] op_sel_hi:[1,0]
	v_pk_mul_f32 v[164:165], v[164:165], v[252:253] op_sel_hi:[1,0]
	v_pk_mul_f32 v[162:163], v[162:163], v[226:227]
	v_pk_mul_f32 v[164:165], v[164:165], v[228:229]
	v_pk_fma_f32 v[22:23], v[230:231], v[162:163], v[22:23]
	v_pk_fma_f32 v[24:25], v[232:233], v[164:165], v[24:25]
	v_pk_fma_f32 v[170:171], v[22:23], v[22:23], v[170:171]
	v_pk_fma_f32 v[172:173], v[24:25], v[24:25], v[172:173]
	v_cvt_pk_bf16_f32 v168, v22, v23
	v_cvt_pk_bf16_f32 v169, v24, v25
	global_store_dwordx2 v244, v[168:169], s[22:23] offset:2560
	ds_read_b128 v[226:229], v238 offset:7168
	ds_read_b128 v[230:233], v239 offset:23552
	s_waitcnt lgkmcnt(2)
	v_lshlrev_b32_e32 v162, 16, v142
	v_and_b32_e32 v163, 0xffff0000, v142
	v_lshlrev_b32_e32 v164, 16, v143
	v_and_b32_e32 v165, 0xffff0000, v143
	v_pk_mul_f32 v[162:163], v[162:163], v[252:253] op_sel_hi:[1,0]
	v_pk_mul_f32 v[164:165], v[164:165], v[252:253] op_sel_hi:[1,0]
	v_pk_mul_f32 v[162:163], v[162:163], v[214:215]
	v_pk_mul_f32 v[164:165], v[164:165], v[216:217]
	v_pk_fma_f32 v[26:27], v[218:219], v[162:163], v[26:27]
	v_pk_fma_f32 v[28:29], v[220:221], v[164:165], v[28:29]
	v_pk_fma_f32 v[170:171], v[26:27], v[26:27], v[170:171]
	v_pk_fma_f32 v[172:173], v[28:29], v[28:29], v[172:173]
	v_cvt_pk_bf16_f32 v166, v26, v27
	v_cvt_pk_bf16_f32 v167, v28, v29
	global_store_dwordx2 v244, v[166:167], s[22:23] offset:3072
	ds_read_b128 v[214:217], v238 offset:8192
	ds_read_b128 v[218:221], v239 offset:24576
	s_waitcnt lgkmcnt(2)
	v_lshlrev_b32_e32 v162, 16, v144
	v_and_b32_e32 v163, 0xffff0000, v144
	v_lshlrev_b32_e32 v164, 16, v145
	v_and_b32_e32 v165, 0xffff0000, v145
	v_pk_mul_f32 v[162:163], v[162:163], v[252:253] op_sel_hi:[1,0]
	v_pk_mul_f32 v[164:165], v[164:165], v[252:253] op_sel_hi:[1,0]
	v_pk_mul_f32 v[162:163], v[162:163], v[226:227]
	v_pk_mul_f32 v[164:165], v[164:165], v[228:229]
	v_pk_fma_f32 v[30:31], v[230:231], v[162:163], v[30:31]
	v_pk_fma_f32 v[32:33], v[232:233], v[164:165], v[32:33]
	v_pk_fma_f32 v[170:171], v[30:31], v[30:31], v[170:171]
	v_pk_fma_f32 v[172:173], v[32:33], v[32:33], v[172:173]
	v_cvt_pk_bf16_f32 v168, v30, v31
	v_cvt_pk_bf16_f32 v169, v32, v33
	global_store_dwordx2 v244, v[168:169], s[22:23] offset:3584
	ds_read_b128 v[226:229], v238 offset:9216
	ds_read_b128 v[230:233], v239 offset:25600
	s_waitcnt lgkmcnt(2)
	v_lshlrev_b32_e32 v162, 16, v146
	v_and_b32_e32 v163, 0xffff0000, v146
	v_lshlrev_b32_e32 v164, 16, v147
	v_and_b32_e32 v165, 0xffff0000, v147
	v_pk_mul_f32 v[162:163], v[162:163], v[252:253] op_sel_hi:[1,0]
	v_pk_mul_f32 v[164:165], v[164:165], v[252:253] op_sel_hi:[1,0]
	v_pk_mul_f32 v[162:163], v[162:163], v[214:215]
	v_pk_mul_f32 v[164:165], v[164:165], v[216:217]
	v_pk_fma_f32 v[34:35], v[218:219], v[162:163], v[34:35]
	v_pk_fma_f32 v[36:37], v[220:221], v[164:165], v[36:37]
	v_pk_fma_f32 v[170:171], v[34:35], v[34:35], v[170:171]
	v_pk_fma_f32 v[172:173], v[36:37], v[36:37], v[172:173]
	v_cvt_pk_bf16_f32 v166, v34, v35
	v_cvt_pk_bf16_f32 v167, v36, v37
	global_store_dwordx2 v245, v[166:167], s[22:23] offset:0
	ds_read_b128 v[214:217], v238 offset:10240
	ds_read_b128 v[218:221], v239 offset:26624
	s_waitcnt lgkmcnt(2)
	v_lshlrev_b32_e32 v162, 16, v148
	v_and_b32_e32 v163, 0xffff0000, v148
	v_lshlrev_b32_e32 v164, 16, v149
	v_and_b32_e32 v165, 0xffff0000, v149
	v_pk_mul_f32 v[162:163], v[162:163], v[252:253] op_sel_hi:[1,0]
	v_pk_mul_f32 v[164:165], v[164:165], v[252:253] op_sel_hi:[1,0]
	v_pk_mul_f32 v[162:163], v[162:163], v[226:227]
	v_pk_mul_f32 v[164:165], v[164:165], v[228:229]
	v_pk_fma_f32 v[38:39], v[230:231], v[162:163], v[38:39]
	v_pk_fma_f32 v[40:41], v[232:233], v[164:165], v[40:41]
	v_pk_fma_f32 v[170:171], v[38:39], v[38:39], v[170:171]
	v_pk_fma_f32 v[172:173], v[40:41], v[40:41], v[172:173]
	v_cvt_pk_bf16_f32 v168, v38, v39
	v_cvt_pk_bf16_f32 v169, v40, v41
	global_store_dwordx2 v245, v[168:169], s[22:23] offset:512
	ds_read_b128 v[226:229], v238 offset:11264
	ds_read_b128 v[230:233], v239 offset:27648
	s_waitcnt lgkmcnt(2)
	v_lshlrev_b32_e32 v162, 16, v150
	v_and_b32_e32 v163, 0xffff0000, v150
	v_lshlrev_b32_e32 v164, 16, v151
	v_and_b32_e32 v165, 0xffff0000, v151
	v_pk_mul_f32 v[162:163], v[162:163], v[252:253] op_sel_hi:[1,0]
	v_pk_mul_f32 v[164:165], v[164:165], v[252:253] op_sel_hi:[1,0]
	v_pk_mul_f32 v[162:163], v[162:163], v[214:215]
	v_pk_mul_f32 v[164:165], v[164:165], v[216:217]
	v_pk_fma_f32 v[42:43], v[218:219], v[162:163], v[42:43]
	v_pk_fma_f32 v[44:45], v[220:221], v[164:165], v[44:45]
	v_pk_fma_f32 v[170:171], v[42:43], v[42:43], v[170:171]
	v_pk_fma_f32 v[172:173], v[44:45], v[44:45], v[172:173]
	v_cvt_pk_bf16_f32 v166, v42, v43
	v_cvt_pk_bf16_f32 v167, v44, v45
	global_store_dwordx2 v245, v[166:167], s[22:23] offset:1024
	ds_read_b128 v[214:217], v238 offset:12288
	ds_read_b128 v[218:221], v239 offset:28672
	s_waitcnt lgkmcnt(2)
	v_lshlrev_b32_e32 v162, 16, v152
	v_and_b32_e32 v163, 0xffff0000, v152
	v_lshlrev_b32_e32 v164, 16, v153
	v_and_b32_e32 v165, 0xffff0000, v153
	v_pk_mul_f32 v[162:163], v[162:163], v[252:253] op_sel_hi:[1,0]
	v_pk_mul_f32 v[164:165], v[164:165], v[252:253] op_sel_hi:[1,0]
	v_pk_mul_f32 v[162:163], v[162:163], v[226:227]
	v_pk_mul_f32 v[164:165], v[164:165], v[228:229]
	v_pk_fma_f32 v[46:47], v[230:231], v[162:163], v[46:47]
	v_pk_fma_f32 v[48:49], v[232:233], v[164:165], v[48:49]
	v_pk_fma_f32 v[170:171], v[46:47], v[46:47], v[170:171]
	v_pk_fma_f32 v[172:173], v[48:49], v[48:49], v[172:173]
	v_cvt_pk_bf16_f32 v168, v46, v47
	v_cvt_pk_bf16_f32 v169, v48, v49
	global_store_dwordx2 v245, v[168:169], s[22:23] offset:1536
	ds_read_b128 v[226:229], v238 offset:13312
	ds_read_b128 v[230:233], v239 offset:29696
	s_waitcnt lgkmcnt(2)
	v_lshlrev_b32_e32 v162, 16, v154
	v_and_b32_e32 v163, 0xffff0000, v154
	v_lshlrev_b32_e32 v164, 16, v155
	v_and_b32_e32 v165, 0xffff0000, v155
	v_pk_mul_f32 v[162:163], v[162:163], v[252:253] op_sel_hi:[1,0]
	v_pk_mul_f32 v[164:165], v[164:165], v[252:253] op_sel_hi:[1,0]
	v_pk_mul_f32 v[162:163], v[162:163], v[214:215]
	v_pk_mul_f32 v[164:165], v[164:165], v[216:217]
	v_pk_fma_f32 v[50:51], v[218:219], v[162:163], v[50:51]
	v_pk_fma_f32 v[52:53], v[220:221], v[164:165], v[52:53]
	v_pk_fma_f32 v[170:171], v[50:51], v[50:51], v[170:171]
	v_pk_fma_f32 v[172:173], v[52:53], v[52:53], v[172:173]
	v_cvt_pk_bf16_f32 v166, v50, v51
	v_cvt_pk_bf16_f32 v167, v52, v53
	global_store_dwordx2 v245, v[166:167], s[22:23] offset:2048
	ds_read_b128 v[214:217], v238 offset:14336
	ds_read_b128 v[218:221], v239 offset:30720
	s_waitcnt lgkmcnt(2)
	v_lshlrev_b32_e32 v162, 16, v156
	v_and_b32_e32 v163, 0xffff0000, v156
	v_lshlrev_b32_e32 v164, 16, v157
	v_and_b32_e32 v165, 0xffff0000, v157
	v_pk_mul_f32 v[162:163], v[162:163], v[252:253] op_sel_hi:[1,0]
	v_pk_mul_f32 v[164:165], v[164:165], v[252:253] op_sel_hi:[1,0]
	v_pk_mul_f32 v[162:163], v[162:163], v[226:227]
	v_pk_mul_f32 v[164:165], v[164:165], v[228:229]
	v_pk_fma_f32 v[54:55], v[230:231], v[162:163], v[54:55]
	v_pk_fma_f32 v[56:57], v[232:233], v[164:165], v[56:57]
	v_pk_fma_f32 v[170:171], v[54:55], v[54:55], v[170:171]
	v_pk_fma_f32 v[172:173], v[56:57], v[56:57], v[172:173]
	v_cvt_pk_bf16_f32 v168, v54, v55
	v_cvt_pk_bf16_f32 v169, v56, v57
	global_store_dwordx2 v245, v[168:169], s[22:23] offset:2560
	ds_read_b128 v[226:229], v238 offset:15360
	ds_read_b128 v[230:233], v239 offset:31744
	s_waitcnt lgkmcnt(2)
	v_lshlrev_b32_e32 v162, 16, v158
	v_and_b32_e32 v163, 0xffff0000, v158
	v_lshlrev_b32_e32 v164, 16, v159
	v_and_b32_e32 v165, 0xffff0000, v159
	v_pk_mul_f32 v[162:163], v[162:163], v[252:253] op_sel_hi:[1,0]
	v_pk_mul_f32 v[164:165], v[164:165], v[252:253] op_sel_hi:[1,0]
	v_pk_mul_f32 v[162:163], v[162:163], v[214:215]
	v_pk_mul_f32 v[164:165], v[164:165], v[216:217]
	v_pk_fma_f32 v[58:59], v[218:219], v[162:163], v[58:59]
	v_pk_fma_f32 v[60:61], v[220:221], v[164:165], v[60:61]
	v_pk_fma_f32 v[170:171], v[58:59], v[58:59], v[170:171]
	v_pk_fma_f32 v[172:173], v[60:61], v[60:61], v[172:173]
	v_cvt_pk_bf16_f32 v166, v58, v59
	v_cvt_pk_bf16_f32 v167, v60, v61
	global_store_dwordx2 v245, v[166:167], s[22:23] offset:3072
	s_waitcnt lgkmcnt(0)
	v_lshlrev_b32_e32 v162, 16, v160
	v_and_b32_e32 v163, 0xffff0000, v160
	v_lshlrev_b32_e32 v164, 16, v161
	v_and_b32_e32 v165, 0xffff0000, v161
	v_pk_mul_f32 v[162:163], v[162:163], v[252:253] op_sel_hi:[1,0]
	v_pk_mul_f32 v[164:165], v[164:165], v[252:253] op_sel_hi:[1,0]
	v_pk_mul_f32 v[162:163], v[162:163], v[226:227]
	v_pk_mul_f32 v[164:165], v[164:165], v[228:229]
	v_pk_fma_f32 v[62:63], v[230:231], v[162:163], v[62:63]
	v_pk_fma_f32 v[64:65], v[232:233], v[164:165], v[64:65]
	v_pk_fma_f32 v[170:171], v[62:63], v[62:63], v[170:171]
	v_pk_fma_f32 v[172:173], v[64:65], v[64:65], v[172:173]
	v_cvt_pk_bf16_f32 v168, v62, v63
	v_cvt_pk_bf16_f32 v169, v64, v65
	global_store_dwordx2 v245, v[168:169], s[22:23] offset:3584
	ds_read_b128 v[214:217], v238 offset:16384
	ds_read_b128 v[218:221], v239 offset:32768
	ds_read_b128 v[222:225], v239 offset:49152
	v_pk_add_f32 v[170:171], v[170:171], v[172:173]
	s_nop 0
	v_add_f32_e32 v252, v170, v171
	s_waitcnt lgkmcnt(0)
	ds_bpermute_b32 v254, v246, v252
	s_waitcnt lgkmcnt(0)
	v_add_f32_e32 v252, v252, v254
	ds_bpermute_b32 v254, v247, v252
	s_waitcnt lgkmcnt(0)
	v_add_f32_e32 v252, v252, v254
	ds_bpermute_b32 v254, v248, v252
	s_waitcnt lgkmcnt(0)
	v_add_f32_e32 v252, v252, v254
	ds_bpermute_b32 v254, v249, v252
	s_waitcnt lgkmcnt(0)
	v_add_f32_e32 v252, v252, v254
	ds_bpermute_b32 v254, v250, v252
	s_waitcnt lgkmcnt(0)
	v_add_f32_e32 v252, v252, v254
	ds_bpermute_b32 v254, v251, v252
	s_waitcnt lgkmcnt(0)
	v_add_f32_e32 v252, v252, v254
	v_mov_b32_e32 v254, 0x358637bd
	v_fmac_f32_e32 v254, 0x39800000, v252
	v_mul_f32_e32 v252, 0x4b800000, v254
	v_cmp_gt_f32_e32 vcc, s32, v254
	s_nop 1
	v_cndmask_b32_e32 v254, v254, v252, vcc
	v_rsq_f32_e32 v254, v254
	s_nop 0
	v_mul_f32_e32 v252, 0x45800000, v254
	v_cndmask_b32_e32 v252, v254, v252, vcc
	s_add_u32 s16, s16, 0x1000000
	s_addc_u32 s17, s17, 0
	global_load_dwordx2 v[130:131], v244, s[16:17] offset:0
	global_load_dwordx2 v[132:133], v244, s[16:17] offset:512
	global_load_dwordx2 v[134:135], v244, s[16:17] offset:1024
	global_load_dwordx2 v[136:137], v244, s[16:17] offset:1536
	global_load_dwordx2 v[138:139], v244, s[16:17] offset:2048
	global_load_dwordx2 v[140:141], v244, s[16:17] offset:2560
	global_load_dwordx2 v[142:143], v244, s[16:17] offset:3072
	global_load_dwordx2 v[144:145], v244, s[16:17] offset:3584
	global_load_dwordx2 v[146:147], v245, s[16:17] offset:0
	global_load_dwordx2 v[148:149], v245, s[16:17] offset:512
	global_load_dwordx2 v[150:151], v245, s[16:17] offset:1024
	global_load_dwordx2 v[152:153], v245, s[16:17] offset:1536
	global_load_dwordx2 v[154:155], v245, s[16:17] offset:2048
	global_load_dwordx2 v[156:157], v245, s[16:17] offset:2560
	global_load_dwordx2 v[158:159], v245, s[16:17] offset:3072
	global_load_dwordx2 v[160:161], v245, s[16:17] offset:3584
	ds_read_b128 v[226:229], v238 offset:17408
	ds_read_b128 v[230:233], v239 offset:33792
	ds_read_b128 v[234:237], v239 offset:50176
	s_waitcnt lgkmcnt(3)
	v_pk_mul_f32 v[2:3], v[2:3], v[252:253] op_sel_hi:[1,0]
	v_pk_mul_f32 v[4:5], v[4:5], v[252:253] op_sel_hi:[1,0]
	v_pk_mul_f32 v[2:3], v[2:3], v[214:215]
	v_pk_mul_f32 v[4:5], v[4:5], v[216:217]
	v_pk_add_f32 v[222:223], v[222:223], 1.0 op_sel_hi:[1,0]
	v_pk_add_f32 v[224:225], v[224:225], 1.0 op_sel_hi:[1,0]
	v_pk_fma_f32 v[2:3], v[2:3], v[222:223], v[218:219]
	v_pk_fma_f32 v[4:5], v[4:5], v[224:225], v[220:221]
	s_nop 0
	v_cvt_pk_bf16_f32 v2, v2, v3
	v_cvt_pk_bf16_f32 v3, v4, v5
	global_store_dwordx2 v244, v[2:3], s[38:39] offset:0
	ds_read_b128 v[214:217], v238 offset:18432
	ds_read_b128 v[218:221], v239 offset:34816
	ds_read_b128 v[222:225], v239 offset:51200
	s_waitcnt lgkmcnt(3)
	v_pk_mul_f32 v[6:7], v[6:7], v[252:253] op_sel_hi:[1,0]
	v_pk_mul_f32 v[8:9], v[8:9], v[252:253] op_sel_hi:[1,0]
	v_pk_mul_f32 v[6:7], v[6:7], v[226:227]
	v_pk_mul_f32 v[8:9], v[8:9], v[228:229]
	v_pk_add_f32 v[234:235], v[234:235], 1.0 op_sel_hi:[1,0]
	v_pk_add_f32 v[236:237], v[236:237], 1.0 op_sel_hi:[1,0]
	v_pk_fma_f32 v[6:7], v[6:7], v[234:235], v[230:231]
	v_pk_fma_f32 v[8:9], v[8:9], v[236:237], v[232:233]
	s_nop 0
	v_cvt_pk_bf16_f32 v6, v6, v7
	v_cvt_pk_bf16_f32 v7, v8, v9
	global_store_dwordx2 v244, v[6:7], s[38:39] offset:512
	ds_read_b128 v[226:229], v238 offset:19456
	ds_read_b128 v[230:233], v239 offset:35840
	ds_read_b128 v[234:237], v239 offset:52224
	s_waitcnt lgkmcnt(3)
	v_pk_mul_f32 v[10:11], v[10:11], v[252:253] op_sel_hi:[1,0]
	v_pk_mul_f32 v[12:13], v[12:13], v[252:253] op_sel_hi:[1,0]
	v_pk_mul_f32 v[10:11], v[10:11], v[214:215]
	v_pk_mul_f32 v[12:13], v[12:13], v[216:217]
	v_pk_add_f32 v[222:223], v[222:223], 1.0 op_sel_hi:[1,0]
	v_pk_add_f32 v[224:225], v[224:225], 1.0 op_sel_hi:[1,0]
	v_pk_fma_f32 v[10:11], v[10:11], v[222:223], v[218:219]
	v_pk_fma_f32 v[12:13], v[12:13], v[224:225], v[220:221]
	s_nop 0
	v_cvt_pk_bf16_f32 v10, v10, v11
	v_cvt_pk_bf16_f32 v11, v12, v13
	global_store_dwordx2 v244, v[10:11], s[38:39] offset:1024
	ds_read_b128 v[214:217], v238 offset:20480
	ds_read_b128 v[218:221], v239 offset:36864
	ds_read_b128 v[222:225], v239 offset:53248
	s_waitcnt lgkmcnt(3)
	v_pk_mul_f32 v[14:15], v[14:15], v[252:253] op_sel_hi:[1,0]
	v_pk_mul_f32 v[16:17], v[16:17], v[252:253] op_sel_hi:[1,0]
	v_pk_mul_f32 v[14:15], v[14:15], v[226:227]
	v_pk_mul_f32 v[16:17], v[16:17], v[228:229]
	v_pk_add_f32 v[234:235], v[234:235], 1.0 op_sel_hi:[1,0]
	v_pk_add_f32 v[236:237], v[236:237], 1.0 op_sel_hi:[1,0]
	v_pk_fma_f32 v[14:15], v[14:15], v[234:235], v[230:231]
	v_pk_fma_f32 v[16:17], v[16:17], v[236:237], v[232:233]
	s_nop 0
	v_cvt_pk_bf16_f32 v14, v14, v15
	v_cvt_pk_bf16_f32 v15, v16, v17
	global_store_dwordx2 v244, v[14:15], s[38:39] offset:1536
	ds_read_b128 v[226:229], v238 offset:21504
	ds_read_b128 v[230:233], v239 offset:37888
	ds_read_b128 v[234:237], v239 offset:54272
	s_waitcnt lgkmcnt(3)
	v_pk_mul_f32 v[18:19], v[18:19], v[252:253] op_sel_hi:[1,0]
	v_pk_mul_f32 v[20:21], v[20:21], v[252:253] op_sel_hi:[1,0]
	v_pk_mul_f32 v[18:19], v[18:19], v[214:215]
	v_pk_mul_f32 v[20:21], v[20:21], v[216:217]
	v_pk_add_f32 v[222:223], v[222:223], 1.0 op_sel_hi:[1,0]
	v_pk_add_f32 v[224:225], v[224:225], 1.0 op_sel_hi:[1,0]
	v_pk_fma_f32 v[18:19], v[18:19], v[222:223], v[218:219]
	v_pk_fma_f32 v[20:21], v[20:21], v[224:225], v[220:221]
	s_nop 0
	v_cvt_pk_bf16_f32 v18, v18, v19
	v_cvt_pk_bf16_f32 v19, v20, v21
	global_store_dwordx2 v244, v[18:19], s[38:39] offset:2048
	ds_read_b128 v[214:217], v238 offset:22528
	ds_read_b128 v[218:221], v239 offset:38912
	ds_read_b128 v[222:225], v239 offset:55296
	s_waitcnt lgkmcnt(3)
	v_pk_mul_f32 v[22:23], v[22:23], v[252:253] op_sel_hi:[1,0]
	v_pk_mul_f32 v[24:25], v[24:25], v[252:253] op_sel_hi:[1,0]
	v_pk_mul_f32 v[22:23], v[22:23], v[226:227]
	v_pk_mul_f32 v[24:25], v[24:25], v[228:229]
	v_pk_add_f32 v[234:235], v[234:235], 1.0 op_sel_hi:[1,0]
	v_pk_add_f32 v[236:237], v[236:237], 1.0 op_sel_hi:[1,0]
	v_pk_fma_f32 v[22:23], v[22:23], v[234:235], v[230:231]
	v_pk_fma_f32 v[24:25], v[24:25], v[236:237], v[232:233]
	s_nop 0
	v_cvt_pk_bf16_f32 v22, v22, v23
	v_cvt_pk_bf16_f32 v23, v24, v25
	global_store_dwordx2 v244, v[22:23], s[38:39] offset:2560
	ds_read_b128 v[226:229], v238 offset:23552
	ds_read_b128 v[230:233], v239 offset:39936
	ds_read_b128 v[234:237], v239 offset:56320
	s_waitcnt lgkmcnt(3)
	v_pk_mul_f32 v[26:27], v[26:27], v[252:253] op_sel_hi:[1,0]
	v_pk_mul_f32 v[28:29], v[28:29], v[252:253] op_sel_hi:[1,0]
	v_pk_mul_f32 v[26:27], v[26:27], v[214:215]
	v_pk_mul_f32 v[28:29], v[28:29], v[216:217]
	v_pk_add_f32 v[222:223], v[222:223], 1.0 op_sel_hi:[1,0]
	v_pk_add_f32 v[224:225], v[224:225], 1.0 op_sel_hi:[1,0]
	v_pk_fma_f32 v[26:27], v[26:27], v[222:223], v[218:219]
	v_pk_fma_f32 v[28:29], v[28:29], v[224:225], v[220:221]
	s_nop 0
	v_cvt_pk_bf16_f32 v26, v26, v27
	v_cvt_pk_bf16_f32 v27, v28, v29
	global_store_dwordx2 v244, v[26:27], s[38:39] offset:3072
	ds_read_b128 v[214:217], v238 offset:24576
	ds_read_b128 v[218:221], v239 offset:40960
	ds_read_b128 v[222:225], v239 offset:57344
	s_waitcnt lgkmcnt(3)
	v_pk_mul_f32 v[30:31], v[30:31], v[252:253] op_sel_hi:[1,0]
	v_pk_mul_f32 v[32:33], v[32:33], v[252:253] op_sel_hi:[1,0]
	v_pk_mul_f32 v[30:31], v[30:31], v[226:227]
	v_pk_mul_f32 v[32:33], v[32:33], v[228:229]
	v_pk_add_f32 v[234:235], v[234:235], 1.0 op_sel_hi:[1,0]
	v_pk_add_f32 v[236:237], v[236:237], 1.0 op_sel_hi:[1,0]
	v_pk_fma_f32 v[30:31], v[30:31], v[234:235], v[230:231]
	v_pk_fma_f32 v[32:33], v[32:33], v[236:237], v[232:233]
	s_nop 0
	v_cvt_pk_bf16_f32 v30, v30, v31
	v_cvt_pk_bf16_f32 v31, v32, v33
	global_store_dwordx2 v244, v[30:31], s[38:39] offset:3584
	ds_read_b128 v[226:229], v238 offset:25600
	ds_read_b128 v[230:233], v239 offset:41984
	ds_read_b128 v[234:237], v239 offset:58368
	s_waitcnt lgkmcnt(3)
	v_pk_mul_f32 v[34:35], v[34:35], v[252:253] op_sel_hi:[1,0]
	v_pk_mul_f32 v[36:37], v[36:37], v[252:253] op_sel_hi:[1,0]
	v_pk_mul_f32 v[34:35], v[34:35], v[214:215]
	v_pk_mul_f32 v[36:37], v[36:37], v[216:217]
	v_pk_add_f32 v[222:223], v[222:223], 1.0 op_sel_hi:[1,0]
	v_pk_add_f32 v[224:225], v[224:225], 1.0 op_sel_hi:[1,0]
	v_pk_fma_f32 v[34:35], v[34:35], v[222:223], v[218:219]
	v_pk_fma_f32 v[36:37], v[36:37], v[224:225], v[220:221]
	s_nop 0
	v_cvt_pk_bf16_f32 v34, v34, v35
	v_cvt_pk_bf16_f32 v35, v36, v37
	global_store_dwordx2 v245, v[34:35], s[38:39] offset:0
	ds_read_b128 v[214:217], v238 offset:26624
	ds_read_b128 v[218:221], v239 offset:43008
	ds_read_b128 v[222:225], v239 offset:59392
	s_waitcnt lgkmcnt(3)
	v_pk_mul_f32 v[38:39], v[38:39], v[252:253] op_sel_hi:[1,0]
	v_pk_mul_f32 v[40:41], v[40:41], v[252:253] op_sel_hi:[1,0]
	v_pk_mul_f32 v[38:39], v[38:39], v[226:227]
	v_pk_mul_f32 v[40:41], v[40:41], v[228:229]
	v_pk_add_f32 v[234:235], v[234:235], 1.0 op_sel_hi:[1,0]
	v_pk_add_f32 v[236:237], v[236:237], 1.0 op_sel_hi:[1,0]
	v_pk_fma_f32 v[38:39], v[38:39], v[234:235], v[230:231]
	v_pk_fma_f32 v[40:41], v[40:41], v[236:237], v[232:233]
	s_nop 0
	v_cvt_pk_bf16_f32 v38, v38, v39
	v_cvt_pk_bf16_f32 v39, v40, v41
	global_store_dwordx2 v245, v[38:39], s[38:39] offset:512
	ds_read_b128 v[226:229], v238 offset:27648
	ds_read_b128 v[230:233], v239 offset:44032
	ds_read_b128 v[234:237], v239 offset:60416
	s_waitcnt lgkmcnt(3)
	v_pk_mul_f32 v[42:43], v[42:43], v[252:253] op_sel_hi:[1,0]
	v_pk_mul_f32 v[44:45], v[44:45], v[252:253] op_sel_hi:[1,0]
	v_pk_mul_f32 v[42:43], v[42:43], v[214:215]
	v_pk_mul_f32 v[44:45], v[44:45], v[216:217]
	v_pk_add_f32 v[222:223], v[222:223], 1.0 op_sel_hi:[1,0]
	v_pk_add_f32 v[224:225], v[224:225], 1.0 op_sel_hi:[1,0]
	v_pk_fma_f32 v[42:43], v[42:43], v[222:223], v[218:219]
	v_pk_fma_f32 v[44:45], v[44:45], v[224:225], v[220:221]
	s_nop 0
	v_cvt_pk_bf16_f32 v42, v42, v43
	v_cvt_pk_bf16_f32 v43, v44, v45
	global_store_dwordx2 v245, v[42:43], s[38:39] offset:1024
	ds_read_b128 v[214:217], v238 offset:28672
	ds_read_b128 v[218:221], v239 offset:45056
	ds_read_b128 v[222:225], v239 offset:61440
	s_waitcnt lgkmcnt(3)
	v_pk_mul_f32 v[46:47], v[46:47], v[252:253] op_sel_hi:[1,0]
	v_pk_mul_f32 v[48:49], v[48:49], v[252:253] op_sel_hi:[1,0]
	v_pk_mul_f32 v[46:47], v[46:47], v[226:227]
	v_pk_mul_f32 v[48:49], v[48:49], v[228:229]
	v_pk_add_f32 v[234:235], v[234:235], 1.0 op_sel_hi:[1,0]
	v_pk_add_f32 v[236:237], v[236:237], 1.0 op_sel_hi:[1,0]
	v_pk_fma_f32 v[46:47], v[46:47], v[234:235], v[230:231]
	v_pk_fma_f32 v[48:49], v[48:49], v[236:237], v[232:233]
	s_nop 0
	v_cvt_pk_bf16_f32 v46, v46, v47
	v_cvt_pk_bf16_f32 v47, v48, v49
	global_store_dwordx2 v245, v[46:47], s[38:39] offset:1536
	ds_read_b128 v[226:229], v238 offset:29696
	ds_read_b128 v[230:233], v239 offset:46080
	ds_read_b128 v[234:237], v239 offset:62464
	s_waitcnt lgkmcnt(3)
	v_pk_mul_f32 v[50:51], v[50:51], v[252:253] op_sel_hi:[1,0]
	v_pk_mul_f32 v[52:53], v[52:53], v[252:253] op_sel_hi:[1,0]
	v_pk_mul_f32 v[50:51], v[50:51], v[214:215]
	v_pk_mul_f32 v[52:53], v[52:53], v[216:217]
	v_pk_add_f32 v[222:223], v[222:223], 1.0 op_sel_hi:[1,0]
	v_pk_add_f32 v[224:225], v[224:225], 1.0 op_sel_hi:[1,0]
	v_pk_fma_f32 v[50:51], v[50:51], v[222:223], v[218:219]
	v_pk_fma_f32 v[52:53], v[52:53], v[224:225], v[220:221]
	s_nop 0
	v_cvt_pk_bf16_f32 v50, v50, v51
	v_cvt_pk_bf16_f32 v51, v52, v53
	global_store_dwordx2 v245, v[50:51], s[38:39] offset:2048
	ds_read_b128 v[214:217], v238 offset:30720
	ds_read_b128 v[218:221], v239 offset:47104
	ds_read_b128 v[222:225], v239 offset:63488
	s_waitcnt lgkmcnt(3)
	v_pk_mul_f32 v[54:55], v[54:55], v[252:253] op_sel_hi:[1,0]
	v_pk_mul_f32 v[56:57], v[56:57], v[252:253] op_sel_hi:[1,0]
	v_pk_mul_f32 v[54:55], v[54:55], v[226:227]
	v_pk_mul_f32 v[56:57], v[56:57], v[228:229]
	v_pk_add_f32 v[234:235], v[234:235], 1.0 op_sel_hi:[1,0]
	v_pk_add_f32 v[236:237], v[236:237], 1.0 op_sel_hi:[1,0]
	v_pk_fma_f32 v[54:55], v[54:55], v[234:235], v[230:231]
	v_pk_fma_f32 v[56:57], v[56:57], v[236:237], v[232:233]
	s_nop 0
	v_cvt_pk_bf16_f32 v54, v54, v55
	v_cvt_pk_bf16_f32 v55, v56, v57
	global_store_dwordx2 v245, v[54:55], s[38:39] offset:2560
	ds_read_b128 v[226:229], v238 offset:31744
	ds_read_b128 v[230:233], v239 offset:48128
	ds_read_b128 v[234:237], v239 offset:64512
	s_waitcnt lgkmcnt(3)
	v_pk_mul_f32 v[58:59], v[58:59], v[252:253] op_sel_hi:[1,0]
	v_pk_mul_f32 v[60:61], v[60:61], v[252:253] op_sel_hi:[1,0]
	v_pk_mul_f32 v[58:59], v[58:59], v[214:215]
	v_pk_mul_f32 v[60:61], v[60:61], v[216:217]
	v_pk_add_f32 v[222:223], v[222:223], 1.0 op_sel_hi:[1,0]
	v_pk_add_f32 v[224:225], v[224:225], 1.0 op_sel_hi:[1,0]
	v_pk_fma_f32 v[58:59], v[58:59], v[222:223], v[218:219]
	v_pk_fma_f32 v[60:61], v[60:61], v[224:225], v[220:221]
	s_nop 0
	v_cvt_pk_bf16_f32 v58, v58, v59
	v_cvt_pk_bf16_f32 v59, v60, v61
	global_store_dwordx2 v245, v[58:59], s[38:39] offset:3072
	s_waitcnt lgkmcnt(0)
	v_pk_mul_f32 v[62:63], v[62:63], v[252:253] op_sel_hi:[1,0]
	v_pk_mul_f32 v[64:65], v[64:65], v[252:253] op_sel_hi:[1,0]
	v_pk_mul_f32 v[62:63], v[62:63], v[226:227]
	v_pk_mul_f32 v[64:65], v[64:65], v[228:229]
	v_pk_add_f32 v[234:235], v[234:235], 1.0 op_sel_hi:[1,0]
	v_pk_add_f32 v[236:237], v[236:237], 1.0 op_sel_hi:[1,0]
	v_pk_fma_f32 v[62:63], v[62:63], v[234:235], v[230:231]
	v_pk_fma_f32 v[64:65], v[64:65], v[236:237], v[232:233]
	s_nop 0
	v_cvt_pk_bf16_f32 v62, v62, v63
	v_cvt_pk_bf16_f32 v63, v64, v65
	global_store_dwordx2 v245, v[62:63], s[38:39] offset:3584
	s_add_u32 s22, s22, 0x1000000
	s_addc_u32 s23, s23, 0
	s_add_u32 s38, s38, 0x1000000
	s_addc_u32 s39, s39, 0
	s_waitcnt vmcnt(16)
	s_barrier
	ds_read_b128 v[214:217], v238 offset:0
	ds_read_b128 v[218:221], v238 offset:32768
	v_lshlrev_b32_e32 v162, 16, v130
	v_and_b32_e32 v163, 0xffff0000, v130
	v_lshlrev_b32_e32 v164, 16, v131
	v_and_b32_e32 v165, 0xffff0000, v131
	v_pk_mul_f32 v[170:171], v[162:163], v[162:163]
	v_pk_mul_f32 v[172:173], v[164:165], v[164:165]
	v_lshlrev_b32_e32 v166, 16, v132
	v_and_b32_e32 v167, 0xffff0000, v132
	v_lshlrev_b32_e32 v168, 16, v133
	v_and_b32_e32 v169, 0xffff0000, v133
	v_pk_fma_f32 v[170:171], v[166:167], v[166:167], v[170:171]
	v_pk_fma_f32 v[172:173], v[168:169], v[168:169], v[172:173]
	v_lshlrev_b32_e32 v162, 16, v134
	v_and_b32_e32 v163, 0xffff0000, v134
	v_lshlrev_b32_e32 v164, 16, v135
	v_and_b32_e32 v165, 0xffff0000, v135
	v_pk_fma_f32 v[170:171], v[162:163], v[162:163], v[170:171]
	v_pk_fma_f32 v[172:173], v[164:165], v[164:165], v[172:173]
	v_lshlrev_b32_e32 v166, 16, v136
	v_and_b32_e32 v167, 0xffff0000, v136
	v_lshlrev_b32_e32 v168, 16, v137
	v_and_b32_e32 v169, 0xffff0000, v137
	v_pk_fma_f32 v[170:171], v[166:167], v[166:167], v[170:171]
	v_pk_fma_f32 v[172:173], v[168:169], v[168:169], v[172:173]
	v_lshlrev_b32_e32 v162, 16, v138
	v_and_b32_e32 v163, 0xffff0000, v138
	v_lshlrev_b32_e32 v164, 16, v139
	v_and_b32_e32 v165, 0xffff0000, v139
	v_pk_fma_f32 v[170:171], v[162:163], v[162:163], v[170:171]
	v_pk_fma_f32 v[172:173], v[164:165], v[164:165], v[172:173]
	v_lshlrev_b32_e32 v166, 16, v140
	v_and_b32_e32 v167, 0xffff0000, v140
	v_lshlrev_b32_e32 v168, 16, v141
	v_and_b32_e32 v169, 0xffff0000, v141
	v_pk_fma_f32 v[170:171], v[166:167], v[166:167], v[170:171]
	v_pk_fma_f32 v[172:173], v[168:169], v[168:169], v[172:173]
	v_lshlrev_b32_e32 v162, 16, v142
	v_and_b32_e32 v163, 0xffff0000, v142
	v_lshlrev_b32_e32 v164, 16, v143
	v_and_b32_e32 v165, 0xffff0000, v143
	v_pk_fma_f32 v[170:171], v[162:163], v[162:163], v[170:171]
	v_pk_fma_f32 v[172:173], v[164:165], v[164:165], v[172:173]
	v_lshlrev_b32_e32 v166, 16, v144
	v_and_b32_e32 v167, 0xffff0000, v144
	v_lshlrev_b32_e32 v168, 16, v145
	v_and_b32_e32 v169, 0xffff0000, v145
	v_pk_fma_f32 v[170:171], v[166:167], v[166:167], v[170:171]
	v_pk_fma_f32 v[172:173], v[168:169], v[168:169], v[172:173]
	v_lshlrev_b32_e32 v162, 16, v146
	v_and_b32_e32 v163, 0xffff0000, v146
	v_lshlrev_b32_e32 v164, 16, v147
	v_and_b32_e32 v165, 0xffff0000, v147
	v_pk_fma_f32 v[170:171], v[162:163], v[162:163], v[170:171]
	v_pk_fma_f32 v[172:173], v[164:165], v[164:165], v[172:173]
	v_lshlrev_b32_e32 v166, 16, v148
	v_and_b32_e32 v167, 0xffff0000, v148
	v_lshlrev_b32_e32 v168, 16, v149
	v_and_b32_e32 v169, 0xffff0000, v149
	v_pk_fma_f32 v[170:171], v[166:167], v[166:167], v[170:171]
	v_pk_fma_f32 v[172:173], v[168:169], v[168:169], v[172:173]
	v_lshlrev_b32_e32 v162, 16, v150
	v_and_b32_e32 v163, 0xffff0000, v150
	v_lshlrev_b32_e32 v164, 16, v151
	v_and_b32_e32 v165, 0xffff0000, v151
	v_pk_fma_f32 v[170:171], v[162:163], v[162:163], v[170:171]
	v_pk_fma_f32 v[172:173], v[164:165], v[164:165], v[172:173]
	v_lshlrev_b32_e32 v166, 16, v152
	v_and_b32_e32 v167, 0xffff0000, v152
	v_lshlrev_b32_e32 v168, 16, v153
	v_and_b32_e32 v169, 0xffff0000, v153
	v_pk_fma_f32 v[170:171], v[166:167], v[166:167], v[170:171]
	v_pk_fma_f32 v[172:173], v[168:169], v[168:169], v[172:173]
	v_lshlrev_b32_e32 v162, 16, v154
	v_and_b32_e32 v163, 0xffff0000, v154
	v_lshlrev_b32_e32 v164, 16, v155
	v_and_b32_e32 v165, 0xffff0000, v155
	v_pk_fma_f32 v[170:171], v[162:163], v[162:163], v[170:171]
	v_pk_fma_f32 v[172:173], v[164:165], v[164:165], v[172:173]
	v_lshlrev_b32_e32 v166, 16, v156
	v_and_b32_e32 v167, 0xffff0000, v156
	v_lshlrev_b32_e32 v168, 16, v157
	v_and_b32_e32 v169, 0xffff0000, v157
	v_pk_fma_f32 v[170:171], v[166:167], v[166:167], v[170:171]
	v_pk_fma_f32 v[172:173], v[168:169], v[168:169], v[172:173]
	v_lshlrev_b32_e32 v162, 16, v158
	v_and_b32_e32 v163, 0xffff0000, v158
	v_lshlrev_b32_e32 v164, 16, v159
	v_and_b32_e32 v165, 0xffff0000, v159
	v_pk_fma_f32 v[170:171], v[162:163], v[162:163], v[170:171]
	v_pk_fma_f32 v[172:173], v[164:165], v[164:165], v[172:173]
	v_lshlrev_b32_e32 v166, 16, v160
	v_and_b32_e32 v167, 0xffff0000, v160
	v_lshlrev_b32_e32 v168, 16, v161
	v_and_b32_e32 v169, 0xffff0000, v161
	v_pk_fma_f32 v[170:171], v[166:167], v[166:167], v[170:171]
	v_pk_fma_f32 v[172:173], v[168:169], v[168:169], v[172:173]
	v_pk_add_f32 v[170:171], v[170:171], v[172:173]
	s_nop 0
	v_add_f32_e32 v252, v170, v171
	s_waitcnt lgkmcnt(0)
	ds_bpermute_b32 v254, v246, v252
	s_waitcnt lgkmcnt(0)
	v_add_f32_e32 v252, v252, v254
	ds_bpermute_b32 v254, v247, v252
	s_waitcnt lgkmcnt(0)
	v_add_f32_e32 v252, v252, v254
	ds_bpermute_b32 v254, v248, v252
	s_waitcnt lgkmcnt(0)
	v_add_f32_e32 v252, v252, v254
	ds_bpermute_b32 v254, v249, v252
	s_waitcnt lgkmcnt(0)
	v_add_f32_e32 v252, v252, v254
	ds_bpermute_b32 v254, v250, v252
	s_waitcnt lgkmcnt(0)
	v_add_f32_e32 v252, v252, v254
	ds_bpermute_b32 v254, v251, v252
	s_waitcnt lgkmcnt(0)
	v_add_f32_e32 v252, v252, v254
	v_mov_b32_e32 v254, 0x358637bd
	v_fmac_f32_e32 v254, 0x39800000, v252
	v_mul_f32_e32 v252, 0x4b800000, v254
	v_cmp_gt_f32_e32 vcc, s32, v254
	s_nop 1
	v_cndmask_b32_e32 v254, v254, v252, vcc
	v_rsq_f32_e32 v254, v254
	s_nop 0
	v_mul_f32_e32 v252, 0x45800000, v254
	v_cndmask_b32_e32 v252, v254, v252, vcc
	ds_read_b128 v[226:229], v238 offset:1024
	ds_read_b128 v[230:233], v238 offset:33792
	s_waitcnt lgkmcnt(2)
	v_lshlrev_b32_e32 v162, 16, v130
	v_and_b32_e32 v163, 0xffff0000, v130
	v_lshlrev_b32_e32 v164, 16, v131
	v_and_b32_e32 v165, 0xffff0000, v131
	v_pk_mul_f32 v[162:163], v[162:163], v[252:253] op_sel_hi:[1,0]
	v_pk_mul_f32 v[164:165], v[164:165], v[252:253] op_sel_hi:[1,0]
	v_pk_mul_f32 v[162:163], v[162:163], v[214:215]
	v_pk_mul_f32 v[164:165], v[164:165], v[216:217]
	v_pk_fma_f32 v[66:67], v[218:219], v[162:163], v[66:67]
	v_pk_fma_f32 v[68:69], v[220:221], v[164:165], v[68:69]
	v_pk_mul_f32 v[170:171], v[66:67], v[66:67]
	v_pk_mul_f32 v[172:173], v[68:69], v[68:69]
	v_cvt_pk_bf16_f32 v166, v66, v67
	v_cvt_pk_bf16_f32 v167, v68, v69
	global_store_dwordx2 v244, v[166:167], s[22:23] offset:0
	ds_read_b128 v[214:217], v238 offset:2048
	ds_read_b128 v[218:221], v238 offset:34816
	s_waitcnt lgkmcnt(2)
	v_lshlrev_b32_e32 v162, 16, v132
	v_and_b32_e32 v163, 0xffff0000, v132
	v_lshlrev_b32_e32 v164, 16, v133
	v_and_b32_e32 v165, 0xffff0000, v133
	v_pk_mul_f32 v[162:163], v[162:163], v[252:253] op_sel_hi:[1,0]
	v_pk_mul_f32 v[164:165], v[164:165], v[252:253] op_sel_hi:[1,0]
	v_pk_mul_f32 v[162:163], v[162:163], v[226:227]
	v_pk_mul_f32 v[164:165], v[164:165], v[228:229]
	v_pk_fma_f32 v[70:71], v[230:231], v[162:163], v[70:71]
	v_pk_fma_f32 v[72:73], v[232:233], v[164:165], v[72:73]
	v_pk_fma_f32 v[170:171], v[70:71], v[70:71], v[170:171]
	v_pk_fma_f32 v[172:173], v[72:73], v[72:73], v[172:173]
	v_cvt_pk_bf16_f32 v168, v70, v71
	v_cvt_pk_bf16_f32 v169, v72, v73
	global_store_dwordx2 v244, v[168:169], s[22:23] offset:512
	ds_read_b128 v[226:229], v238 offset:3072
	ds_read_b128 v[230:233], v238 offset:35840
	s_waitcnt lgkmcnt(2)
	v_lshlrev_b32_e32 v162, 16, v134
	v_and_b32_e32 v163, 0xffff0000, v134
	v_lshlrev_b32_e32 v164, 16, v135
	v_and_b32_e32 v165, 0xffff0000, v135
	v_pk_mul_f32 v[162:163], v[162:163], v[252:253] op_sel_hi:[1,0]
	v_pk_mul_f32 v[164:165], v[164:165], v[252:253] op_sel_hi:[1,0]
	v_pk_mul_f32 v[162:163], v[162:163], v[214:215]
	v_pk_mul_f32 v[164:165], v[164:165], v[216:217]
	v_pk_fma_f32 v[74:75], v[218:219], v[162:163], v[74:75]
	v_pk_fma_f32 v[76:77], v[220:221], v[164:165], v[76:77]
	v_pk_fma_f32 v[170:171], v[74:75], v[74:75], v[170:171]
	v_pk_fma_f32 v[172:173], v[76:77], v[76:77], v[172:173]
	v_cvt_pk_bf16_f32 v166, v74, v75
	v_cvt_pk_bf16_f32 v167, v76, v77
	global_store_dwordx2 v244, v[166:167], s[22:23] offset:1024
	ds_read_b128 v[214:217], v238 offset:4096
	ds_read_b128 v[218:221], v238 offset:36864
	s_waitcnt lgkmcnt(2)
	v_lshlrev_b32_e32 v162, 16, v136
	v_and_b32_e32 v163, 0xffff0000, v136
	v_lshlrev_b32_e32 v164, 16, v137
	v_and_b32_e32 v165, 0xffff0000, v137
	v_pk_mul_f32 v[162:163], v[162:163], v[252:253] op_sel_hi:[1,0]
	v_pk_mul_f32 v[164:165], v[164:165], v[252:253] op_sel_hi:[1,0]
	v_pk_mul_f32 v[162:163], v[162:163], v[226:227]
	v_pk_mul_f32 v[164:165], v[164:165], v[228:229]
	v_pk_fma_f32 v[78:79], v[230:231], v[162:163], v[78:79]
	v_pk_fma_f32 v[80:81], v[232:233], v[164:165], v[80:81]
	v_pk_fma_f32 v[170:171], v[78:79], v[78:79], v[170:171]
	v_pk_fma_f32 v[172:173], v[80:81], v[80:81], v[172:173]
	v_cvt_pk_bf16_f32 v168, v78, v79
	v_cvt_pk_bf16_f32 v169, v80, v81
	global_store_dwordx2 v244, v[168:169], s[22:23] offset:1536
	ds_read_b128 v[226:229], v238 offset:5120
	ds_read_b128 v[230:233], v238 offset:37888
	s_waitcnt lgkmcnt(2)
	v_lshlrev_b32_e32 v162, 16, v138
	v_and_b32_e32 v163, 0xffff0000, v138
	v_lshlrev_b32_e32 v164, 16, v139
	v_and_b32_e32 v165, 0xffff0000, v139
	v_pk_mul_f32 v[162:163], v[162:163], v[252:253] op_sel_hi:[1,0]
	v_pk_mul_f32 v[164:165], v[164:165], v[252:253] op_sel_hi:[1,0]
	v_pk_mul_f32 v[162:163], v[162:163], v[214:215]
	v_pk_mul_f32 v[164:165], v[164:165], v[216:217]
	v_pk_fma_f32 v[82:83], v[218:219], v[162:163], v[82:83]
	v_pk_fma_f32 v[84:85], v[220:221], v[164:165], v[84:85]
	v_pk_fma_f32 v[170:171], v[82:83], v[82:83], v[170:171]
	v_pk_fma_f32 v[172:173], v[84:85], v[84:85], v[172:173]
	v_cvt_pk_bf16_f32 v166, v82, v83
	v_cvt_pk_bf16_f32 v167, v84, v85
	global_store_dwordx2 v244, v[166:167], s[22:23] offset:2048
	ds_read_b128 v[214:217], v238 offset:6144
	ds_read_b128 v[218:221], v238 offset:38912
	s_waitcnt lgkmcnt(2)
	v_lshlrev_b32_e32 v162, 16, v140
	v_and_b32_e32 v163, 0xffff0000, v140
	v_lshlrev_b32_e32 v164, 16, v141
	v_and_b32_e32 v165, 0xffff0000, v141
	v_pk_mul_f32 v[162:163], v[162:163], v[252:253] op_sel_hi:[1,0]
	v_pk_mul_f32 v[164:165], v[164:165], v[252:253] op_sel_hi:[1,0]
	v_pk_mul_f32 v[162:163], v[162:163], v[226:227]
	v_pk_mul_f32 v[164:165], v[164:165], v[228:229]
	v_pk_fma_f32 v[86:87], v[230:231], v[162:163], v[86:87]
	v_pk_fma_f32 v[88:89], v[232:233], v[164:165], v[88:89]
	v_pk_fma_f32 v[170:171], v[86:87], v[86:87], v[170:171]
	v_pk_fma_f32 v[172:173], v[88:89], v[88:89], v[172:173]
	v_cvt_pk_bf16_f32 v168, v86, v87
	v_cvt_pk_bf16_f32 v169, v88, v89
	global_store_dwordx2 v244, v[168:169], s[22:23] offset:2560
	ds_read_b128 v[226:229], v238 offset:7168
	ds_read_b128 v[230:233], v238 offset:39936
	s_waitcnt lgkmcnt(2)
	v_lshlrev_b32_e32 v162, 16, v142
	v_and_b32_e32 v163, 0xffff0000, v142
	v_lshlrev_b32_e32 v164, 16, v143
	v_and_b32_e32 v165, 0xffff0000, v143
	v_pk_mul_f32 v[162:163], v[162:163], v[252:253] op_sel_hi:[1,0]
	v_pk_mul_f32 v[164:165], v[164:165], v[252:253] op_sel_hi:[1,0]
	v_pk_mul_f32 v[162:163], v[162:163], v[214:215]
	v_pk_mul_f32 v[164:165], v[164:165], v[216:217]
	v_pk_fma_f32 v[90:91], v[218:219], v[162:163], v[90:91]
	v_pk_fma_f32 v[92:93], v[220:221], v[164:165], v[92:93]
	v_pk_fma_f32 v[170:171], v[90:91], v[90:91], v[170:171]
	v_pk_fma_f32 v[172:173], v[92:93], v[92:93], v[172:173]
	v_cvt_pk_bf16_f32 v166, v90, v91
	v_cvt_pk_bf16_f32 v167, v92, v93
	global_store_dwordx2 v244, v[166:167], s[22:23] offset:3072
	ds_read_b128 v[214:217], v238 offset:8192
	ds_read_b128 v[218:221], v238 offset:40960
	s_waitcnt lgkmcnt(2)
	v_lshlrev_b32_e32 v162, 16, v144
	v_and_b32_e32 v163, 0xffff0000, v144
	v_lshlrev_b32_e32 v164, 16, v145
	v_and_b32_e32 v165, 0xffff0000, v145
	v_pk_mul_f32 v[162:163], v[162:163], v[252:253] op_sel_hi:[1,0]
	v_pk_mul_f32 v[164:165], v[164:165], v[252:253] op_sel_hi:[1,0]
	v_pk_mul_f32 v[162:163], v[162:163], v[226:227]
	v_pk_mul_f32 v[164:165], v[164:165], v[228:229]
	v_pk_fma_f32 v[94:95], v[230:231], v[162:163], v[94:95]
	v_pk_fma_f32 v[96:97], v[232:233], v[164:165], v[96:97]
	v_pk_fma_f32 v[170:171], v[94:95], v[94:95], v[170:171]
	v_pk_fma_f32 v[172:173], v[96:97], v[96:97], v[172:173]
	v_cvt_pk_bf16_f32 v168, v94, v95
	v_cvt_pk_bf16_f32 v169, v96, v97
	global_store_dwordx2 v244, v[168:169], s[22:23] offset:3584
	ds_read_b128 v[226:229], v238 offset:9216
	ds_read_b128 v[230:233], v238 offset:41984
	s_waitcnt lgkmcnt(2)
	v_lshlrev_b32_e32 v162, 16, v146
	v_and_b32_e32 v163, 0xffff0000, v146
	v_lshlrev_b32_e32 v164, 16, v147
	v_and_b32_e32 v165, 0xffff0000, v147
	v_pk_mul_f32 v[162:163], v[162:163], v[252:253] op_sel_hi:[1,0]
	v_pk_mul_f32 v[164:165], v[164:165], v[252:253] op_sel_hi:[1,0]
	v_pk_mul_f32 v[162:163], v[162:163], v[214:215]
	v_pk_mul_f32 v[164:165], v[164:165], v[216:217]
	v_pk_fma_f32 v[98:99], v[218:219], v[162:163], v[98:99]
	v_pk_fma_f32 v[100:101], v[220:221], v[164:165], v[100:101]
	v_pk_fma_f32 v[170:171], v[98:99], v[98:99], v[170:171]
	v_pk_fma_f32 v[172:173], v[100:101], v[100:101], v[172:173]
	v_cvt_pk_bf16_f32 v166, v98, v99
	v_cvt_pk_bf16_f32 v167, v100, v101
	global_store_dwordx2 v245, v[166:167], s[22:23] offset:0
	ds_read_b128 v[214:217], v238 offset:10240
	ds_read_b128 v[218:221], v238 offset:43008
	s_waitcnt lgkmcnt(2)
	v_lshlrev_b32_e32 v162, 16, v148
	v_and_b32_e32 v163, 0xffff0000, v148
	v_lshlrev_b32_e32 v164, 16, v149
	v_and_b32_e32 v165, 0xffff0000, v149
	v_pk_mul_f32 v[162:163], v[162:163], v[252:253] op_sel_hi:[1,0]
	v_pk_mul_f32 v[164:165], v[164:165], v[252:253] op_sel_hi:[1,0]
	v_pk_mul_f32 v[162:163], v[162:163], v[226:227]
	v_pk_mul_f32 v[164:165], v[164:165], v[228:229]
	v_pk_fma_f32 v[102:103], v[230:231], v[162:163], v[102:103]
	v_pk_fma_f32 v[104:105], v[232:233], v[164:165], v[104:105]
	v_pk_fma_f32 v[170:171], v[102:103], v[102:103], v[170:171]
	v_pk_fma_f32 v[172:173], v[104:105], v[104:105], v[172:173]
	v_cvt_pk_bf16_f32 v168, v102, v103
	v_cvt_pk_bf16_f32 v169, v104, v105
	global_store_dwordx2 v245, v[168:169], s[22:23] offset:512
	ds_read_b128 v[226:229], v238 offset:11264
	ds_read_b128 v[230:233], v238 offset:44032
	s_waitcnt lgkmcnt(2)
	v_lshlrev_b32_e32 v162, 16, v150
	v_and_b32_e32 v163, 0xffff0000, v150
	v_lshlrev_b32_e32 v164, 16, v151
	v_and_b32_e32 v165, 0xffff0000, v151
	v_pk_mul_f32 v[162:163], v[162:163], v[252:253] op_sel_hi:[1,0]
	v_pk_mul_f32 v[164:165], v[164:165], v[252:253] op_sel_hi:[1,0]
	v_pk_mul_f32 v[162:163], v[162:163], v[214:215]
	v_pk_mul_f32 v[164:165], v[164:165], v[216:217]
	v_pk_fma_f32 v[106:107], v[218:219], v[162:163], v[106:107]
	v_pk_fma_f32 v[108:109], v[220:221], v[164:165], v[108:109]
	v_pk_fma_f32 v[170:171], v[106:107], v[106:107], v[170:171]
	v_pk_fma_f32 v[172:173], v[108:109], v[108:109], v[172:173]
	v_cvt_pk_bf16_f32 v166, v106, v107
	v_cvt_pk_bf16_f32 v167, v108, v109
	global_store_dwordx2 v245, v[166:167], s[22:23] offset:1024
	ds_read_b128 v[214:217], v238 offset:12288
	ds_read_b128 v[218:221], v238 offset:45056
	s_waitcnt lgkmcnt(2)
	v_lshlrev_b32_e32 v162, 16, v152
	v_and_b32_e32 v163, 0xffff0000, v152
	v_lshlrev_b32_e32 v164, 16, v153
	v_and_b32_e32 v165, 0xffff0000, v153
	v_pk_mul_f32 v[162:163], v[162:163], v[252:253] op_sel_hi:[1,0]
	v_pk_mul_f32 v[164:165], v[164:165], v[252:253] op_sel_hi:[1,0]
	v_pk_mul_f32 v[162:163], v[162:163], v[226:227]
	v_pk_mul_f32 v[164:165], v[164:165], v[228:229]
	v_pk_fma_f32 v[110:111], v[230:231], v[162:163], v[110:111]
	v_pk_fma_f32 v[112:113], v[232:233], v[164:165], v[112:113]
	v_pk_fma_f32 v[170:171], v[110:111], v[110:111], v[170:171]
	v_pk_fma_f32 v[172:173], v[112:113], v[112:113], v[172:173]
	v_cvt_pk_bf16_f32 v168, v110, v111
	v_cvt_pk_bf16_f32 v169, v112, v113
	global_store_dwordx2 v245, v[168:169], s[22:23] offset:1536
	ds_read_b128 v[226:229], v238 offset:13312
	ds_read_b128 v[230:233], v238 offset:46080
	s_waitcnt lgkmcnt(2)
	v_lshlrev_b32_e32 v162, 16, v154
	v_and_b32_e32 v163, 0xffff0000, v154
	v_lshlrev_b32_e32 v164, 16, v155
	v_and_b32_e32 v165, 0xffff0000, v155
	v_pk_mul_f32 v[162:163], v[162:163], v[252:253] op_sel_hi:[1,0]
	v_pk_mul_f32 v[164:165], v[164:165], v[252:253] op_sel_hi:[1,0]
	v_pk_mul_f32 v[162:163], v[162:163], v[214:215]
	v_pk_mul_f32 v[164:165], v[164:165], v[216:217]
	v_pk_fma_f32 v[114:115], v[218:219], v[162:163], v[114:115]
	v_pk_fma_f32 v[116:117], v[220:221], v[164:165], v[116:117]
	v_pk_fma_f32 v[170:171], v[114:115], v[114:115], v[170:171]
	v_pk_fma_f32 v[172:173], v[116:117], v[116:117], v[172:173]
	v_cvt_pk_bf16_f32 v166, v114, v115
	v_cvt_pk_bf16_f32 v167, v116, v117
	global_store_dwordx2 v245, v[166:167], s[22:23] offset:2048
	ds_read_b128 v[214:217], v238 offset:14336
	ds_read_b128 v[218:221], v238 offset:47104
	s_waitcnt lgkmcnt(2)
	v_lshlrev_b32_e32 v162, 16, v156
	v_and_b32_e32 v163, 0xffff0000, v156
	v_lshlrev_b32_e32 v164, 16, v157
	v_and_b32_e32 v165, 0xffff0000, v157
	v_pk_mul_f32 v[162:163], v[162:163], v[252:253] op_sel_hi:[1,0]
	v_pk_mul_f32 v[164:165], v[164:165], v[252:253] op_sel_hi:[1,0]
	v_pk_mul_f32 v[162:163], v[162:163], v[226:227]
	v_pk_mul_f32 v[164:165], v[164:165], v[228:229]
	v_pk_fma_f32 v[118:119], v[230:231], v[162:163], v[118:119]
	v_pk_fma_f32 v[120:121], v[232:233], v[164:165], v[120:121]
	v_pk_fma_f32 v[170:171], v[118:119], v[118:119], v[170:171]
	v_pk_fma_f32 v[172:173], v[120:121], v[120:121], v[172:173]
	v_cvt_pk_bf16_f32 v168, v118, v119
	v_cvt_pk_bf16_f32 v169, v120, v121
	global_store_dwordx2 v245, v[168:169], s[22:23] offset:2560
	ds_read_b128 v[226:229], v238 offset:15360
	ds_read_b128 v[230:233], v238 offset:48128
	s_waitcnt lgkmcnt(2)
	v_lshlrev_b32_e32 v162, 16, v158
	v_and_b32_e32 v163, 0xffff0000, v158
	v_lshlrev_b32_e32 v164, 16, v159
	v_and_b32_e32 v165, 0xffff0000, v159
	v_pk_mul_f32 v[162:163], v[162:163], v[252:253] op_sel_hi:[1,0]
	v_pk_mul_f32 v[164:165], v[164:165], v[252:253] op_sel_hi:[1,0]
	v_pk_mul_f32 v[162:163], v[162:163], v[214:215]
	v_pk_mul_f32 v[164:165], v[164:165], v[216:217]
	v_pk_fma_f32 v[122:123], v[218:219], v[162:163], v[122:123]
	v_pk_fma_f32 v[124:125], v[220:221], v[164:165], v[124:125]
	v_pk_fma_f32 v[170:171], v[122:123], v[122:123], v[170:171]
	v_pk_fma_f32 v[172:173], v[124:125], v[124:125], v[172:173]
	v_cvt_pk_bf16_f32 v166, v122, v123
	v_cvt_pk_bf16_f32 v167, v124, v125
	global_store_dwordx2 v245, v[166:167], s[22:23] offset:3072
	s_waitcnt lgkmcnt(0)
	v_lshlrev_b32_e32 v162, 16, v160
	v_and_b32_e32 v163, 0xffff0000, v160
	v_lshlrev_b32_e32 v164, 16, v161
	v_and_b32_e32 v165, 0xffff0000, v161
	v_pk_mul_f32 v[162:163], v[162:163], v[252:253] op_sel_hi:[1,0]
	v_pk_mul_f32 v[164:165], v[164:165], v[252:253] op_sel_hi:[1,0]
	v_pk_mul_f32 v[162:163], v[162:163], v[226:227]
	v_pk_mul_f32 v[164:165], v[164:165], v[228:229]
	v_pk_fma_f32 v[126:127], v[230:231], v[162:163], v[126:127]
	v_pk_fma_f32 v[128:129], v[232:233], v[164:165], v[128:129]
	v_pk_fma_f32 v[170:171], v[126:127], v[126:127], v[170:171]
	v_pk_fma_f32 v[172:173], v[128:129], v[128:129], v[172:173]
	v_cvt_pk_bf16_f32 v168, v126, v127
	v_cvt_pk_bf16_f32 v169, v128, v129
	global_store_dwordx2 v245, v[168:169], s[22:23] offset:3584
	ds_read_b128 v[214:217], v238 offset:16384
	ds_read_b128 v[218:221], v238 offset:49152
	ds_read_b128 v[222:225], v239 offset:0
	v_pk_add_f32 v[170:171], v[170:171], v[172:173]
	s_nop 0
	v_add_f32_e32 v252, v170, v171
	s_waitcnt lgkmcnt(0)
	ds_bpermute_b32 v254, v246, v252
	s_waitcnt lgkmcnt(0)
	v_add_f32_e32 v252, v252, v254
	ds_bpermute_b32 v254, v247, v252
	s_waitcnt lgkmcnt(0)
	v_add_f32_e32 v252, v252, v254
	ds_bpermute_b32 v254, v248, v252
	s_waitcnt lgkmcnt(0)
	v_add_f32_e32 v252, v252, v254
	ds_bpermute_b32 v254, v249, v252
	s_waitcnt lgkmcnt(0)
	v_add_f32_e32 v252, v252, v254
	ds_bpermute_b32 v254, v250, v252
	s_waitcnt lgkmcnt(0)
	v_add_f32_e32 v252, v252, v254
	ds_bpermute_b32 v254, v251, v252
	s_waitcnt lgkmcnt(0)
	v_add_f32_e32 v252, v252, v254
	v_mov_b32_e32 v254, 0x358637bd
	v_fmac_f32_e32 v254, 0x39800000, v252
	v_mul_f32_e32 v252, 0x4b800000, v254
	v_cmp_gt_f32_e32 vcc, s32, v254
	s_nop 1
	v_cndmask_b32_e32 v254, v254, v252, vcc
	v_rsq_f32_e32 v254, v254
	s_nop 0
	v_mul_f32_e32 v252, 0x45800000, v254
	v_cndmask_b32_e32 v252, v254, v252, vcc
	ds_read_b128 v[226:229], v238 offset:17408
	ds_read_b128 v[230:233], v238 offset:50176
	ds_read_b128 v[234:237], v239 offset:1024
	s_waitcnt lgkmcnt(3)
	v_pk_mul_f32 v[66:67], v[66:67], v[252:253] op_sel_hi:[1,0]
	v_pk_mul_f32 v[68:69], v[68:69], v[252:253] op_sel_hi:[1,0]
	v_pk_mul_f32 v[66:67], v[66:67], v[214:215]
	v_pk_mul_f32 v[68:69], v[68:69], v[216:217]
	v_pk_add_f32 v[222:223], v[222:223], 1.0 op_sel_hi:[1,0]
	v_pk_add_f32 v[224:225], v[224:225], 1.0 op_sel_hi:[1,0]
	v_pk_fma_f32 v[66:67], v[66:67], v[222:223], v[218:219]
	v_pk_fma_f32 v[68:69], v[68:69], v[224:225], v[220:221]
	s_nop 0
	v_cvt_pk_bf16_f32 v66, v66, v67
	v_cvt_pk_bf16_f32 v67, v68, v69
	global_store_dwordx2 v244, v[66:67], s[38:39] offset:0
	ds_read_b128 v[214:217], v238 offset:18432
	ds_read_b128 v[218:221], v238 offset:51200
	ds_read_b128 v[222:225], v239 offset:2048
	s_waitcnt lgkmcnt(3)
	v_pk_mul_f32 v[70:71], v[70:71], v[252:253] op_sel_hi:[1,0]
	v_pk_mul_f32 v[72:73], v[72:73], v[252:253] op_sel_hi:[1,0]
	v_pk_mul_f32 v[70:71], v[70:71], v[226:227]
	v_pk_mul_f32 v[72:73], v[72:73], v[228:229]
	v_pk_add_f32 v[234:235], v[234:235], 1.0 op_sel_hi:[1,0]
	v_pk_add_f32 v[236:237], v[236:237], 1.0 op_sel_hi:[1,0]
	v_pk_fma_f32 v[70:71], v[70:71], v[234:235], v[230:231]
	v_pk_fma_f32 v[72:73], v[72:73], v[236:237], v[232:233]
	s_nop 0
	v_cvt_pk_bf16_f32 v70, v70, v71
	v_cvt_pk_bf16_f32 v71, v72, v73
	global_store_dwordx2 v244, v[70:71], s[38:39] offset:512
	ds_read_b128 v[226:229], v238 offset:19456
	ds_read_b128 v[230:233], v238 offset:52224
	ds_read_b128 v[234:237], v239 offset:3072
	s_waitcnt lgkmcnt(3)
	v_pk_mul_f32 v[74:75], v[74:75], v[252:253] op_sel_hi:[1,0]
	v_pk_mul_f32 v[76:77], v[76:77], v[252:253] op_sel_hi:[1,0]
	v_pk_mul_f32 v[74:75], v[74:75], v[214:215]
	v_pk_mul_f32 v[76:77], v[76:77], v[216:217]
	v_pk_add_f32 v[222:223], v[222:223], 1.0 op_sel_hi:[1,0]
	v_pk_add_f32 v[224:225], v[224:225], 1.0 op_sel_hi:[1,0]
	v_pk_fma_f32 v[74:75], v[74:75], v[222:223], v[218:219]
	v_pk_fma_f32 v[76:77], v[76:77], v[224:225], v[220:221]
	s_nop 0
	v_cvt_pk_bf16_f32 v74, v74, v75
	v_cvt_pk_bf16_f32 v75, v76, v77
	global_store_dwordx2 v244, v[74:75], s[38:39] offset:1024
	ds_read_b128 v[214:217], v238 offset:20480
	ds_read_b128 v[218:221], v238 offset:53248
	ds_read_b128 v[222:225], v239 offset:4096
	s_waitcnt lgkmcnt(3)
	v_pk_mul_f32 v[78:79], v[78:79], v[252:253] op_sel_hi:[1,0]
	v_pk_mul_f32 v[80:81], v[80:81], v[252:253] op_sel_hi:[1,0]
	v_pk_mul_f32 v[78:79], v[78:79], v[226:227]
	v_pk_mul_f32 v[80:81], v[80:81], v[228:229]
	v_pk_add_f32 v[234:235], v[234:235], 1.0 op_sel_hi:[1,0]
	v_pk_add_f32 v[236:237], v[236:237], 1.0 op_sel_hi:[1,0]
	v_pk_fma_f32 v[78:79], v[78:79], v[234:235], v[230:231]
	v_pk_fma_f32 v[80:81], v[80:81], v[236:237], v[232:233]
	s_nop 0
	v_cvt_pk_bf16_f32 v78, v78, v79
	v_cvt_pk_bf16_f32 v79, v80, v81
	global_store_dwordx2 v244, v[78:79], s[38:39] offset:1536
	ds_read_b128 v[226:229], v238 offset:21504
	ds_read_b128 v[230:233], v238 offset:54272
	ds_read_b128 v[234:237], v239 offset:5120
	s_waitcnt lgkmcnt(3)
	v_pk_mul_f32 v[82:83], v[82:83], v[252:253] op_sel_hi:[1,0]
	v_pk_mul_f32 v[84:85], v[84:85], v[252:253] op_sel_hi:[1,0]
	v_pk_mul_f32 v[82:83], v[82:83], v[214:215]
	v_pk_mul_f32 v[84:85], v[84:85], v[216:217]
	v_pk_add_f32 v[222:223], v[222:223], 1.0 op_sel_hi:[1,0]
	v_pk_add_f32 v[224:225], v[224:225], 1.0 op_sel_hi:[1,0]
	v_pk_fma_f32 v[82:83], v[82:83], v[222:223], v[218:219]
	v_pk_fma_f32 v[84:85], v[84:85], v[224:225], v[220:221]
	s_nop 0
	v_cvt_pk_bf16_f32 v82, v82, v83
	v_cvt_pk_bf16_f32 v83, v84, v85
	global_store_dwordx2 v244, v[82:83], s[38:39] offset:2048
	ds_read_b128 v[214:217], v238 offset:22528
	ds_read_b128 v[218:221], v238 offset:55296
	ds_read_b128 v[222:225], v239 offset:6144
	s_waitcnt lgkmcnt(3)
	v_pk_mul_f32 v[86:87], v[86:87], v[252:253] op_sel_hi:[1,0]
	v_pk_mul_f32 v[88:89], v[88:89], v[252:253] op_sel_hi:[1,0]
	v_pk_mul_f32 v[86:87], v[86:87], v[226:227]
	v_pk_mul_f32 v[88:89], v[88:89], v[228:229]
	v_pk_add_f32 v[234:235], v[234:235], 1.0 op_sel_hi:[1,0]
	v_pk_add_f32 v[236:237], v[236:237], 1.0 op_sel_hi:[1,0]
	v_pk_fma_f32 v[86:87], v[86:87], v[234:235], v[230:231]
	v_pk_fma_f32 v[88:89], v[88:89], v[236:237], v[232:233]
	s_nop 0
	v_cvt_pk_bf16_f32 v86, v86, v87
	v_cvt_pk_bf16_f32 v87, v88, v89
	global_store_dwordx2 v244, v[86:87], s[38:39] offset:2560
	ds_read_b128 v[226:229], v238 offset:23552
	ds_read_b128 v[230:233], v238 offset:56320
	ds_read_b128 v[234:237], v239 offset:7168
	s_waitcnt lgkmcnt(3)
	v_pk_mul_f32 v[90:91], v[90:91], v[252:253] op_sel_hi:[1,0]
	v_pk_mul_f32 v[92:93], v[92:93], v[252:253] op_sel_hi:[1,0]
	v_pk_mul_f32 v[90:91], v[90:91], v[214:215]
	v_pk_mul_f32 v[92:93], v[92:93], v[216:217]
	v_pk_add_f32 v[222:223], v[222:223], 1.0 op_sel_hi:[1,0]
	v_pk_add_f32 v[224:225], v[224:225], 1.0 op_sel_hi:[1,0]
	v_pk_fma_f32 v[90:91], v[90:91], v[222:223], v[218:219]
	v_pk_fma_f32 v[92:93], v[92:93], v[224:225], v[220:221]
	s_nop 0
	v_cvt_pk_bf16_f32 v90, v90, v91
	v_cvt_pk_bf16_f32 v91, v92, v93
	global_store_dwordx2 v244, v[90:91], s[38:39] offset:3072
	ds_read_b128 v[214:217], v238 offset:24576
	ds_read_b128 v[218:221], v238 offset:57344
	ds_read_b128 v[222:225], v239 offset:8192
	s_waitcnt lgkmcnt(3)
	v_pk_mul_f32 v[94:95], v[94:95], v[252:253] op_sel_hi:[1,0]
	v_pk_mul_f32 v[96:97], v[96:97], v[252:253] op_sel_hi:[1,0]
	v_pk_mul_f32 v[94:95], v[94:95], v[226:227]
	v_pk_mul_f32 v[96:97], v[96:97], v[228:229]
	v_pk_add_f32 v[234:235], v[234:235], 1.0 op_sel_hi:[1,0]
	v_pk_add_f32 v[236:237], v[236:237], 1.0 op_sel_hi:[1,0]
	v_pk_fma_f32 v[94:95], v[94:95], v[234:235], v[230:231]
	v_pk_fma_f32 v[96:97], v[96:97], v[236:237], v[232:233]
	s_nop 0
	v_cvt_pk_bf16_f32 v94, v94, v95
	v_cvt_pk_bf16_f32 v95, v96, v97
	global_store_dwordx2 v244, v[94:95], s[38:39] offset:3584
	ds_read_b128 v[226:229], v238 offset:25600
	ds_read_b128 v[230:233], v238 offset:58368
	ds_read_b128 v[234:237], v239 offset:9216
	s_waitcnt lgkmcnt(3)
	v_pk_mul_f32 v[98:99], v[98:99], v[252:253] op_sel_hi:[1,0]
	v_pk_mul_f32 v[100:101], v[100:101], v[252:253] op_sel_hi:[1,0]
	v_pk_mul_f32 v[98:99], v[98:99], v[214:215]
	v_pk_mul_f32 v[100:101], v[100:101], v[216:217]
	v_pk_add_f32 v[222:223], v[222:223], 1.0 op_sel_hi:[1,0]
	v_pk_add_f32 v[224:225], v[224:225], 1.0 op_sel_hi:[1,0]
	v_pk_fma_f32 v[98:99], v[98:99], v[222:223], v[218:219]
	v_pk_fma_f32 v[100:101], v[100:101], v[224:225], v[220:221]
	s_nop 0
	v_cvt_pk_bf16_f32 v98, v98, v99
	v_cvt_pk_bf16_f32 v99, v100, v101
	global_store_dwordx2 v245, v[98:99], s[38:39] offset:0
	ds_read_b128 v[214:217], v238 offset:26624
	ds_read_b128 v[218:221], v238 offset:59392
	ds_read_b128 v[222:225], v239 offset:10240
	s_waitcnt lgkmcnt(3)
	v_pk_mul_f32 v[102:103], v[102:103], v[252:253] op_sel_hi:[1,0]
	v_pk_mul_f32 v[104:105], v[104:105], v[252:253] op_sel_hi:[1,0]
	v_pk_mul_f32 v[102:103], v[102:103], v[226:227]
	v_pk_mul_f32 v[104:105], v[104:105], v[228:229]
	v_pk_add_f32 v[234:235], v[234:235], 1.0 op_sel_hi:[1,0]
	v_pk_add_f32 v[236:237], v[236:237], 1.0 op_sel_hi:[1,0]
	v_pk_fma_f32 v[102:103], v[102:103], v[234:235], v[230:231]
	v_pk_fma_f32 v[104:105], v[104:105], v[236:237], v[232:233]
	s_nop 0
	v_cvt_pk_bf16_f32 v102, v102, v103
	v_cvt_pk_bf16_f32 v103, v104, v105
	global_store_dwordx2 v245, v[102:103], s[38:39] offset:512
	ds_read_b128 v[226:229], v238 offset:27648
	ds_read_b128 v[230:233], v238 offset:60416
	ds_read_b128 v[234:237], v239 offset:11264
	s_waitcnt lgkmcnt(3)
	v_pk_mul_f32 v[106:107], v[106:107], v[252:253] op_sel_hi:[1,0]
	v_pk_mul_f32 v[108:109], v[108:109], v[252:253] op_sel_hi:[1,0]
	v_pk_mul_f32 v[106:107], v[106:107], v[214:215]
	v_pk_mul_f32 v[108:109], v[108:109], v[216:217]
	v_pk_add_f32 v[222:223], v[222:223], 1.0 op_sel_hi:[1,0]
	v_pk_add_f32 v[224:225], v[224:225], 1.0 op_sel_hi:[1,0]
	v_pk_fma_f32 v[106:107], v[106:107], v[222:223], v[218:219]
	v_pk_fma_f32 v[108:109], v[108:109], v[224:225], v[220:221]
	s_nop 0
	v_cvt_pk_bf16_f32 v106, v106, v107
	v_cvt_pk_bf16_f32 v107, v108, v109
	global_store_dwordx2 v245, v[106:107], s[38:39] offset:1024
	ds_read_b128 v[214:217], v238 offset:28672
	ds_read_b128 v[218:221], v238 offset:61440
	ds_read_b128 v[222:225], v239 offset:12288
	s_waitcnt lgkmcnt(3)
	v_pk_mul_f32 v[110:111], v[110:111], v[252:253] op_sel_hi:[1,0]
	v_pk_mul_f32 v[112:113], v[112:113], v[252:253] op_sel_hi:[1,0]
	v_pk_mul_f32 v[110:111], v[110:111], v[226:227]
	v_pk_mul_f32 v[112:113], v[112:113], v[228:229]
	v_pk_add_f32 v[234:235], v[234:235], 1.0 op_sel_hi:[1,0]
	v_pk_add_f32 v[236:237], v[236:237], 1.0 op_sel_hi:[1,0]
	v_pk_fma_f32 v[110:111], v[110:111], v[234:235], v[230:231]
	v_pk_fma_f32 v[112:113], v[112:113], v[236:237], v[232:233]
	s_nop 0
	v_cvt_pk_bf16_f32 v110, v110, v111
	v_cvt_pk_bf16_f32 v111, v112, v113
	global_store_dwordx2 v245, v[110:111], s[38:39] offset:1536
	ds_read_b128 v[226:229], v238 offset:29696
	ds_read_b128 v[230:233], v238 offset:62464
	ds_read_b128 v[234:237], v239 offset:13312
	s_waitcnt lgkmcnt(3)
	v_pk_mul_f32 v[114:115], v[114:115], v[252:253] op_sel_hi:[1,0]
	v_pk_mul_f32 v[116:117], v[116:117], v[252:253] op_sel_hi:[1,0]
	v_pk_mul_f32 v[114:115], v[114:115], v[214:215]
	v_pk_mul_f32 v[116:117], v[116:117], v[216:217]
	v_pk_add_f32 v[222:223], v[222:223], 1.0 op_sel_hi:[1,0]
	v_pk_add_f32 v[224:225], v[224:225], 1.0 op_sel_hi:[1,0]
	v_pk_fma_f32 v[114:115], v[114:115], v[222:223], v[218:219]
	v_pk_fma_f32 v[116:117], v[116:117], v[224:225], v[220:221]
	s_nop 0
	v_cvt_pk_bf16_f32 v114, v114, v115
	v_cvt_pk_bf16_f32 v115, v116, v117
	global_store_dwordx2 v245, v[114:115], s[38:39] offset:2048
	ds_read_b128 v[214:217], v238 offset:30720
	ds_read_b128 v[218:221], v238 offset:63488
	ds_read_b128 v[222:225], v239 offset:14336
	s_waitcnt lgkmcnt(3)
	v_pk_mul_f32 v[118:119], v[118:119], v[252:253] op_sel_hi:[1,0]
	v_pk_mul_f32 v[120:121], v[120:121], v[252:253] op_sel_hi:[1,0]
	v_pk_mul_f32 v[118:119], v[118:119], v[226:227]
	v_pk_mul_f32 v[120:121], v[120:121], v[228:229]
	v_pk_add_f32 v[234:235], v[234:235], 1.0 op_sel_hi:[1,0]
	v_pk_add_f32 v[236:237], v[236:237], 1.0 op_sel_hi:[1,0]
	v_pk_fma_f32 v[118:119], v[118:119], v[234:235], v[230:231]
	v_pk_fma_f32 v[120:121], v[120:121], v[236:237], v[232:233]
	s_nop 0
	v_cvt_pk_bf16_f32 v118, v118, v119
	v_cvt_pk_bf16_f32 v119, v120, v121
	global_store_dwordx2 v245, v[118:119], s[38:39] offset:2560
	ds_read_b128 v[226:229], v238 offset:31744
	ds_read_b128 v[230:233], v238 offset:64512
	ds_read_b128 v[234:237], v239 offset:15360
	s_waitcnt lgkmcnt(3)
	v_pk_mul_f32 v[122:123], v[122:123], v[252:253] op_sel_hi:[1,0]
	v_pk_mul_f32 v[124:125], v[124:125], v[252:253] op_sel_hi:[1,0]
	v_pk_mul_f32 v[122:123], v[122:123], v[214:215]
	v_pk_mul_f32 v[124:125], v[124:125], v[216:217]
	v_pk_add_f32 v[222:223], v[222:223], 1.0 op_sel_hi:[1,0]
	v_pk_add_f32 v[224:225], v[224:225], 1.0 op_sel_hi:[1,0]
	v_pk_fma_f32 v[122:123], v[122:123], v[222:223], v[218:219]
	v_pk_fma_f32 v[124:125], v[124:125], v[224:225], v[220:221]
	s_nop 0
	v_cvt_pk_bf16_f32 v122, v122, v123
	v_cvt_pk_bf16_f32 v123, v124, v125
	global_store_dwordx2 v245, v[122:123], s[38:39] offset:3072
	s_waitcnt lgkmcnt(0)
	v_pk_mul_f32 v[126:127], v[126:127], v[252:253] op_sel_hi:[1,0]
	v_pk_mul_f32 v[128:129], v[128:129], v[252:253] op_sel_hi:[1,0]
	v_pk_mul_f32 v[126:127], v[126:127], v[226:227]
	v_pk_mul_f32 v[128:129], v[128:129], v[228:229]
	v_pk_add_f32 v[234:235], v[234:235], 1.0 op_sel_hi:[1,0]
	v_pk_add_f32 v[236:237], v[236:237], 1.0 op_sel_hi:[1,0]
	v_pk_fma_f32 v[126:127], v[126:127], v[234:235], v[230:231]
	v_pk_fma_f32 v[128:129], v[128:129], v[236:237], v[232:233]
	s_nop 0
	v_cvt_pk_bf16_f32 v126, v126, v127
	v_cvt_pk_bf16_f32 v127, v128, v129
	global_store_dwordx2 v245, v[126:127], s[38:39] offset:3584
	s_branch .LBB0_715
.LrA_old:
	v_mbcnt_lo_u32_b32 v1, -1, 0
	v_mbcnt_hi_u32_b32 v3, -1, v1
	v_and_b32_e32 v1, 64, v3
	v_add_u32_e32 v4, 64, v1
	v_xor_b32_e32 v1, 1, v3
	v_cmp_lt_i32_e32 vcc, v1, v4
	v_xor_b32_e32 v5, 2, v3
	s_lshl_b32 s8, s33, 3
	v_cndmask_b32_e32 v1, v3, v1, vcc
	v_cmp_lt_i32_e32 vcc, v5, v4
	s_ashr_i32 s7, s6, 31
	v_lshlrev_b32_e32 v2, 2, v174
	v_cndmask_b32_e32 v5, v3, v5, vcc
	v_lshlrev_b32_e32 v157, 2, v5
	v_xor_b32_e32 v5, 4, v3
	v_cmp_lt_i32_e32 vcc, v5, v4
	v_readlane_b32 s12, v255, 2
	s_ashr_i32 s9, s8, 31
	v_cndmask_b32_e32 v5, v3, v5, vcc
	v_lshlrev_b32_e32 v175, 2, v5
	v_xor_b32_e32 v5, 8, v3
	v_cmp_lt_i32_e32 vcc, v5, v4
	s_lshl_b64 s[10:11], s[6:7], 13
	v_mov_b32_e32 v67, 0
	v_cndmask_b32_e32 v5, v3, v5, vcc
	v_lshlrev_b32_e32 v190, 2, v5
	v_xor_b32_e32 v5, 16, v3
	v_cmp_lt_i32_e32 vcc, v5, v4
	v_or_b32_e32 v12, 0x400, v2
	v_lshlrev_b32_e32 v66, 4, v174
	v_cndmask_b32_e32 v5, v3, v5, vcc
	v_lshlrev_b32_e32 v191, 2, v5
	v_xor_b32_e32 v5, 32, v3
	v_readlane_b32 s18, v255, 8
	v_readlane_b32 s19, v255, 9
	v_readlane_b32 s20, v255, 10
	v_readlane_b32 s21, v255, 11
	s_add_u32 s10, s70, s10
	v_cmp_lt_i32_e32 vcc, v5, v4
	v_or_b32_e32 v4, 0xc00, v2
	v_or_b32_e32 v14, 0x500, v2
	v_or_b32_e32 v16, 0x600, v2
	v_or_b32_e32 v18, 0x700, v2
	v_or_b32_e32 v20, 0x800, v2
	v_or_b32_e32 v22, 0x900, v2
	v_or_b32_e32 v24, 0xa00, v2
	v_or_b32_e32 v26, 0xb00, v2
	v_or_b32_e32 v28, 0xd00, v2
	v_or_b32_e32 v30, 0xe00, v2
	v_or_b32_e32 v32, 0xf00, v2
	v_lshl_add_u64 v[68:69], s[18:19], 0, v[66:67]
	v_lshlrev_b32_e32 v34, 2, v12
	v_mov_b32_e32 v35, v67
	v_lshl_add_u64 v[94:95], s[20:21], 0, v[66:67]
	v_lshlrev_b32_e32 v66, 3, v174
	s_addc_u32 s11, s71, s11
	v_cndmask_b32_e32 v3, v3, v5, vcc
	v_or_b32_e32 v6, 0x100, v2
	v_or_b32_e32 v8, 0x200, v2
	v_or_b32_e32 v10, 0x300, v2
	v_readlane_b32 s26, v255, 16
	v_readlane_b32 s27, v255, 17
	v_lshl_add_u64 v[70:71], s[18:19], 0, v[34:35]
	v_lshlrev_b32_e32 v36, 2, v14
	v_mov_b32_e32 v37, v67
	v_lshlrev_b32_e32 v38, 2, v16
	v_mov_b32_e32 v39, v67
	v_lshlrev_b32_e32 v40, 2, v18
	v_mov_b32_e32 v41, v67
	v_lshlrev_b32_e32 v42, 2, v20
	v_mov_b32_e32 v43, v67
	v_lshlrev_b32_e32 v44, 2, v22
	v_mov_b32_e32 v45, v67
	v_lshlrev_b32_e32 v46, 2, v24
	v_mov_b32_e32 v47, v67
	v_lshlrev_b32_e32 v48, 2, v26
	v_mov_b32_e32 v49, v67
	v_lshlrev_b32_e32 v50, 2, v4
	v_mov_b32_e32 v51, v67
	v_lshlrev_b32_e32 v52, 2, v28
	v_mov_b32_e32 v53, v67
	v_lshlrev_b32_e32 v54, 2, v30
	v_mov_b32_e32 v55, v67
	v_lshlrev_b32_e32 v56, 2, v32
	v_mov_b32_e32 v57, v67
	v_lshl_add_u64 v[96:97], s[20:21], 0, v[34:35]
	v_lshl_add_u64 v[34:35], s[10:11], 0, v[66:67]
	s_mov_b64 s[10:11], 0x3f000000
	v_lshlrev_b32_e32 v1, 2, v1
	v_lshlrev_b32_e32 v192, 2, v3
	v_lshl_add_u64 v[72:73], s[18:19], 0, v[36:37]
	v_lshl_add_u64 v[74:75], s[18:19], 0, v[38:39]
	v_lshl_add_u64 v[76:77], s[18:19], 0, v[40:41]
	v_lshl_add_u64 v[78:79], s[18:19], 0, v[42:43]
	v_lshl_add_u64 v[80:81], s[18:19], 0, v[44:45]
	v_lshl_add_u64 v[82:83], s[18:19], 0, v[46:47]
	v_lshl_add_u64 v[84:85], s[18:19], 0, v[48:49]
	v_lshl_add_u64 v[86:87], s[18:19], 0, v[50:51]
	v_lshl_add_u64 v[88:89], s[18:19], 0, v[52:53]
	v_lshl_add_u64 v[90:91], s[18:19], 0, v[54:55]
	v_lshl_add_u64 v[92:93], s[18:19], 0, v[56:57]
	v_lshl_add_u64 v[98:99], s[20:21], 0, v[36:37]
	v_lshl_add_u64 v[100:101], s[20:21], 0, v[38:39]
	v_lshl_add_u64 v[102:103], s[20:21], 0, v[40:41]
	v_lshl_add_u64 v[104:105], s[20:21], 0, v[42:43]
	v_lshl_add_u64 v[106:107], s[20:21], 0, v[44:45]
	v_lshl_add_u64 v[108:109], s[20:21], 0, v[46:47]
	v_lshl_add_u64 v[110:111], s[20:21], 0, v[48:49]
	v_lshl_add_u64 v[112:113], s[20:21], 0, v[50:51]
	s_waitcnt vmcnt(0)
	v_lshl_add_u64 v[114:115], s[20:21], 0, v[52:53]
	v_lshl_add_u64 v[116:117], s[20:21], 0, v[54:55]
	v_lshl_add_u64 v[118:119], s[20:21], 0, v[56:57]
	v_lshl_add_u64 v[120:121], v[34:35], 0, s[10:11]
	s_lshl_b64 s[18:19], s[8:9], 13
	s_movk_i32 s3, 0x2000
	v_lshlrev_b32_e32 v66, 4, v174
	s_mov_b32 s10, 0xdfc01000
	s_movk_i32 s11, 0x1000
	s_mov_b32 s26, 0xdfc02000
	s_movk_i32 s27, 0x3000
	v_mov_b32_e32 v193, 0x358637bd
	s_mov_b32 s30, 0x800000
	v_lshlrev_b32_e32 v194, 2, v2
	v_lshlrev_b32_e32 v195, 2, v6
	v_lshlrev_b32_e32 v196, 2, v8
	v_lshlrev_b32_e32 v197, 2, v10
	v_lshlrev_b32_e32 v198, 2, v12
	v_lshlrev_b32_e32 v199, 2, v14
	v_lshlrev_b32_e32 v200, 2, v16
	v_lshlrev_b32_e32 v201, 2, v18
	v_lshlrev_b32_e32 v202, 2, v20
	v_lshlrev_b32_e32 v203, 2, v22
	v_lshlrev_b32_e32 v204, 2, v24
	v_lshlrev_b32_e32 v205, 2, v26
	v_lshlrev_b32_e32 v206, 2, v4
	v_lshlrev_b32_e32 v207, 2, v28
	v_lshlrev_b32_e32 v208, 2, v30
	v_lshlrev_b32_e32 v209, 2, v32
	s_brev_b32 s31, 48
	s_mov_b32 s34, 0xc001000
	v_readlane_b32 s13, v255, 3
	v_readlane_b32 s14, v255, 4
	v_readlane_b32 s15, v255, 5
	v_readlane_b32 s16, v255, 6
	v_readlane_b32 s17, v255, 7
	v_readlane_b32 s22, v255, 12
	v_readlane_b32 s23, v255, 13
	v_readlane_b32 s24, v255, 14
	v_readlane_b32 s25, v255, 15
